# SwiGLU and rope-epilogue store addresses by running pointer increments instead of per-store 64-bit multiplies
# speedup vs baseline: 1.0021x; 1.0021x over previous
.LBB0_503:
	s_and_b32 s69, s69, 1
	v_lshl_add_u32 v128, s69, 12, v227
	ds_read2st64_b32 v[180:181], v128 offset1:1
	ds_read2st64_b32 v[178:179], v128 offset0:2 offset1:3
	ds_read2st64_b32 v[176:177], v128 offset0:4 offset1:5
	ds_read2st64_b32 v[174:175], v128 offset0:6 offset1:7
	v_lshl_add_u32 v128, s69, 10, v226
	ds_read_b128 v[140:143], v128
	ds_read_b128 v[136:139], v128 offset:16
	ds_read_b128 v[132:135], v128 offset:512
	ds_read_b128 v[128:131], v128 offset:528
	v_cvt_f32_i32_e32 v83, v83
	v_cvt_f32_i32_e32 v82, v82
	v_cvt_f32_i32_e32 v73, v73
	v_cvt_f32_i32_e32 v72, v72
	v_cvt_f32_i32_e32 v65, v65
	v_cvt_f32_i32_e32 v64, v64
	v_cvt_f32_i32_e32 v127, v127
	v_cvt_f32_i32_e32 v126, v126
	v_cvt_f32_i32_e32 v125, v125
	v_cvt_f32_i32_e32 v124, v124
	v_cvt_f32_i32_e32 v183, v123
	v_cvt_f32_i32_e32 v182, v122
	s_waitcnt lgkmcnt(0)
	v_pk_mul_f32 v[188:189], v[130:131], v[82:83]
	v_pk_mul_f32 v[82:83], v[128:129], v[72:73]
	v_cvt_f32_i32_e32 v73, v67
	v_cvt_f32_i32_e32 v72, v66
	v_pk_mul_f32 v[66:67], v[128:129], v[64:65]
	v_cvt_f32_i32_e32 v63, v63
	v_cvt_f32_i32_e32 v62, v62
	v_cvt_f32_i32_e32 v61, v61
	v_cvt_f32_i32_e32 v60, v60
	v_cvt_f32_i32_e32 v65, v59
	v_cvt_f32_i32_e32 v64, v58
	v_pk_mul_f32 v[122:123], v[140:141], v[124:125]
	v_pk_mul_f32 v[124:125], v[142:143], v[126:127]
	v_pk_mul_f32 v[126:127], v[138:139], v[182:183]
	v_cvt_f32_i32_e32 v119, v119
	v_cvt_f32_i32_e32 v118, v118
	v_cvt_f32_i32_e32 v117, v117
	v_cvt_f32_i32_e32 v116, v116
	v_cvt_f32_i32_e32 v183, v115
	v_cvt_f32_i32_e32 v182, v114
	v_pk_mul_f32 v[58:59], v[140:141], v[60:61]
	v_pk_mul_f32 v[60:61], v[142:143], v[62:63]
	v_pk_mul_f32 v[62:63], v[138:139], v[64:65]
	v_cvt_f32_i32_e32 v55, v55
	v_cvt_f32_i32_e32 v54, v54
	v_cvt_f32_i32_e32 v53, v53
	v_cvt_f32_i32_e32 v52, v52
	v_cvt_f32_i32_e32 v65, v51
	v_cvt_f32_i32_e32 v64, v50
	v_pk_mul_f32 v[114:115], v[140:141], v[116:117]
	v_pk_mul_f32 v[116:117], v[142:143], v[118:119]
	v_pk_mul_f32 v[118:119], v[138:139], v[182:183]
	v_cvt_f32_i32_e32 v111, v111
	v_cvt_f32_i32_e32 v110, v110
	v_cvt_f32_i32_e32 v109, v109
	v_cvt_f32_i32_e32 v108, v108
	v_cvt_f32_i32_e32 v183, v107
	v_cvt_f32_i32_e32 v182, v106
	v_pk_mul_f32 v[50:51], v[140:141], v[52:53]
	v_pk_mul_f32 v[52:53], v[142:143], v[54:55]
	v_pk_mul_f32 v[54:55], v[138:139], v[64:65]
	v_cvt_f32_i32_e32 v47, v47
	v_cvt_f32_i32_e32 v46, v46
	v_cvt_f32_i32_e32 v45, v45
	v_cvt_f32_i32_e32 v44, v44
	v_cvt_f32_i32_e32 v65, v43
	v_cvt_f32_i32_e32 v64, v42
	v_cvt_f32_i32_e32 v95, v95
	v_cvt_f32_i32_e32 v94, v94
	v_cvt_f32_i32_e32 v91, v91
	v_cvt_f32_i32_e32 v90, v90
	v_cvt_f32_i32_e32 v87, v87
	v_cvt_f32_i32_e32 v86, v86
	v_cvt_f32_i32_e32 v85, v85
	v_cvt_f32_i32_e32 v84, v84
	v_cvt_f32_i32_e32 v79, v79
	v_cvt_f32_i32_e32 v78, v78
	v_cvt_f32_i32_e32 v77, v77
	v_cvt_f32_i32_e32 v76, v76
	v_cvt_f32_i32_e32 v71, v71
	v_cvt_f32_i32_e32 v70, v70
	v_cvt_f32_i32_e32 v31, v31
	v_cvt_f32_i32_e32 v30, v30
	v_cvt_f32_i32_e32 v25, v25
	v_cvt_f32_i32_e32 v24, v24
	v_cvt_f32_i32_e32 v23, v23
	v_cvt_f32_i32_e32 v22, v22
	v_cvt_f32_i32_e32 v21, v21
	v_cvt_f32_i32_e32 v20, v20
	v_cvt_f32_i32_e32 v15, v15
	v_cvt_f32_i32_e32 v14, v14
	v_cvt_f32_i32_e32 v7, v7
	v_cvt_f32_i32_e32 v6, v6
	v_cvt_f32_i32_e32 v121, v121
	v_cvt_f32_i32_e32 v120, v120
	v_cvt_f32_i32_e32 v113, v113
	v_cvt_f32_i32_e32 v112, v112
	v_cvt_f32_i32_e32 v105, v105
	v_cvt_f32_i32_e32 v104, v104
	v_pk_mul_f32 v[106:107], v[140:141], v[108:109]
	v_pk_mul_f32 v[108:109], v[142:143], v[110:111]
	v_pk_mul_f32 v[110:111], v[138:139], v[182:183]
	v_cvt_f32_i32_e32 v103, v103
	v_cvt_f32_i32_e32 v102, v102
	v_cvt_f32_i32_e32 v101, v101
	v_cvt_f32_i32_e32 v100, v100
	v_cvt_f32_i32_e32 v183, v99
	v_cvt_f32_i32_e32 v97, v97
	v_cvt_f32_i32_e32 v96, v96
	v_cvt_f32_i32_e32 v182, v98
	v_cvt_f32_i32_e32 v93, v93
	v_cvt_f32_i32_e32 v92, v92
	v_cvt_f32_i32_e32 v89, v89
	v_cvt_f32_i32_e32 v88, v88
	v_cvt_f32_i32_e32 v81, v81
	v_cvt_f32_i32_e32 v80, v80
	v_cvt_f32_i32_e32 v75, v75
	v_cvt_f32_i32_e32 v74, v74
	v_cvt_f32_i32_e32 v69, v69
	v_cvt_f32_i32_e32 v68, v68
	v_cvt_f32_i32_e32 v57, v57
	v_cvt_f32_i32_e32 v56, v56
	v_cvt_f32_i32_e32 v49, v49
	v_cvt_f32_i32_e32 v48, v48
	v_cvt_f32_i32_e32 v41, v41
	v_cvt_f32_i32_e32 v40, v40
	v_pk_mul_f32 v[42:43], v[140:141], v[44:45]
	v_pk_mul_f32 v[44:45], v[142:143], v[46:47]
	v_pk_mul_f32 v[46:47], v[138:139], v[64:65]
	v_cvt_f32_i32_e32 v39, v39
	v_cvt_f32_i32_e32 v38, v38
	v_cvt_f32_i32_e32 v37, v37
	v_cvt_f32_i32_e32 v36, v36
	v_cvt_f32_i32_e32 v65, v35
	v_cvt_f32_i32_e32 v33, v33
	v_cvt_f32_i32_e32 v32, v32
	v_cvt_f32_i32_e32 v64, v34
	v_cvt_f32_i32_e32 v29, v29
	v_cvt_f32_i32_e32 v28, v28
	v_cvt_f32_i32_e32 v27, v27
	v_cvt_f32_i32_e32 v26, v26
	v_cvt_f32_i32_e32 v19, v19
	v_cvt_f32_i32_e32 v17, v17
	v_cvt_f32_i32_e32 v16, v16
	v_cvt_f32_i32_e32 v18, v18
	v_cvt_f32_i32_e32 v13, v13
	v_cvt_f32_i32_e32 v12, v12
	v_cvt_f32_i32_e32 v11, v11
	v_cvt_f32_i32_e32 v9, v9
	v_cvt_f32_i32_e32 v8, v8
	v_cvt_f32_i32_e32 v10, v10
	v_cvt_f32_i32_e32 v5, v5
	v_cvt_f32_i32_e32 v4, v4
	v_cvt_f32_i32_e32 v3, v3
	v_cvt_f32_i32_e32 v1, v1
	v_cvt_f32_i32_e32 v0, v0
	v_cvt_f32_i32_e32 v2, v2
	v_pk_mul_f32 v[194:195], v[134:135], v[94:95]
	v_pk_mul_f32 v[196:197], v[130:131], v[90:91]
	v_pk_mul_f32 v[184:185], v[132:133], v[84:85]
	v_pk_mul_f32 v[186:187], v[134:135], v[86:87]
	v_pk_mul_f32 v[84:85], v[132:133], v[76:77]
	v_pk_mul_f32 v[86:87], v[134:135], v[78:79]
	v_pk_mul_f32 v[70:71], v[134:135], v[70:71]
	v_pk_mul_f32 v[94:95], v[134:135], v[30:31]
	v_pk_mul_f32 v[90:91], v[128:129], v[24:25]
	v_pk_mul_f32 v[76:77], v[132:133], v[20:21]
	v_pk_mul_f32 v[78:79], v[134:135], v[22:23]
	v_pk_mul_f32 v[30:31], v[134:135], v[14:15]
	v_pk_mul_f32 v[20:21], v[134:135], v[6:7]
	v_lshl_or_b32 v134, s59, 6, v160
	v_lshl_add_u32 v24, s68, 8, v224
	v_pk_mul_f32 v[120:121], v[136:137], v[120:121]
	v_pk_mul_f32 v[112:113], v[136:137], v[112:113]
	v_pk_mul_f32 v[104:105], v[136:137], v[104:105]
	v_pk_mul_f32 v[98:99], v[140:141], v[100:101]
	v_pk_mul_f32 v[100:101], v[142:143], v[102:103]
	v_pk_mul_f32 v[96:97], v[136:137], v[96:97]
	v_pk_mul_f32 v[102:103], v[138:139], v[182:183]
	v_pk_mul_f32 v[192:193], v[132:133], v[92:93]
	v_pk_mul_f32 v[190:191], v[128:129], v[88:89]
	v_pk_mul_f32 v[182:183], v[128:129], v[80:81]
	v_pk_mul_f32 v[88:89], v[130:131], v[74:75]
	v_pk_mul_f32 v[68:69], v[132:133], v[68:69]
	v_pk_mul_f32 v[72:73], v[130:131], v[72:73]
	v_pk_mul_f32 v[56:57], v[136:137], v[56:57]
	v_pk_mul_f32 v[48:49], v[136:137], v[48:49]
	v_pk_mul_f32 v[40:41], v[136:137], v[40:41]
	v_pk_mul_f32 v[34:35], v[140:141], v[36:37]
	v_pk_mul_f32 v[36:37], v[142:143], v[38:39]
	v_pk_mul_f32 v[32:33], v[136:137], v[32:33]
	v_pk_mul_f32 v[38:39], v[138:139], v[64:65]
	v_pk_mul_f32 v[92:93], v[132:133], v[28:29]
	v_pk_mul_f32 v[136:137], v[130:131], v[26:27]
	v_pk_mul_f32 v[74:75], v[128:129], v[16:17]
	v_pk_mul_f32 v[80:81], v[130:131], v[18:19]
	v_pk_mul_f32 v[28:29], v[132:133], v[12:13]
	v_pk_mul_f32 v[26:27], v[128:129], v[8:9]
	v_pk_mul_f32 v[64:65], v[130:131], v[10:11]
	v_pk_mul_f32 v[18:19], v[132:133], v[4:5]
	v_pk_mul_f32 v[16:17], v[128:129], v[0:1]
	v_pk_mul_f32 v[22:23], v[130:131], v[2:3]
	s_mov_b64 s[68:69], -1
	s_andn2_b64 vcc, exec, s[48:49]
	v_ashrrev_i32_e32 v135, 31, v134
	v_ashrrev_i32_e32 v25, 31, v24
	v_or_b32_e32 v132, 16, v24
	v_or_b32_e32 v130, 32, v24
	v_or_b32_e32 v128, 48, v24
	s_cbranch_vccz .LBB0_505
	v_lshlrev_b32_e32 v0, 7, v24
	v_and_b32_e32 v144, 0x3e780, v0
	v_lshl_add_u64 v[0:1], s[34:35], 0, v[144:145]
	v_mov_b32_e32 v173, v145
	v_cmp_lt_i32_e32 vcc, v215, v214
	v_lshl_add_u64 v[12:13], v[0:1], 0, v[172:173]
	v_mul_f32_e32 v1, v193, v193
	v_cndmask_b32_e32 v0, v161, v215, vcc
	v_cmp_lt_i32_e32 vcc, v216, v214
	v_lshlrev_b32_e32 v131, 2, v0
	v_fmac_f32_e32 v1, v123, v123
	v_cndmask_b32_e32 v0, v161, v216, vcc
	v_lshlrev_b32_e32 v129, 2, v0
	v_mul_f32_e32 v0, v192, v192
	v_fmac_f32_e32 v0, v122, v122
	v_add_f32_e32 v4, v0, v1
	v_pk_mul_f32 v[0:1], v[194:195], v[194:195]
	v_lshl_add_u64 v[2:3], s[70:71], 2, v[162:163]
	v_pk_fma_f32 v[0:1], v[124:125], v[124:125], v[0:1]
	global_load_dwordx4 v[202:205], v[12:13], off
	global_load_dwordx4 v[234:237], v[12:13], off offset:16
	v_add_f32_e32 v0, v0, v4
	v_pk_mul_f32 v[4:5], v[190:191], v[190:191]
	v_add_f32_e32 v6, v1, v0
	v_pk_fma_f32 v[4:5], v[120:121], v[120:121], v[4:5]
	v_pk_mul_f32 v[0:1], v[196:197], v[196:197]
	v_add_f32_e32 v4, v4, v6
	v_pk_fma_f32 v[0:1], v[126:127], v[126:127], v[0:1]
	v_add_f32_e32 v4, v5, v4
	v_add_f32_e32 v0, v0, v4
	global_load_dwordx4 v[4:7], v[2:3], off
	global_load_dwordx4 v[208:211], v[2:3], off offset:16
	v_add_f32_e32 v0, v1, v0
	ds_bpermute_b32 v1, v131, v0
	v_mul_lo_u32 v133, s66, v25
	v_lshl_add_u64 v[138:139], v[134:135], 1, s[8:9]
	s_mov_b64 s[68:69], 0
	s_waitcnt lgkmcnt(0)
	v_add_f32_e32 v0, v0, v1
	ds_bpermute_b32 v1, v129, v0
	s_waitcnt lgkmcnt(0)
	v_add_f32_e32 v0, v0, v1
	v_mul_f32_e32 v0, v180, v0
	v_mul_f32_e32 v0, v180, v0
	v_fmamk_f32 v0, v0, 0x3c800000, v217
	v_cmp_gt_f32_e32 vcc, s85, v0
	v_mul_f32_e32 v1, 0x4b800000, v0
	s_waitcnt vmcnt(0)
	v_cvt_f32_f16_e32 v15, v203
	v_cndmask_b32_e32 v0, v0, v1, vcc
	v_rsq_f32_e32 v0, v0
	v_cvt_f32_f16_e32 v14, v202
	v_cvt_f32_f16_e32 v207, v235
	v_cvt_f32_f16_e32 v206, v234
	v_mul_f32_e32 v1, 0x45800000, v0
	v_cndmask_b32_e32 v0, v0, v1, vcc
	v_mul_f32_e32 v0, v180, v0
	v_mul_f32_e32 v8, s83, v0
	v_cvt_f32_f16_sdwa v199, v5 dst_sel:DWORD dst_unused:UNUSED_PAD src0_sel:WORD_1
	v_cvt_f32_f16_sdwa v198, v4 dst_sel:DWORD dst_unused:UNUSED_PAD src0_sel:WORD_1
	v_cvt_f32_f16_e32 v201, v5
	v_cvt_f32_f16_e32 v200, v4
	v_cvt_f32_f16_sdwa v5, v203 dst_sel:DWORD dst_unused:UNUSED_PAD src0_sel:WORD_1
	v_cvt_f32_f16_sdwa v4, v202 dst_sel:DWORD dst_unused:UNUSED_PAD src0_sel:WORD_1
	v_pk_mul_f32 v[10:11], v[8:9], v[198:199] op_sel_hi:[0,1]
	v_pk_mul_f32 v[0:1], v[8:9], v[200:201] op_sel_hi:[0,1]
	v_pk_mul_f32 v[10:11], v[192:193], v[10:11]
	v_pk_mul_f32 v[0:1], v[122:123], v[0:1]
	v_pk_mul_f32 v[140:141], v[10:11], v[14:15]
	v_cvt_f32_f16_e32 v143, v7
	v_pk_fma_f32 v[202:203], v[0:1], v[4:5], v[140:141]
	v_cvt_f32_f16_sdwa v141, v7 dst_sel:DWORD dst_unused:UNUSED_PAD src0_sel:WORD_1
	v_cvt_f32_f16_sdwa v140, v6 dst_sel:DWORD dst_unused:UNUSED_PAD src0_sel:WORD_1
	v_pk_mul_f32 v[4:5], v[10:11], v[4:5]
	v_cvt_f32_f16_e32 v142, v6
	v_pk_fma_f32 v[0:1], v[0:1], v[14:15], v[4:5] neg_lo:[0,0,1] neg_hi:[0,0,1]
	v_cvt_f32_f16_e32 v15, v205
	v_cvt_f32_f16_e32 v14, v204
	v_cvt_f32_f16_sdwa v7, v205 dst_sel:DWORD dst_unused:UNUSED_PAD src0_sel:WORD_1
	v_cvt_f32_f16_sdwa v6, v204 dst_sel:DWORD dst_unused:UNUSED_PAD src0_sel:WORD_1
	v_pk_mul_f32 v[10:11], v[8:9], v[140:141] op_sel_hi:[0,1]
	v_pk_mul_f32 v[4:5], v[8:9], v[142:143] op_sel_hi:[0,1]
	v_pk_mul_f32 v[10:11], v[194:195], v[10:11]
	v_pk_mul_f32 v[4:5], v[124:125], v[4:5]
	v_pk_mul_f32 v[204:205], v[10:11], v[14:15]
	v_cvt_pk_bf16_f32 v0, v0, v1
	v_pk_fma_f32 v[204:205], v[4:5], v[6:7], v[204:205]
	v_pk_mul_f32 v[6:7], v[10:11], v[6:7]
	v_cvt_f32_f16_sdwa v11, v235 dst_sel:DWORD dst_unused:UNUSED_PAD src0_sel:WORD_1
	v_pk_fma_f32 v[4:5], v[4:5], v[14:15], v[6:7] neg_lo:[0,0,1] neg_hi:[0,0,1]
	v_cvt_f32_f16_sdwa v10, v234 dst_sel:DWORD dst_unused:UNUSED_PAD src0_sel:WORD_1
	v_cvt_pk_bf16_f32 v1, v4, v5
	v_cvt_pk_bf16_f32 v4, v202, v203
	v_cvt_f32_f16_sdwa v203, v209 dst_sel:DWORD dst_unused:UNUSED_PAD src0_sel:WORD_1
	v_cvt_f32_f16_sdwa v202, v208 dst_sel:DWORD dst_unused:UNUSED_PAD src0_sel:WORD_1
	v_cvt_pk_bf16_f32 v5, v204, v205
	v_cvt_f32_f16_e32 v205, v209
	v_cvt_f32_f16_e32 v204, v208
	v_pk_mul_f32 v[6:7], v[8:9], v[202:203] op_sel_hi:[0,1]
	v_pk_mul_f32 v[14:15], v[190:191], v[6:7]
	v_cvt_f32_f16_e32 v209, v211
	v_pk_mul_f32 v[2:3], v[8:9], v[204:205] op_sel_hi:[0,1]
	v_pk_mul_f32 v[2:3], v[120:121], v[2:3]
	v_pk_mul_f32 v[6:7], v[14:15], v[206:207]
	v_cvt_f32_f16_e32 v208, v210
	v_pk_fma_f32 v[6:7], v[2:3], v[10:11], v[6:7]
	v_pk_mul_f32 v[10:11], v[14:15], v[10:11]
	v_cvt_f32_f16_sdwa v15, v237 dst_sel:DWORD dst_unused:UNUSED_PAD src0_sel:WORD_1
	v_pk_fma_f32 v[2:3], v[2:3], v[206:207], v[10:11] neg_lo:[0,0,1] neg_hi:[0,0,1]
	v_cvt_f32_f16_sdwa v207, v211 dst_sel:DWORD dst_unused:UNUSED_PAD src0_sel:WORD_1
	v_cvt_f32_f16_sdwa v206, v210 dst_sel:DWORD dst_unused:UNUSED_PAD src0_sel:WORD_1
	v_cvt_f32_f16_sdwa v14, v236 dst_sel:DWORD dst_unused:UNUSED_PAD src0_sel:WORD_1
	v_cvt_f32_f16_e32 v211, v237
	v_cvt_f32_f16_e32 v210, v236
	v_pk_mul_f32 v[10:11], v[8:9], v[208:209] op_sel_hi:[0,1]
	v_pk_mul_f32 v[8:9], v[8:9], v[206:207] op_sel_hi:[0,1]
	v_pk_mul_f32 v[8:9], v[196:197], v[8:9]
	v_pk_mul_f32 v[10:11], v[126:127], v[10:11]
	v_pk_mul_f32 v[212:213], v[8:9], v[210:211]
	v_pk_mul_f32 v[8:9], v[8:9], v[14:15]
	v_cvt_pk_bf16_f32 v2, v2, v3
	v_pk_fma_f32 v[8:9], v[10:11], v[210:211], v[8:9] neg_lo:[0,0,1] neg_hi:[0,0,1]
	v_pk_fma_f32 v[212:213], v[10:11], v[14:15], v[212:213]
	v_cvt_pk_bf16_f32 v3, v8, v9
	v_mul_lo_u32 v10, s67, v24
	v_mad_u64_u32 v[8:9], s[48:49], s66, v24, 0
	v_add3_u32 v9, v9, v133, v10
	v_lshl_add_u64 v[14:15], v[8:9], 1, v[138:139]
	v_mov_b64_e32 v[250:251], v[14:15]
	s_mul_i32 s98, s66, 32
	s_mov_b32 s99, 0
	s_mul_i32 s100, s66, 0xa0
	s_mov_b32 s101, 0
	global_load_dwordx4 v[8:11], v[12:13], off offset:2048
	global_load_dwordx4 v[234:237], v[12:13], off offset:2064
	v_cvt_pk_bf16_f32 v6, v6, v7
	v_cvt_pk_bf16_f32 v7, v212, v213
	global_store_dwordx4 v[14:15], v[0:3], off
	global_store_dwordx4 v[14:15], v[4:7], off offset:64
	v_lshl_add_u64 v[210:211], v[12:13], 0, s[20:21]
	v_mul_f32_e32 v0, v184, v184
	v_mul_f32_e32 v1, v185, v185
	v_fmac_f32_e32 v0, v114, v114
	v_fmac_f32_e32 v1, v115, v115
	v_add_f32_e32 v2, v0, v1
	v_pk_mul_f32 v[0:1], v[186:187], v[186:187]
	s_waitcnt vmcnt(3)
	v_cvt_f32_f16_e32 v7, v9
	v_pk_fma_f32 v[0:1], v[116:117], v[116:117], v[0:1]
	v_cvt_f32_f16_e32 v6, v8
	v_add_f32_e32 v0, v0, v2
	v_pk_mul_f32 v[2:3], v[182:183], v[182:183]
	v_add_f32_e32 v4, v1, v0
	v_pk_fma_f32 v[2:3], v[112:113], v[112:113], v[2:3]
	v_pk_mul_f32 v[0:1], v[188:189], v[188:189]
	v_add_f32_e32 v2, v2, v4
	v_pk_fma_f32 v[0:1], v[118:119], v[118:119], v[0:1]
	v_add_f32_e32 v2, v3, v2
	v_add_f32_e32 v0, v0, v2
	v_add_f32_e32 v0, v1, v0
	ds_bpermute_b32 v1, v131, v0
	v_cvt_f32_f16_sdwa v3, v9 dst_sel:DWORD dst_unused:UNUSED_PAD src0_sel:WORD_1
	v_cvt_f32_f16_sdwa v2, v8 dst_sel:DWORD dst_unused:UNUSED_PAD src0_sel:WORD_1
	s_waitcnt lgkmcnt(0)
	v_add_f32_e32 v0, v0, v1
	ds_bpermute_b32 v1, v129, v0
	s_waitcnt lgkmcnt(0)
	v_add_f32_e32 v0, v0, v1
	v_mul_f32_e32 v0, v181, v0
	v_mul_f32_e32 v0, v181, v0
	v_fmamk_f32 v0, v0, 0x3c800000, v217
	v_cmp_gt_f32_e32 vcc, s85, v0
	v_mul_f32_e32 v1, 0x4b800000, v0
	s_nop 0
	v_cndmask_b32_e32 v0, v0, v1, vcc
	v_rsq_f32_e32 v0, v0
	s_nop 0
	v_mul_f32_e32 v1, 0x45800000, v0
	v_cndmask_b32_e32 v0, v0, v1, vcc
	v_mul_f32_e32 v0, v181, v0
	v_mul_f32_e32 v14, s83, v0
	v_pk_mul_f32 v[4:5], v[14:15], v[198:199] op_sel_hi:[0,1]
	v_pk_mul_f32 v[0:1], v[14:15], v[200:201] op_sel_hi:[0,1]
	v_pk_mul_f32 v[4:5], v[184:185], v[4:5]
	v_pk_mul_f32 v[0:1], v[114:115], v[0:1]
	v_pk_mul_f32 v[8:9], v[4:5], v[6:7]
	s_nop 0
	v_pk_fma_f32 v[8:9], v[0:1], v[2:3], v[8:9]
	v_pk_mul_f32 v[2:3], v[4:5], v[2:3]
	v_cvt_f32_f16_sdwa v5, v11 dst_sel:DWORD dst_unused:UNUSED_PAD src0_sel:WORD_1
	v_cvt_f32_f16_sdwa v4, v10 dst_sel:DWORD dst_unused:UNUSED_PAD src0_sel:WORD_1
	v_cvt_f32_f16_e32 v11, v11
	v_cvt_f32_f16_e32 v10, v10
	v_pk_fma_f32 v[0:1], v[0:1], v[6:7], v[2:3] neg_lo:[0,0,1] neg_hi:[0,0,1]
	v_pk_mul_f32 v[6:7], v[14:15], v[140:141] op_sel_hi:[0,1]
	v_pk_mul_f32 v[2:3], v[14:15], v[142:143] op_sel_hi:[0,1]
	v_pk_mul_f32 v[6:7], v[186:187], v[6:7]
	v_pk_mul_f32 v[2:3], v[116:117], v[2:3]
	v_pk_mul_f32 v[212:213], v[6:7], v[10:11]
	v_cvt_pk_bf16_f32 v0, v0, v1
	v_pk_fma_f32 v[212:213], v[2:3], v[4:5], v[212:213]
	v_pk_mul_f32 v[4:5], v[6:7], v[4:5]
	v_pk_mul_f32 v[6:7], v[14:15], v[202:203] op_sel_hi:[0,1]
	v_pk_fma_f32 v[2:3], v[2:3], v[10:11], v[4:5] neg_lo:[0,0,1] neg_hi:[0,0,1]
	v_cvt_pk_bf16_f32 v5, v212, v213
	s_waitcnt vmcnt(2)
	v_cvt_f32_f16_e32 v213, v235
	v_cvt_f32_f16_e32 v212, v234
	v_cvt_pk_bf16_f32 v4, v8, v9
	v_cvt_f32_f16_sdwa v9, v235 dst_sel:DWORD dst_unused:UNUSED_PAD src0_sel:WORD_1
	v_cvt_f32_f16_sdwa v8, v234 dst_sel:DWORD dst_unused:UNUSED_PAD src0_sel:WORD_1
	v_cvt_pk_bf16_f32 v1, v2, v3
	v_pk_mul_f32 v[2:3], v[14:15], v[204:205] op_sel_hi:[0,1]
	v_pk_mul_f32 v[10:11], v[182:183], v[6:7]
	v_pk_mul_f32 v[2:3], v[112:113], v[2:3]
	v_pk_mul_f32 v[6:7], v[10:11], v[212:213]
	s_nop 0
	v_pk_fma_f32 v[6:7], v[2:3], v[8:9], v[6:7]
	v_pk_mul_f32 v[8:9], v[10:11], v[8:9]
	v_cvt_f32_f16_sdwa v11, v237 dst_sel:DWORD dst_unused:UNUSED_PAD src0_sel:WORD_1
	v_pk_fma_f32 v[2:3], v[2:3], v[212:213], v[8:9] neg_lo:[0,0,1] neg_hi:[0,0,1]
	v_cvt_f32_f16_e32 v213, v237
	v_cvt_f32_f16_e32 v212, v236
	v_cvt_f32_f16_sdwa v10, v236 dst_sel:DWORD dst_unused:UNUSED_PAD src0_sel:WORD_1
	v_pk_mul_f32 v[8:9], v[14:15], v[208:209] op_sel_hi:[0,1]
	v_pk_mul_f32 v[14:15], v[14:15], v[206:207] op_sel_hi:[0,1]
	v_pk_mul_f32 v[14:15], v[188:189], v[14:15]
	v_pk_mul_f32 v[8:9], v[118:119], v[8:9]
	v_pk_mul_f32 v[230:231], v[14:15], v[212:213]
	v_cvt_pk_bf16_f32 v2, v2, v3
	v_pk_fma_f32 v[230:231], v[8:9], v[10:11], v[230:231]
	v_pk_mul_f32 v[10:11], v[14:15], v[10:11]
	v_add_co_u32_e32 v14, vcc, s86, v12
	v_pk_fma_f32 v[8:9], v[8:9], v[212:213], v[10:11] neg_lo:[0,0,1] neg_hi:[0,0,1]
	v_cvt_pk_bf16_f32 v3, v8, v9
	v_addc_co_u32_e32 v15, vcc, 0, v13, vcc
	v_lshl_add_u64 v[250:251], v[250:251], 0, s[98:99]
	global_load_dwordx4 v[8:11], v[14:15], off
	global_load_dwordx4 v[234:237], v[210:211], off offset:16
	v_cvt_pk_bf16_f32 v6, v6, v7
	v_cvt_pk_bf16_f32 v7, v230, v231
	global_store_dwordx4 v[250:251], v[0:3], off
	global_store_dwordx4 v[250:251], v[4:7], off offset:64
	v_lshl_add_u64 v[12:13], v[12:13], 0, s[22:23]
	v_mul_f32_e32 v0, v84, v84
	v_mul_f32_e32 v1, v85, v85
	v_fmac_f32_e32 v0, v106, v106
	v_fmac_f32_e32 v1, v107, v107
	v_add_f32_e32 v2, v0, v1
	v_pk_mul_f32 v[0:1], v[86:87], v[86:87]
	s_waitcnt vmcnt(3)
	v_cvt_f32_f16_sdwa v5, v9 dst_sel:DWORD dst_unused:UNUSED_PAD src0_sel:WORD_1
	v_pk_fma_f32 v[0:1], v[108:109], v[108:109], v[0:1]
	v_cvt_f32_f16_e32 v9, v9
	v_add_f32_e32 v0, v0, v2
	v_pk_mul_f32 v[2:3], v[82:83], v[82:83]
	v_add_f32_e32 v4, v1, v0
	v_pk_fma_f32 v[2:3], v[104:105], v[104:105], v[2:3]
	v_pk_mul_f32 v[0:1], v[88:89], v[88:89]
	v_add_f32_e32 v2, v2, v4
	v_pk_fma_f32 v[0:1], v[110:111], v[110:111], v[0:1]
	v_add_f32_e32 v2, v3, v2
	v_add_f32_e32 v0, v0, v2
	v_add_f32_e32 v0, v1, v0
	ds_bpermute_b32 v1, v131, v0
	v_cvt_f32_f16_sdwa v4, v8 dst_sel:DWORD dst_unused:UNUSED_PAD src0_sel:WORD_1
	v_cvt_f32_f16_e32 v8, v8
	s_waitcnt lgkmcnt(0)
	v_add_f32_e32 v0, v0, v1
	ds_bpermute_b32 v1, v129, v0
	s_waitcnt lgkmcnt(0)
	v_add_f32_e32 v0, v0, v1
	v_mul_f32_e32 v0, v178, v0
	v_mul_f32_e32 v0, v178, v0
	v_fmamk_f32 v0, v0, 0x3c800000, v217
	v_cmp_gt_f32_e32 vcc, s85, v0
	v_mul_f32_e32 v1, 0x4b800000, v0
	s_nop 0
	v_cndmask_b32_e32 v0, v0, v1, vcc
	v_rsq_f32_e32 v0, v0
	s_nop 0
	v_mul_f32_e32 v1, 0x45800000, v0
	v_cndmask_b32_e32 v0, v0, v1, vcc
	v_mul_f32_e32 v0, v178, v0
	v_mul_f32_e32 v0, s83, v0
	v_pk_mul_f32 v[6:7], v[0:1], v[198:199] op_sel_hi:[0,1]
	v_pk_mul_f32 v[2:3], v[0:1], v[200:201] op_sel_hi:[0,1]
	v_pk_mul_f32 v[6:7], v[84:85], v[6:7]
	v_pk_mul_f32 v[2:3], v[106:107], v[2:3]
	v_pk_mul_f32 v[210:211], v[6:7], v[8:9]
	s_nop 0
	v_pk_fma_f32 v[210:211], v[2:3], v[4:5], v[210:211]
	v_pk_mul_f32 v[4:5], v[6:7], v[4:5]
	v_cvt_f32_f16_sdwa v7, v11 dst_sel:DWORD dst_unused:UNUSED_PAD src0_sel:WORD_1
	v_cvt_f32_f16_sdwa v6, v10 dst_sel:DWORD dst_unused:UNUSED_PAD src0_sel:WORD_1
	v_cvt_f32_f16_e32 v11, v11
	v_cvt_f32_f16_e32 v10, v10
	v_pk_fma_f32 v[2:3], v[2:3], v[8:9], v[4:5] neg_lo:[0,0,1] neg_hi:[0,0,1]
	v_pk_mul_f32 v[8:9], v[0:1], v[140:141] op_sel_hi:[0,1]
	v_pk_mul_f32 v[4:5], v[0:1], v[142:143] op_sel_hi:[0,1]
	v_pk_mul_f32 v[8:9], v[86:87], v[8:9]
	v_pk_mul_f32 v[4:5], v[108:109], v[4:5]
	v_pk_mul_f32 v[212:213], v[8:9], v[10:11]
	s_nop 0
	v_pk_fma_f32 v[212:213], v[4:5], v[6:7], v[212:213]
	v_pk_mul_f32 v[6:7], v[8:9], v[6:7]
	v_cvt_pk_bf16_f32 v9, v212, v213
	v_pk_fma_f32 v[6:7], v[4:5], v[10:11], v[6:7] neg_lo:[0,0,1] neg_hi:[0,0,1]
	s_waitcnt vmcnt(2)
	v_cvt_f32_f16_e32 v213, v235
	v_cvt_f32_f16_e32 v212, v234
	v_cvt_pk_bf16_f32 v5, v6, v7
	v_cvt_f32_f16_sdwa v7, v235 dst_sel:DWORD dst_unused:UNUSED_PAD src0_sel:WORD_1
	v_cvt_f32_f16_sdwa v6, v234 dst_sel:DWORD dst_unused:UNUSED_PAD src0_sel:WORD_1
	v_pk_mul_f32 v[10:11], v[0:1], v[202:203] op_sel_hi:[0,1]
	v_cvt_pk_bf16_f32 v4, v2, v3
	v_cvt_pk_bf16_f32 v8, v210, v211
	v_pk_mul_f32 v[2:3], v[0:1], v[204:205] op_sel_hi:[0,1]
	v_pk_mul_f32 v[210:211], v[82:83], v[10:11]
	v_pk_mul_f32 v[2:3], v[104:105], v[2:3]
	v_pk_mul_f32 v[10:11], v[210:211], v[212:213]
	s_nop 0
	v_pk_fma_f32 v[10:11], v[2:3], v[6:7], v[10:11]
	v_pk_mul_f32 v[6:7], v[210:211], v[6:7]
	v_cvt_f32_f16_sdwa v211, v237 dst_sel:DWORD dst_unused:UNUSED_PAD src0_sel:WORD_1
	v_pk_fma_f32 v[2:3], v[2:3], v[212:213], v[6:7] neg_lo:[0,0,1] neg_hi:[0,0,1]
	v_cvt_f32_f16_sdwa v210, v236 dst_sel:DWORD dst_unused:UNUSED_PAD src0_sel:WORD_1
	v_cvt_f32_f16_e32 v213, v237
	v_cvt_f32_f16_e32 v212, v236
	v_cvt_pk_bf16_f32 v6, v2, v3
	v_pk_mul_f32 v[2:3], v[0:1], v[208:209] op_sel_hi:[0,1]
	v_pk_mul_f32 v[0:1], v[0:1], v[206:207] op_sel_hi:[0,1]
	v_pk_mul_f32 v[0:1], v[88:89], v[0:1]
	v_pk_mul_f32 v[2:3], v[110:111], v[2:3]
	v_pk_mul_f32 v[230:231], v[0:1], v[212:213]
	v_pk_mul_f32 v[0:1], v[0:1], v[210:211]
	v_pk_fma_f32 v[230:231], v[2:3], v[210:211], v[230:231]
	v_pk_fma_f32 v[0:1], v[2:3], v[212:213], v[0:1] neg_lo:[0,0,1] neg_hi:[0,0,1]
	v_cvt_pk_bf16_f32 v7, v0, v1
	v_lshl_add_u64 v[250:251], v[250:251], 0, s[98:99]
	global_load_dwordx4 v[0:3], v[14:15], off offset:2048
	global_load_dwordx4 v[234:237], v[12:13], off offset:16
	v_cvt_pk_bf16_f32 v10, v10, v11
	v_cvt_pk_bf16_f32 v11, v230, v231
	global_store_dwordx4 v[250:251], v[4:7], off
	global_store_dwordx4 v[250:251], v[8:11], off offset:64
	s_nop 0
	v_lshl_add_u32 v4, v24, 5, v219
	v_and_b32_e32 v4, 0xf9e0, v4
	v_lshlrev_b32_e32 v144, 2, v4
	v_mul_f32_e32 v4, v68, v68
	v_mul_f32_e32 v5, v69, v69
	v_fmac_f32_e32 v4, v98, v98
	v_fmac_f32_e32 v5, v99, v99
	v_add_f32_e32 v6, v4, v5
	v_pk_mul_f32 v[4:5], v[70:71], v[70:71]
	v_lshl_add_u64 v[12:13], v[164:165], 0, v[144:145]
	v_pk_fma_f32 v[4:5], v[100:101], v[100:101], v[4:5]
	s_nop 0
	v_add_f32_e32 v4, v4, v6
	v_pk_mul_f32 v[6:7], v[66:67], v[66:67]
	v_add_f32_e32 v8, v5, v4
	v_pk_fma_f32 v[6:7], v[96:97], v[96:97], v[6:7]
	v_pk_mul_f32 v[4:5], v[72:73], v[72:73]
	v_add_f32_e32 v6, v6, v8
	v_pk_fma_f32 v[4:5], v[102:103], v[102:103], v[4:5]
	v_add_f32_e32 v6, v7, v6
	v_add_f32_e32 v4, v4, v6
	v_add_f32_e32 v4, v5, v4
	ds_bpermute_b32 v5, v131, v4
	s_waitcnt lgkmcnt(0)
	v_add_f32_e32 v4, v4, v5
	ds_bpermute_b32 v5, v129, v4
	s_waitcnt lgkmcnt(0)
	v_add_f32_e32 v4, v4, v5
	v_mul_f32_e32 v4, v179, v4
	v_mul_f32_e32 v4, v179, v4
	v_fmamk_f32 v4, v4, 0x3c800000, v217
	v_cmp_gt_f32_e32 vcc, s85, v4
	v_mul_f32_e32 v5, 0x4b800000, v4
	s_waitcnt vmcnt(3)
	v_cvt_f32_f16_sdwa v7, v1 dst_sel:DWORD dst_unused:UNUSED_PAD src0_sel:WORD_1
	v_cndmask_b32_e32 v4, v4, v5, vcc
	v_rsq_f32_e32 v4, v4
	v_cvt_f32_f16_sdwa v6, v0 dst_sel:DWORD dst_unused:UNUSED_PAD src0_sel:WORD_1
	v_cvt_f32_f16_e32 v1, v1
	v_cvt_f32_f16_e32 v0, v0
	v_mul_f32_e32 v5, 0x45800000, v4
	v_cndmask_b32_e32 v4, v4, v5, vcc
	v_mul_f32_e32 v4, v179, v4
	v_mul_f32_e32 v14, s83, v4
	v_pk_mul_f32 v[8:9], v[14:15], v[198:199] op_sel_hi:[0,1]
	v_pk_mul_f32 v[4:5], v[14:15], v[200:201] op_sel_hi:[0,1]
	v_pk_mul_f32 v[8:9], v[68:69], v[8:9]
	v_pk_mul_f32 v[4:5], v[98:99], v[4:5]
	v_pk_mul_f32 v[10:11], v[8:9], v[0:1]
	s_nop 0
	v_pk_fma_f32 v[10:11], v[4:5], v[6:7], v[10:11]
	v_pk_mul_f32 v[6:7], v[8:9], v[6:7]
	v_pk_mul_f32 v[8:9], v[14:15], v[140:141] op_sel_hi:[0,1]
	v_pk_fma_f32 v[0:1], v[4:5], v[0:1], v[6:7] neg_lo:[0,0,1] neg_hi:[0,0,1]
	v_cvt_f32_f16_sdwa v7, v3 dst_sel:DWORD dst_unused:UNUSED_PAD src0_sel:WORD_1
	v_cvt_f32_f16_sdwa v6, v2 dst_sel:DWORD dst_unused:UNUSED_PAD src0_sel:WORD_1
	v_cvt_f32_f16_e32 v3, v3
	v_cvt_f32_f16_e32 v2, v2
	v_pk_mul_f32 v[4:5], v[14:15], v[142:143] op_sel_hi:[0,1]
	v_pk_mul_f32 v[8:9], v[70:71], v[8:9]
	v_pk_mul_f32 v[4:5], v[100:101], v[4:5]
	v_pk_mul_f32 v[210:211], v[8:9], v[2:3]
	s_nop 0
	v_pk_fma_f32 v[210:211], v[4:5], v[6:7], v[210:211]
	v_pk_mul_f32 v[6:7], v[8:9], v[6:7]
	v_cvt_pk_bf16_f32 v9, v210, v211
	v_pk_fma_f32 v[2:3], v[4:5], v[2:3], v[6:7] neg_lo:[0,0,1] neg_hi:[0,0,1]
	s_waitcnt vmcnt(2)
	v_cvt_f32_f16_e32 v211, v235
	v_cvt_f32_f16_e32 v210, v234
	v_cvt_pk_bf16_f32 v5, v2, v3
	v_cvt_f32_f16_sdwa v3, v235 dst_sel:DWORD dst_unused:UNUSED_PAD src0_sel:WORD_1
	v_cvt_f32_f16_sdwa v2, v234 dst_sel:DWORD dst_unused:UNUSED_PAD src0_sel:WORD_1
	v_pk_mul_f32 v[6:7], v[14:15], v[202:203] op_sel_hi:[0,1]
	v_cvt_pk_bf16_f32 v4, v0, v1
	v_pk_mul_f32 v[0:1], v[14:15], v[204:205] op_sel_hi:[0,1]
	v_pk_mul_f32 v[6:7], v[66:67], v[6:7]
	v_cvt_pk_bf16_f32 v8, v10, v11
	v_pk_mul_f32 v[0:1], v[96:97], v[0:1]
	v_pk_mul_f32 v[10:11], v[6:7], v[210:211]
	s_nop 0
	v_pk_fma_f32 v[10:11], v[0:1], v[2:3], v[10:11]
	v_pk_mul_f32 v[2:3], v[6:7], v[2:3]
	v_cvt_pk_bf16_f32 v10, v10, v11
	v_pk_fma_f32 v[0:1], v[0:1], v[210:211], v[2:3] neg_lo:[0,0,1] neg_hi:[0,0,1]
	v_cvt_f32_f16_e32 v211, v237
	v_cvt_f32_f16_e32 v210, v236
	v_cvt_f32_f16_sdwa v3, v237 dst_sel:DWORD dst_unused:UNUSED_PAD src0_sel:WORD_1
	v_cvt_f32_f16_sdwa v2, v236 dst_sel:DWORD dst_unused:UNUSED_PAD src0_sel:WORD_1
	v_cvt_pk_bf16_f32 v6, v0, v1
	v_pk_mul_f32 v[0:1], v[14:15], v[208:209] op_sel_hi:[0,1]
	v_pk_mul_f32 v[14:15], v[14:15], v[206:207] op_sel_hi:[0,1]
	v_pk_mul_f32 v[14:15], v[72:73], v[14:15]
	v_pk_mul_f32 v[0:1], v[102:103], v[0:1]
	v_pk_mul_f32 v[212:213], v[14:15], v[210:211]
	s_nop 0
	v_pk_fma_f32 v[212:213], v[0:1], v[2:3], v[212:213]
	v_pk_mul_f32 v[2:3], v[14:15], v[2:3]
	v_cvt_pk_bf16_f32 v11, v212, v213
	v_pk_fma_f32 v[0:1], v[0:1], v[210:211], v[2:3] neg_lo:[0,0,1] neg_hi:[0,0,1]
	v_cvt_pk_bf16_f32 v7, v0, v1
	v_lshl_add_u64 v[250:251], v[250:251], 0, s[98:99]
	global_load_dwordx4 v[0:3], v[12:13], off
	s_nop 0
	global_load_dwordx4 v[12:15], v[12:13], off offset:16
	v_add_u32_e32 v133, 0x80, v24
	global_store_dwordx4 v[250:251], v[4:7], off
	global_store_dwordx4 v[250:251], v[8:11], off offset:64
	s_nop 0
	v_lshlrev_b32_e32 v4, 7, v133
	v_and_b32_e32 v144, 0x3e780, v4
	v_lshl_add_u64 v[4:5], s[34:35], 0, v[144:145]
	v_lshl_add_u64 v[210:211], v[4:5], 0, v[172:173]
	v_mul_f32_e32 v4, v92, v92
	v_mul_f32_e32 v5, v93, v93
	v_fmac_f32_e32 v4, v58, v58
	v_fmac_f32_e32 v5, v59, v59
	v_add_f32_e32 v6, v4, v5
	v_pk_mul_f32 v[4:5], v[94:95], v[94:95]
	s_nop 0
	v_pk_fma_f32 v[4:5], v[60:61], v[60:61], v[4:5]
	s_nop 0
	v_add_f32_e32 v4, v4, v6
	v_pk_mul_f32 v[6:7], v[90:91], v[90:91]
	v_add_f32_e32 v8, v5, v4
	v_pk_fma_f32 v[6:7], v[56:57], v[56:57], v[6:7]
	v_pk_mul_f32 v[4:5], v[136:137], v[136:137]
	v_add_f32_e32 v6, v6, v8
	v_pk_fma_f32 v[4:5], v[62:63], v[62:63], v[4:5]
	v_add_f32_e32 v6, v7, v6
	v_add_f32_e32 v4, v4, v6
	v_add_f32_e32 v4, v5, v4
	ds_bpermute_b32 v5, v131, v4
	s_waitcnt lgkmcnt(0)
	v_add_f32_e32 v4, v4, v5
	ds_bpermute_b32 v5, v129, v4
	s_waitcnt lgkmcnt(0)
	v_add_f32_e32 v4, v4, v5
	v_mul_f32_e32 v4, v176, v4
	v_mul_f32_e32 v4, v176, v4
	v_fmamk_f32 v4, v4, 0x3c800000, v217
	v_cmp_gt_f32_e32 vcc, s85, v4
	v_mul_f32_e32 v5, 0x4b800000, v4
	s_waitcnt vmcnt(3)
	v_cvt_f32_f16_sdwa v7, v1 dst_sel:DWORD dst_unused:UNUSED_PAD src0_sel:WORD_1
	v_cndmask_b32_e32 v4, v4, v5, vcc
	v_rsq_f32_e32 v4, v4
	v_cvt_f32_f16_sdwa v6, v0 dst_sel:DWORD dst_unused:UNUSED_PAD src0_sel:WORD_1
	v_cvt_f32_f16_e32 v1, v1
	v_cvt_f32_f16_e32 v0, v0
	v_mul_f32_e32 v5, 0x45800000, v4
	v_cndmask_b32_e32 v4, v4, v5, vcc
	v_mul_f32_e32 v4, v176, v4
	v_mul_f32_e32 v8, s83, v4
	v_pk_mul_f32 v[10:11], v[8:9], v[198:199] op_sel_hi:[0,1]
	v_pk_mul_f32 v[4:5], v[8:9], v[200:201] op_sel_hi:[0,1]
	v_pk_mul_f32 v[10:11], v[92:93], v[10:11]
	v_pk_mul_f32 v[4:5], v[58:59], v[4:5]
	v_pk_mul_f32 v[212:213], v[10:11], v[0:1]
	s_nop 0
	v_pk_fma_f32 v[212:213], v[4:5], v[6:7], v[212:213]
	v_pk_mul_f32 v[6:7], v[10:11], v[6:7]
	v_pk_mul_f32 v[10:11], v[8:9], v[140:141] op_sel_hi:[0,1]
	v_pk_fma_f32 v[0:1], v[4:5], v[0:1], v[6:7] neg_lo:[0,0,1] neg_hi:[0,0,1]
	v_cvt_f32_f16_sdwa v7, v3 dst_sel:DWORD dst_unused:UNUSED_PAD src0_sel:WORD_1
	v_cvt_f32_f16_sdwa v6, v2 dst_sel:DWORD dst_unused:UNUSED_PAD src0_sel:WORD_1
	v_cvt_f32_f16_e32 v3, v3
	v_cvt_f32_f16_e32 v2, v2
	v_pk_mul_f32 v[4:5], v[8:9], v[142:143] op_sel_hi:[0,1]
	v_pk_mul_f32 v[10:11], v[94:95], v[10:11]
	v_pk_mul_f32 v[4:5], v[60:61], v[4:5]
	v_pk_mul_f32 v[230:231], v[10:11], v[2:3]
	v_cvt_pk_bf16_f32 v0, v0, v1
	v_pk_fma_f32 v[230:231], v[4:5], v[6:7], v[230:231]
	v_pk_mul_f32 v[6:7], v[10:11], v[6:7]
	s_waitcnt vmcnt(2)
	v_cvt_f32_f16_sdwa v11, v13 dst_sel:DWORD dst_unused:UNUSED_PAD src0_sel:WORD_1
	v_cvt_f32_f16_sdwa v10, v12 dst_sel:DWORD dst_unused:UNUSED_PAD src0_sel:WORD_1
	v_cvt_f32_f16_e32 v13, v13
	v_cvt_f32_f16_e32 v12, v12
	v_pk_fma_f32 v[2:3], v[4:5], v[2:3], v[6:7] neg_lo:[0,0,1] neg_hi:[0,0,1]
	v_pk_mul_f32 v[6:7], v[8:9], v[202:203] op_sel_hi:[0,1]
	v_cvt_pk_bf16_f32 v1, v2, v3
	v_cvt_pk_bf16_f32 v4, v212, v213
	v_pk_mul_f32 v[2:3], v[8:9], v[204:205] op_sel_hi:[0,1]
	v_pk_mul_f32 v[212:213], v[90:91], v[6:7]
	v_pk_mul_f32 v[2:3], v[56:57], v[2:3]
	v_pk_mul_f32 v[6:7], v[212:213], v[12:13]
	v_cvt_pk_bf16_f32 v5, v230, v231
	v_pk_fma_f32 v[6:7], v[2:3], v[10:11], v[6:7]
	v_pk_mul_f32 v[10:11], v[212:213], v[10:11]
	v_cvt_pk_bf16_f32 v6, v6, v7
	v_pk_fma_f32 v[2:3], v[2:3], v[12:13], v[10:11] neg_lo:[0,0,1] neg_hi:[0,0,1]
	v_cvt_f32_f16_sdwa v13, v15 dst_sel:DWORD dst_unused:UNUSED_PAD src0_sel:WORD_1
	v_cvt_f32_f16_sdwa v12, v14 dst_sel:DWORD dst_unused:UNUSED_PAD src0_sel:WORD_1
	v_cvt_f32_f16_e32 v15, v15
	v_cvt_f32_f16_e32 v14, v14
	v_pk_mul_f32 v[10:11], v[8:9], v[208:209] op_sel_hi:[0,1]
	v_pk_mul_f32 v[8:9], v[8:9], v[206:207] op_sel_hi:[0,1]
	v_pk_mul_f32 v[8:9], v[136:137], v[8:9]
	v_pk_mul_f32 v[10:11], v[62:63], v[10:11]
	v_pk_mul_f32 v[212:213], v[8:9], v[14:15]
	v_pk_mul_f32 v[8:9], v[8:9], v[12:13]
	v_cvt_pk_bf16_f32 v2, v2, v3
	v_pk_fma_f32 v[8:9], v[10:11], v[14:15], v[8:9] neg_lo:[0,0,1] neg_hi:[0,0,1]
	v_pk_fma_f32 v[212:213], v[10:11], v[12:13], v[212:213]
	v_cvt_pk_bf16_f32 v3, v8, v9
	v_lshl_add_u64 v[250:251], v[250:251], 0, s[100:101]
	global_load_dwordx4 v[8:11], v[210:211], off offset:2048
	global_load_dwordx4 v[234:237], v[210:211], off offset:2064
	v_cvt_pk_bf16_f32 v7, v212, v213
	global_store_dwordx4 v[250:251], v[0:3], off
	global_store_dwordx4 v[250:251], v[4:7], off offset:64
	v_add_u32_e32 v133, 0x90, v24
	v_mul_f32_e32 v0, v76, v76
	v_mul_f32_e32 v1, v77, v77
	v_fmac_f32_e32 v0, v50, v50
	v_fmac_f32_e32 v1, v51, v51
	v_add_f32_e32 v2, v0, v1
	v_pk_mul_f32 v[0:1], v[78:79], v[78:79]
	v_lshl_add_u64 v[14:15], v[210:211], 0, s[20:21]
	v_pk_fma_f32 v[0:1], v[52:53], v[52:53], v[0:1]
	s_waitcnt vmcnt(3)
	v_cvt_f32_f16_e32 v7, v9
	v_add_f32_e32 v0, v0, v2
	v_pk_mul_f32 v[2:3], v[74:75], v[74:75]
	v_add_f32_e32 v4, v1, v0
	v_pk_fma_f32 v[2:3], v[48:49], v[48:49], v[2:3]
	v_pk_mul_f32 v[0:1], v[80:81], v[80:81]
	v_add_f32_e32 v2, v2, v4
	v_pk_fma_f32 v[0:1], v[54:55], v[54:55], v[0:1]
	v_add_f32_e32 v2, v3, v2
	v_add_f32_e32 v0, v0, v2
	v_add_f32_e32 v0, v1, v0
	ds_bpermute_b32 v1, v131, v0
	v_cvt_f32_f16_e32 v6, v8
	v_cvt_f32_f16_sdwa v3, v9 dst_sel:DWORD dst_unused:UNUSED_PAD src0_sel:WORD_1
	v_cvt_f32_f16_sdwa v2, v8 dst_sel:DWORD dst_unused:UNUSED_PAD src0_sel:WORD_1
	s_waitcnt lgkmcnt(0)
	v_add_f32_e32 v0, v0, v1
	ds_bpermute_b32 v1, v129, v0
	s_waitcnt lgkmcnt(0)
	v_add_f32_e32 v0, v0, v1
	v_mul_f32_e32 v0, v177, v0
	v_mul_f32_e32 v0, v177, v0
	v_fmamk_f32 v0, v0, 0x3c800000, v217
	v_cmp_gt_f32_e32 vcc, s85, v0
	v_mul_f32_e32 v1, 0x4b800000, v0
	s_nop 0
	v_cndmask_b32_e32 v0, v0, v1, vcc
	v_rsq_f32_e32 v0, v0
	s_nop 0
	v_mul_f32_e32 v1, 0x45800000, v0
	v_cndmask_b32_e32 v0, v0, v1, vcc
	v_mul_f32_e32 v0, v177, v0
	v_mul_f32_e32 v12, s83, v0
	v_pk_mul_f32 v[4:5], v[12:13], v[198:199] op_sel_hi:[0,1]
	v_pk_mul_f32 v[0:1], v[12:13], v[200:201] op_sel_hi:[0,1]
	v_pk_mul_f32 v[4:5], v[76:77], v[4:5]
	v_pk_mul_f32 v[0:1], v[50:51], v[0:1]
	v_pk_mul_f32 v[8:9], v[4:5], v[6:7]
	s_nop 0
	v_pk_fma_f32 v[8:9], v[0:1], v[2:3], v[8:9]
	v_pk_mul_f32 v[2:3], v[4:5], v[2:3]
	v_cvt_f32_f16_sdwa v5, v11 dst_sel:DWORD dst_unused:UNUSED_PAD src0_sel:WORD_1
	v_cvt_f32_f16_sdwa v4, v10 dst_sel:DWORD dst_unused:UNUSED_PAD src0_sel:WORD_1
	v_cvt_f32_f16_e32 v11, v11
	v_cvt_f32_f16_e32 v10, v10
	v_pk_fma_f32 v[0:1], v[0:1], v[6:7], v[2:3] neg_lo:[0,0,1] neg_hi:[0,0,1]
	v_pk_mul_f32 v[6:7], v[12:13], v[140:141] op_sel_hi:[0,1]
	v_pk_mul_f32 v[2:3], v[12:13], v[142:143] op_sel_hi:[0,1]
	v_pk_mul_f32 v[6:7], v[78:79], v[6:7]
	v_pk_mul_f32 v[2:3], v[52:53], v[2:3]
	v_pk_mul_f32 v[212:213], v[6:7], v[10:11]
	v_cvt_pk_bf16_f32 v0, v0, v1
	v_pk_fma_f32 v[212:213], v[2:3], v[4:5], v[212:213]
	v_pk_mul_f32 v[4:5], v[6:7], v[4:5]
	v_pk_mul_f32 v[6:7], v[12:13], v[202:203] op_sel_hi:[0,1]
	v_pk_fma_f32 v[2:3], v[2:3], v[10:11], v[4:5] neg_lo:[0,0,1] neg_hi:[0,0,1]
	v_cvt_pk_bf16_f32 v5, v212, v213
	s_waitcnt vmcnt(2)
	v_cvt_f32_f16_e32 v213, v235
	v_cvt_f32_f16_e32 v212, v234
	v_cvt_pk_bf16_f32 v4, v8, v9
	v_cvt_f32_f16_sdwa v9, v235 dst_sel:DWORD dst_unused:UNUSED_PAD src0_sel:WORD_1
	v_cvt_f32_f16_sdwa v8, v234 dst_sel:DWORD dst_unused:UNUSED_PAD src0_sel:WORD_1
	v_cvt_pk_bf16_f32 v1, v2, v3
	v_pk_mul_f32 v[2:3], v[12:13], v[204:205] op_sel_hi:[0,1]
	v_pk_mul_f32 v[10:11], v[74:75], v[6:7]
	v_pk_mul_f32 v[2:3], v[48:49], v[2:3]
	v_pk_mul_f32 v[6:7], v[10:11], v[212:213]
	s_nop 0
	v_pk_fma_f32 v[6:7], v[2:3], v[8:9], v[6:7]
	v_pk_mul_f32 v[8:9], v[10:11], v[8:9]
	v_cvt_f32_f16_sdwa v11, v237 dst_sel:DWORD dst_unused:UNUSED_PAD src0_sel:WORD_1
	v_pk_fma_f32 v[2:3], v[2:3], v[212:213], v[8:9] neg_lo:[0,0,1] neg_hi:[0,0,1]
	v_cvt_f32_f16_e32 v213, v237
	v_cvt_f32_f16_e32 v212, v236
	v_cvt_f32_f16_sdwa v10, v236 dst_sel:DWORD dst_unused:UNUSED_PAD src0_sel:WORD_1
	v_pk_mul_f32 v[8:9], v[12:13], v[208:209] op_sel_hi:[0,1]
	v_pk_mul_f32 v[12:13], v[12:13], v[206:207] op_sel_hi:[0,1]
	v_pk_mul_f32 v[12:13], v[80:81], v[12:13]
	v_pk_mul_f32 v[8:9], v[54:55], v[8:9]
	v_pk_mul_f32 v[230:231], v[12:13], v[212:213]
	v_cvt_pk_bf16_f32 v2, v2, v3
	v_pk_fma_f32 v[230:231], v[8:9], v[10:11], v[230:231]
	v_pk_mul_f32 v[10:11], v[12:13], v[10:11]
	v_add_co_u32_e32 v12, vcc, s86, v210
	v_pk_fma_f32 v[8:9], v[8:9], v[212:213], v[10:11] neg_lo:[0,0,1] neg_hi:[0,0,1]
	v_cvt_pk_bf16_f32 v3, v8, v9
	v_addc_co_u32_e32 v13, vcc, 0, v211, vcc
	v_lshl_add_u64 v[250:251], v[250:251], 0, s[98:99]
	global_load_dwordx4 v[8:11], v[12:13], off
	global_load_dwordx4 v[234:237], v[14:15], off offset:16
	v_cvt_pk_bf16_f32 v6, v6, v7
	v_cvt_pk_bf16_f32 v7, v230, v231
	global_store_dwordx4 v[250:251], v[0:3], off
	global_store_dwordx4 v[250:251], v[4:7], off offset:64
	v_lshl_add_u64 v[14:15], v[210:211], 0, s[22:23]
	v_mul_f32_e32 v0, v28, v28
	v_mul_f32_e32 v1, v29, v29
	v_fmac_f32_e32 v0, v42, v42
	v_fmac_f32_e32 v1, v43, v43
	v_add_f32_e32 v2, v0, v1
	v_pk_mul_f32 v[0:1], v[30:31], v[30:31]
	v_add_u32_e32 v133, 0xa0, v24
	v_pk_fma_f32 v[0:1], v[44:45], v[44:45], v[0:1]
	s_waitcnt vmcnt(3)
	v_cvt_f32_f16_e32 v7, v9
	v_add_f32_e32 v0, v0, v2
	v_pk_mul_f32 v[2:3], v[26:27], v[26:27]
	v_add_f32_e32 v4, v1, v0
	v_pk_fma_f32 v[2:3], v[40:41], v[40:41], v[2:3]
	v_pk_mul_f32 v[0:1], v[64:65], v[64:65]
	v_add_f32_e32 v2, v2, v4
	v_pk_fma_f32 v[0:1], v[46:47], v[46:47], v[0:1]
	v_add_f32_e32 v2, v3, v2
	v_add_f32_e32 v0, v0, v2
	v_add_f32_e32 v0, v1, v0
	ds_bpermute_b32 v1, v131, v0
	v_cvt_f32_f16_e32 v6, v8
	v_cvt_f32_f16_sdwa v3, v9 dst_sel:DWORD dst_unused:UNUSED_PAD src0_sel:WORD_1
	v_cvt_f32_f16_sdwa v2, v8 dst_sel:DWORD dst_unused:UNUSED_PAD src0_sel:WORD_1
	s_waitcnt vmcnt(2)
	v_cvt_f32_f16_e32 v213, v237
	s_waitcnt lgkmcnt(0)
	v_add_f32_e32 v0, v0, v1
	ds_bpermute_b32 v1, v129, v0
	v_cvt_f32_f16_e32 v212, v236
	s_waitcnt lgkmcnt(0)
	v_add_f32_e32 v0, v0, v1
	v_mul_f32_e32 v0, v174, v0
	v_mul_f32_e32 v0, v174, v0
	v_fmamk_f32 v0, v0, 0x3c800000, v217
	v_cmp_gt_f32_e32 vcc, s85, v0
	v_mul_f32_e32 v1, 0x4b800000, v0
	s_nop 0
	v_cndmask_b32_e32 v0, v0, v1, vcc
	v_rsq_f32_e32 v0, v0
	s_nop 0
	v_mul_f32_e32 v1, 0x45800000, v0
	v_cndmask_b32_e32 v0, v0, v1, vcc
	v_mul_f32_e32 v0, v174, v0
	v_mul_f32_e32 v144, s83, v0
	v_pk_mul_f32 v[4:5], v[144:145], v[198:199] op_sel_hi:[0,1]
	v_pk_mul_f32 v[0:1], v[144:145], v[200:201] op_sel_hi:[0,1]
	v_pk_mul_f32 v[4:5], v[28:29], v[4:5]
	v_pk_mul_f32 v[0:1], v[42:43], v[0:1]
	v_pk_mul_f32 v[8:9], v[4:5], v[6:7]
	s_nop 0
	v_pk_fma_f32 v[8:9], v[0:1], v[2:3], v[8:9]
	v_pk_mul_f32 v[2:3], v[4:5], v[2:3]
	v_cvt_f32_f16_sdwa v5, v11 dst_sel:DWORD dst_unused:UNUSED_PAD src0_sel:WORD_1
	v_cvt_f32_f16_sdwa v4, v10 dst_sel:DWORD dst_unused:UNUSED_PAD src0_sel:WORD_1
	v_cvt_f32_f16_e32 v11, v11
	v_cvt_f32_f16_e32 v10, v10
	v_pk_fma_f32 v[0:1], v[0:1], v[6:7], v[2:3] neg_lo:[0,0,1] neg_hi:[0,0,1]
	v_pk_mul_f32 v[6:7], v[144:145], v[140:141] op_sel_hi:[0,1]
	v_pk_mul_f32 v[2:3], v[144:145], v[142:143] op_sel_hi:[0,1]
	v_pk_mul_f32 v[6:7], v[30:31], v[6:7]
	v_pk_mul_f32 v[2:3], v[44:45], v[2:3]
	v_pk_mul_f32 v[210:211], v[6:7], v[10:11]
	v_cvt_pk_bf16_f32 v0, v0, v1
	v_pk_fma_f32 v[210:211], v[2:3], v[4:5], v[210:211]
	v_pk_mul_f32 v[4:5], v[6:7], v[4:5]
	v_pk_mul_f32 v[6:7], v[144:145], v[202:203] op_sel_hi:[0,1]
	v_pk_fma_f32 v[2:3], v[2:3], v[10:11], v[4:5] neg_lo:[0,0,1] neg_hi:[0,0,1]
	v_cvt_pk_bf16_f32 v5, v210, v211
	v_cvt_f32_f16_e32 v211, v235
	v_cvt_f32_f16_e32 v210, v234
	v_cvt_pk_bf16_f32 v4, v8, v9
	v_cvt_f32_f16_sdwa v9, v235 dst_sel:DWORD dst_unused:UNUSED_PAD src0_sel:WORD_1
	v_cvt_f32_f16_sdwa v8, v234 dst_sel:DWORD dst_unused:UNUSED_PAD src0_sel:WORD_1
	v_cvt_pk_bf16_f32 v1, v2, v3
	v_pk_mul_f32 v[2:3], v[144:145], v[204:205] op_sel_hi:[0,1]
	v_pk_mul_f32 v[10:11], v[26:27], v[6:7]
	v_pk_mul_f32 v[2:3], v[40:41], v[2:3]
	v_pk_mul_f32 v[6:7], v[10:11], v[210:211]
	s_nop 0
	v_pk_fma_f32 v[6:7], v[2:3], v[8:9], v[6:7]
	v_pk_mul_f32 v[8:9], v[10:11], v[8:9]
	v_cvt_f32_f16_sdwa v11, v237 dst_sel:DWORD dst_unused:UNUSED_PAD src0_sel:WORD_1
	v_cvt_f32_f16_sdwa v10, v236 dst_sel:DWORD dst_unused:UNUSED_PAD src0_sel:WORD_1
	v_pk_fma_f32 v[2:3], v[2:3], v[210:211], v[8:9] neg_lo:[0,0,1] neg_hi:[0,0,1]
	v_pk_mul_f32 v[210:211], v[144:145], v[206:207] op_sel_hi:[0,1]
	v_pk_mul_f32 v[8:9], v[144:145], v[208:209] op_sel_hi:[0,1]
	v_pk_mul_f32 v[210:211], v[64:65], v[210:211]
	v_pk_mul_f32 v[8:9], v[46:47], v[8:9]
	v_pk_mul_f32 v[230:231], v[210:211], v[212:213]
	v_cvt_pk_bf16_f32 v2, v2, v3
	v_pk_fma_f32 v[230:231], v[8:9], v[10:11], v[230:231]
	v_pk_mul_f32 v[10:11], v[210:211], v[10:11]
	v_cvt_pk_bf16_f32 v6, v6, v7
	v_pk_fma_f32 v[8:9], v[8:9], v[212:213], v[10:11] neg_lo:[0,0,1] neg_hi:[0,0,1]
	v_cvt_pk_bf16_f32 v3, v8, v9
	v_lshl_add_u64 v[250:251], v[250:251], 0, s[98:99]
	global_load_dwordx4 v[8:11], v[12:13], off offset:2048
	s_nop 0
	global_load_dwordx4 v[12:15], v[14:15], off offset:16
	v_cvt_pk_bf16_f32 v7, v230, v231
	global_store_dwordx4 v[250:251], v[0:3], off
	global_store_dwordx4 v[250:251], v[4:7], off offset:64
	v_add_u32_e32 v133, 0xb0, v24
	v_mul_f32_e32 v0, v18, v18
	v_mul_f32_e32 v1, v19, v19
	v_fmac_f32_e32 v0, v34, v34
	v_fmac_f32_e32 v1, v35, v35
	v_add_f32_e32 v2, v0, v1
	v_pk_mul_f32 v[0:1], v[20:21], v[20:21]
	s_waitcnt vmcnt(3)
	v_cvt_f32_f16_e32 v7, v9
	v_pk_fma_f32 v[0:1], v[36:37], v[36:37], v[0:1]
	v_cvt_f32_f16_e32 v6, v8
	v_add_f32_e32 v0, v0, v2
	v_pk_mul_f32 v[2:3], v[16:17], v[16:17]
	v_add_f32_e32 v4, v1, v0
	v_pk_fma_f32 v[2:3], v[32:33], v[32:33], v[2:3]
	v_pk_mul_f32 v[0:1], v[22:23], v[22:23]
	v_add_f32_e32 v2, v2, v4
	v_pk_fma_f32 v[0:1], v[38:39], v[38:39], v[0:1]
	v_add_f32_e32 v2, v3, v2
	v_add_f32_e32 v0, v0, v2
	v_add_f32_e32 v0, v1, v0
	ds_bpermute_b32 v1, v131, v0
	v_cvt_f32_f16_sdwa v3, v9 dst_sel:DWORD dst_unused:UNUSED_PAD src0_sel:WORD_1
	v_cvt_f32_f16_sdwa v2, v8 dst_sel:DWORD dst_unused:UNUSED_PAD src0_sel:WORD_1
	s_waitcnt lgkmcnt(0)
	v_add_f32_e32 v0, v0, v1
	ds_bpermute_b32 v1, v129, v0
	s_waitcnt lgkmcnt(0)
	v_add_f32_e32 v0, v0, v1
	v_mul_f32_e32 v0, v175, v0
	v_mul_f32_e32 v0, v175, v0
	v_fmamk_f32 v0, v0, 0x3c800000, v217
	v_cmp_gt_f32_e32 vcc, s85, v0
	v_mul_f32_e32 v1, 0x4b800000, v0
	s_nop 0
	v_cndmask_b32_e32 v0, v0, v1, vcc
	v_rsq_f32_e32 v0, v0
	s_nop 0
	v_mul_f32_e32 v1, 0x45800000, v0
	v_cndmask_b32_e32 v0, v0, v1, vcc
	v_mul_f32_e32 v0, v175, v0
	v_mul_f32_e32 v144, s83, v0
	v_pk_mul_f32 v[4:5], v[144:145], v[198:199] op_sel_hi:[0,1]
	v_pk_mul_f32 v[0:1], v[144:145], v[200:201] op_sel_hi:[0,1]
	v_pk_mul_f32 v[4:5], v[18:19], v[4:5]
	v_pk_mul_f32 v[0:1], v[34:35], v[0:1]
	v_pk_mul_f32 v[8:9], v[4:5], v[6:7]
	s_nop 0
	v_pk_fma_f32 v[8:9], v[0:1], v[2:3], v[8:9]
	v_pk_mul_f32 v[2:3], v[4:5], v[2:3]
	v_cvt_f32_f16_sdwa v5, v11 dst_sel:DWORD dst_unused:UNUSED_PAD src0_sel:WORD_1
	v_cvt_f32_f16_sdwa v4, v10 dst_sel:DWORD dst_unused:UNUSED_PAD src0_sel:WORD_1
	v_cvt_f32_f16_e32 v11, v11
	v_cvt_f32_f16_e32 v10, v10
	v_pk_fma_f32 v[0:1], v[0:1], v[6:7], v[2:3] neg_lo:[0,0,1] neg_hi:[0,0,1]
	v_pk_mul_f32 v[6:7], v[144:145], v[140:141] op_sel_hi:[0,1]
	v_pk_mul_f32 v[2:3], v[144:145], v[142:143] op_sel_hi:[0,1]
	v_pk_mul_f32 v[6:7], v[20:21], v[6:7]
	v_pk_mul_f32 v[2:3], v[36:37], v[2:3]
	v_pk_mul_f32 v[140:141], v[6:7], v[10:11]
	v_cvt_pk_bf16_f32 v0, v0, v1
	v_pk_fma_f32 v[140:141], v[2:3], v[4:5], v[140:141]
	v_pk_mul_f32 v[4:5], v[6:7], v[4:5]
	v_pk_mul_f32 v[6:7], v[144:145], v[202:203] op_sel_hi:[0,1]
	v_pk_fma_f32 v[2:3], v[2:3], v[10:11], v[4:5] neg_lo:[0,0,1] neg_hi:[0,0,1]
	v_cvt_pk_bf16_f32 v4, v8, v9
	s_waitcnt vmcnt(2)
	v_cvt_f32_f16_sdwa v9, v13 dst_sel:DWORD dst_unused:UNUSED_PAD src0_sel:WORD_1
	v_cvt_f32_f16_sdwa v8, v12 dst_sel:DWORD dst_unused:UNUSED_PAD src0_sel:WORD_1
	v_cvt_f32_f16_e32 v13, v13
	v_cvt_f32_f16_e32 v12, v12
	v_cvt_pk_bf16_f32 v1, v2, v3
	v_pk_mul_f32 v[2:3], v[144:145], v[204:205] op_sel_hi:[0,1]
	v_pk_mul_f32 v[10:11], v[16:17], v[6:7]
	v_pk_mul_f32 v[2:3], v[32:33], v[2:3]
	v_pk_mul_f32 v[6:7], v[10:11], v[12:13]
	v_cvt_pk_bf16_f32 v5, v140, v141
	v_pk_fma_f32 v[6:7], v[2:3], v[8:9], v[6:7]
	v_pk_mul_f32 v[8:9], v[10:11], v[8:9]
	v_cvt_f32_f16_sdwa v11, v15 dst_sel:DWORD dst_unused:UNUSED_PAD src0_sel:WORD_1
	v_cvt_f32_f16_sdwa v10, v14 dst_sel:DWORD dst_unused:UNUSED_PAD src0_sel:WORD_1
	v_cvt_f32_f16_e32 v15, v15
	v_cvt_f32_f16_e32 v14, v14
	v_pk_fma_f32 v[2:3], v[2:3], v[12:13], v[8:9] neg_lo:[0,0,1] neg_hi:[0,0,1]
	v_pk_mul_f32 v[12:13], v[144:145], v[206:207] op_sel_hi:[0,1]
	v_pk_mul_f32 v[8:9], v[144:145], v[208:209] op_sel_hi:[0,1]
	v_pk_mul_f32 v[12:13], v[22:23], v[12:13]
	v_pk_mul_f32 v[8:9], v[38:39], v[8:9]
	v_pk_mul_f32 v[140:141], v[12:13], v[14:15]
	v_cvt_pk_bf16_f32 v2, v2, v3
	v_pk_fma_f32 v[140:141], v[8:9], v[10:11], v[140:141]
	v_pk_mul_f32 v[10:11], v[12:13], v[10:11]
	v_cvt_pk_bf16_f32 v6, v6, v7
	v_pk_fma_f32 v[8:9], v[8:9], v[14:15], v[10:11] neg_lo:[0,0,1] neg_hi:[0,0,1]
	v_cvt_pk_bf16_f32 v3, v8, v9
	v_lshl_add_u64 v[250:251], v[250:251], 0, s[98:99]
	v_cvt_pk_bf16_f32 v7, v140, v141
	global_store_dwordx4 v[250:251], v[0:3], off
	global_store_dwordx4 v[250:251], v[4:7], off offset:64

.LBB0_1494:
	s_andn2_b64 vcc, exec, s[34:35]
	s_cbranch_vccnz .LBB0_1501
	s_and_b32 s6, s12, 1
	s_lshl_b32 s7, s6, 12
	v_add_u32_e32 v1, s7, v230
	v_lshl_add_u32 v2, s6, 10, v229
	s_waitcnt lgkmcnt(0)
	ds_read2st64_b32 v[182:183], v1 offset0:4 offset1:5
	ds_read2st64_b32 v[180:181], v1 offset0:6 offset1:7
	ds_read_b128 v[128:131], v2
	ds_read_b128 v[112:115], v2 offset:16
	ds_read_b128 v[124:127], v2 offset:512
	ds_read_b128 v[108:111], v2 offset:528
	s_and_b64 vcc, exec, s[58:59]
	v_lshlrev_b32_e32 v2, 1, v206
	s_mov_b32 s98, 0x3fb8aa3b
	s_mov_b32 s99, 0x3fb8aa3b
	s_mov_b32 s100, 0x3f317218
	s_mov_b32 s101, 0x3f317218
	s_waitcnt lgkmcnt(0)
	v_pk_mul_f32 v[128:129], v[128:129], s[98:99]
	v_pk_mul_f32 v[130:131], v[130:131], s[98:99]
	v_pk_mul_f32 v[112:113], v[112:113], s[98:99]
	v_pk_mul_f32 v[114:115], v[114:115], s[98:99]
	v_pk_mul_f32 v[124:125], v[124:125], s[100:101]
	v_pk_mul_f32 v[126:127], v[126:127], s[100:101]
	v_pk_mul_f32 v[108:109], v[108:109], s[100:101]
	v_pk_mul_f32 v[110:111], v[110:111], s[100:101]
	s_mov_b32 s98, 0x16000
	s_mov_b32 s99, 0
	s_cbranch_vccz .LBB0_1497
	ds_read2st64_b32 v[184:185], v1 offset1:1
	v_cvt_f32_i32_e32 v187, v177
	v_cvt_f32_i32_e32 v186, v176
	ds_read2st64_b32 v[176:177], v1 offset0:2 offset1:3
	v_cvt_f32_i32_e32 v179, v179
	s_waitcnt lgkmcnt(0)
	v_pk_mul_f32 v[188:189], v[128:129], v[184:185] op_sel_hi:[1,0]
	v_cvt_f32_i32_e32 v178, v178
	v_pk_mul_f32 v[186:187], v[188:189], v[186:187]
	v_pk_mul_f32 v[192:193], v[130:131], v[184:185] op_sel_hi:[1,0]
	v_exp_f32_e64 v1, -v186
	v_exp_f32_e64 v3, -v187
	v_pk_mul_f32 v[178:179], v[192:193], v[178:179]
	v_add_f32_e32 v1, 1.0, v1
	v_rcp_f32_e32 v188, v1
	v_add_f32_e32 v1, 1.0, v3
	v_rcp_f32_e32 v189, v1
	v_cvt_f32_i32_e32 v173, v173
	v_cvt_f32_i32_e32 v172, v172
	v_exp_f32_e64 v1, -v178
	v_pk_mul_f32 v[190:191], v[124:125], v[184:185] op_sel_hi:[1,0]
	v_pk_mul_f32 v[186:187], v[186:187], v[188:189]
	v_pk_mul_f32 v[172:173], v[190:191], v[172:173]
	v_add_f32_e32 v1, 1.0, v1
	v_pk_mul_f32 v[172:173], v[172:173], v[186:187]
	v_rcp_f32_e32 v186, v1
	v_exp_f32_e64 v1, -v179
	v_cvt_f32_i32_e32 v169, v169
	v_cvt_f32_i32_e32 v168, v168
	v_pk_mul_f32 v[190:191], v[112:113], v[184:185] op_sel_hi:[1,0]
	v_add_f32_e32 v1, 1.0, v1
	v_rcp_f32_e32 v187, v1
	v_pk_mul_f32 v[168:169], v[190:191], v[168:169]
	v_cvt_f32_i32_e32 v175, v175
	v_cvt_f32_i32_e32 v174, v174
	v_exp_f32_e64 v1, -v168
	v_pk_mul_f32 v[188:189], v[126:127], v[184:185] op_sel_hi:[1,0]
	v_pk_mul_f32 v[178:179], v[178:179], v[186:187]
	v_pk_mul_f32 v[174:175], v[188:189], v[174:175]
	v_add_f32_e32 v1, 1.0, v1
	v_pk_mul_f32 v[174:175], v[174:175], v[178:179]
	v_rcp_f32_e32 v178, v1
	v_exp_f32_e64 v1, -v169
	v_cvt_f32_i32_e32 v171, v171
	v_cvt_f32_i32_e32 v170, v170
	v_pk_mul_f32 v[186:187], v[114:115], v[184:185] op_sel_hi:[1,0]
	v_add_f32_e32 v1, 1.0, v1
	v_rcp_f32_e32 v179, v1
	v_pk_mul_f32 v[170:171], v[186:187], v[170:171]
	v_cvt_f32_i32_e32 v165, v165
	v_exp_f32_e64 v1, -v170
	v_exp_f32_e64 v3, -v171
	v_cvt_f32_i32_e32 v164, v164
	v_add_f32_e32 v1, 1.0, v1
	v_pk_mul_f32 v[168:169], v[168:169], v[178:179]
	v_rcp_f32_e32 v178, v1
	v_add_f32_e32 v1, 1.0, v3
	v_cvt_f32_i32_e32 v167, v167
	v_cvt_f32_i32_e32 v166, v166
	v_rcp_f32_e32 v179, v1
	v_pk_mul_f32 v[186:187], v[108:109], v[184:185] op_sel_hi:[1,0]
	v_cvt_f32_i32_e32 v161, v161
	v_pk_mul_f32 v[164:165], v[186:187], v[164:165]
	v_cvt_f32_i32_e32 v160, v160
	v_pk_mul_f32 v[164:165], v[164:165], v[168:169]
	v_pk_mul_f32 v[168:169], v[110:111], v[184:185] op_sel_hi:[1,0]
	s_lshl_b32 s41, s56, 8
	v_pk_mul_f32 v[166:167], v[168:169], v[166:167]
	v_pk_mul_f32 v[168:169], v[170:171], v[178:179]
	v_add_u32_e32 v1, s41, v221
	v_pk_mul_f32 v[170:171], v[166:167], v[168:169]
	v_cvt_pk_bf16_f32 v166, v172, v173
	v_mov_b32_e32 v172, v185
	v_cvt_pk_bf16_f32 v167, v174, v175
	v_cvt_pk_bf16_f32 v168, v164, v165
	v_mov_b64_e32 v[164:165], s[30:31]
	v_pk_mul_f32 v[174:175], v[128:129], v[172:173] op_sel_hi:[1,0]
	v_cvt_pk_bf16_f32 v169, v170, v171
	v_mad_i64_i32 v[170:171], s[6:7], v1, s66, v[164:165]
	v_pk_mul_f32 v[160:161], v[174:175], v[160:161]
	s_lshl_b32 s6, s54, 7
	s_ashr_i32 s7, s6, 31
	v_exp_f32_e64 v1, -v160
	s_lshl_b64 s[8:9], s[6:7], 1
	v_lshl_add_u64 v[170:171], v[170:171], 0, s[8:9]
	s_lshl_b32 s12, s79, 1
	v_lshl_add_u64 v[170:171], v[170:171], 0, s[12:13]
	v_mov_b32_e32 v3, v0
	v_lshl_add_u64 v[170:171], v[170:171], 0, v[2:3]
	v_add_f32_e32 v1, 1.0, v1
	v_mov_b64_e32 v[4:5], v[170:171]
	global_store_dwordx4 v[170:171], v[166:169], off
	v_cvt_f32_i32_e32 v163, v163
	v_cvt_f32_i32_e32 v162, v162
	v_rcp_f32_e32 v166, v1
	v_exp_f32_e64 v1, -v161
	v_pk_mul_f32 v[170:171], v[130:131], v[172:173] op_sel_hi:[1,0]
	v_cvt_f32_i32_e32 v157, v157
	v_pk_mul_f32 v[162:163], v[170:171], v[162:163]
	v_add_f32_e32 v1, 1.0, v1
	v_rcp_f32_e32 v167, v1
	v_cvt_f32_i32_e32 v156, v156
	v_exp_f32_e64 v1, -v162
	v_pk_mul_f32 v[168:169], v[124:125], v[172:173] op_sel_hi:[1,0]
	v_pk_mul_f32 v[160:161], v[160:161], v[166:167]
	v_pk_mul_f32 v[156:157], v[168:169], v[156:157]
	v_add_f32_e32 v1, 1.0, v1
	v_pk_mul_f32 v[156:157], v[156:157], v[160:161]
	v_rcp_f32_e32 v160, v1
	v_exp_f32_e64 v1, -v163
	v_cvt_f32_i32_e32 v153, v153
	v_cvt_f32_i32_e32 v152, v152
	v_pk_mul_f32 v[168:169], v[112:113], v[172:173] op_sel_hi:[1,0]
	v_add_f32_e32 v1, 1.0, v1
	v_rcp_f32_e32 v161, v1
	v_pk_mul_f32 v[152:153], v[168:169], v[152:153]
	v_cvt_f32_i32_e32 v159, v159
	v_cvt_f32_i32_e32 v158, v158
	v_exp_f32_e64 v1, -v152
	v_pk_mul_f32 v[166:167], v[126:127], v[172:173] op_sel_hi:[1,0]
	v_pk_mul_f32 v[160:161], v[162:163], v[160:161]
	v_pk_mul_f32 v[158:159], v[166:167], v[158:159]
	v_add_f32_e32 v1, 1.0, v1
	v_pk_mul_f32 v[158:159], v[158:159], v[160:161]
	v_rcp_f32_e32 v160, v1
	v_exp_f32_e64 v1, -v153
	v_cvt_f32_i32_e32 v155, v155
	v_cvt_f32_i32_e32 v154, v154
	v_pk_mul_f32 v[162:163], v[114:115], v[172:173] op_sel_hi:[1,0]
	v_add_f32_e32 v1, 1.0, v1
	v_rcp_f32_e32 v161, v1
	v_pk_mul_f32 v[154:155], v[162:163], v[154:155]
	v_cvt_f32_i32_e32 v149, v149
	v_exp_f32_e64 v1, -v154
	v_pk_mul_f32 v[152:153], v[152:153], v[160:161]
	v_exp_f32_e64 v161, -v155
	v_cvt_f32_i32_e32 v148, v148
	v_add_f32_e32 v1, 1.0, v1
	v_rcp_f32_e32 v160, v1
	v_add_f32_e32 v1, 1.0, v161
	v_cvt_f32_i32_e32 v151, v151
	v_cvt_f32_i32_e32 v150, v150
	v_rcp_f32_e32 v161, v1
	v_pk_mul_f32 v[162:163], v[108:109], v[172:173] op_sel_hi:[1,0]
	v_cvt_f32_i32_e32 v145, v145
	v_pk_mul_f32 v[148:149], v[162:163], v[148:149]
	v_cvt_f32_i32_e32 v144, v144
	v_pk_mul_f32 v[152:153], v[148:149], v[152:153]
	v_pk_mul_f32 v[148:149], v[110:111], v[172:173] op_sel_hi:[1,0]
	v_pk_mul_f32 v[148:149], v[148:149], v[150:151]
	v_pk_mul_f32 v[150:151], v[154:155], v[160:161]
	v_cvt_f32_i32_e32 v147, v147
	v_pk_mul_f32 v[154:155], v[148:149], v[150:151]
	v_cvt_pk_bf16_f32 v150, v152, v153
	v_cvt_pk_bf16_f32 v151, v154, v155
	v_pk_mul_f32 v[154:155], v[128:129], v[176:177] op_sel_hi:[1,0]
	v_pk_mul_f32 v[144:145], v[154:155], v[144:145]
	v_exp_f32_e64 v1, -v144
	v_cvt_pk_bf16_f32 v148, v156, v157
	v_cvt_pk_bf16_f32 v149, v158, v159
	v_add_f32_e32 v1, 1.0, v1
	v_lshl_add_u64 v[4:5], v[4:5], 0, s[98:99]
	global_store_dwordx4 v[4:5], v[148:151], off
	v_cvt_f32_i32_e32 v146, v146
	v_pk_mul_f32 v[152:153], v[130:131], v[176:177] op_sel_hi:[1,0]
	v_rcp_f32_e32 v148, v1
	v_exp_f32_e64 v1, -v145
	v_pk_mul_f32 v[146:147], v[152:153], v[146:147]
	v_cvt_f32_i32_e32 v141, v141
	v_cvt_f32_i32_e32 v140, v140
	v_add_f32_e32 v1, 1.0, v1
	v_rcp_f32_e32 v149, v1
	v_exp_f32_e64 v1, -v146
	v_pk_mul_f32 v[150:151], v[124:125], v[176:177] op_sel_hi:[1,0]
	v_pk_mul_f32 v[144:145], v[144:145], v[148:149]
	v_pk_mul_f32 v[140:141], v[150:151], v[140:141]
	v_add_f32_e32 v1, 1.0, v1
	v_pk_mul_f32 v[140:141], v[140:141], v[144:145]
	v_rcp_f32_e32 v144, v1
	v_exp_f32_e64 v1, -v147
	v_cvt_f32_i32_e32 v137, v137
	v_cvt_f32_i32_e32 v136, v136
	v_pk_mul_f32 v[150:151], v[112:113], v[176:177] op_sel_hi:[1,0]
	v_add_f32_e32 v1, 1.0, v1
	v_rcp_f32_e32 v145, v1
	v_pk_mul_f32 v[136:137], v[150:151], v[136:137]
	v_cvt_f32_i32_e32 v143, v143
	v_cvt_f32_i32_e32 v142, v142
	v_exp_f32_e64 v1, -v136
	v_pk_mul_f32 v[148:149], v[126:127], v[176:177] op_sel_hi:[1,0]
	v_pk_mul_f32 v[144:145], v[146:147], v[144:145]
	v_pk_mul_f32 v[142:143], v[148:149], v[142:143]
	v_add_f32_e32 v1, 1.0, v1
	v_pk_mul_f32 v[142:143], v[142:143], v[144:145]
	v_rcp_f32_e32 v144, v1
	v_exp_f32_e64 v1, -v137
	v_cvt_f32_i32_e32 v139, v139
	v_cvt_f32_i32_e32 v138, v138
	v_pk_mul_f32 v[146:147], v[114:115], v[176:177] op_sel_hi:[1,0]
	v_add_f32_e32 v1, 1.0, v1
	v_rcp_f32_e32 v145, v1
	v_pk_mul_f32 v[138:139], v[146:147], v[138:139]
	v_cvt_f32_i32_e32 v133, v133
	v_exp_f32_e64 v1, -v138
	v_pk_mul_f32 v[136:137], v[136:137], v[144:145]
	v_exp_f32_e64 v145, -v139
	v_cvt_f32_i32_e32 v132, v132
	v_add_f32_e32 v1, 1.0, v1
	v_rcp_f32_e32 v144, v1
	v_add_f32_e32 v1, 1.0, v145
	v_cvt_f32_i32_e32 v135, v135
	v_cvt_f32_i32_e32 v134, v134
	v_rcp_f32_e32 v145, v1
	v_pk_mul_f32 v[146:147], v[108:109], v[176:177] op_sel_hi:[1,0]
	v_cvt_f32_i32_e32 v121, v121
	v_pk_mul_f32 v[132:133], v[146:147], v[132:133]
	v_cvt_f32_i32_e32 v120, v120
	v_pk_mul_f32 v[136:137], v[132:133], v[136:137]
	v_pk_mul_f32 v[132:133], v[110:111], v[176:177] op_sel_hi:[1,0]
	v_pk_mul_f32 v[132:133], v[132:133], v[134:135]
	v_pk_mul_f32 v[134:135], v[138:139], v[144:145]
	v_cvt_f32_i32_e32 v123, v123
	v_pk_mul_f32 v[138:139], v[132:133], v[134:135]
	v_cvt_pk_bf16_f32 v132, v140, v141
	v_cvt_pk_bf16_f32 v135, v138, v139
	v_mov_b32_e32 v138, v177
	v_pk_mul_f32 v[140:141], v[128:129], v[138:139] op_sel_hi:[1,0]
	v_cvt_pk_bf16_f32 v134, v136, v137
	v_pk_mul_f32 v[120:121], v[140:141], v[120:121]
	v_exp_f32_e64 v1, -v120
	v_cvt_pk_bf16_f32 v133, v142, v143
	v_add_f32_e32 v1, 1.0, v1
	v_lshl_add_u64 v[4:5], v[4:5], 0, s[98:99]
	global_store_dwordx4 v[4:5], v[132:135], off
	v_cvt_f32_i32_e32 v122, v122
	v_pk_mul_f32 v[136:137], v[130:131], v[138:139] op_sel_hi:[1,0]
	v_rcp_f32_e32 v132, v1
	v_exp_f32_e64 v1, -v121
	v_pk_mul_f32 v[122:123], v[136:137], v[122:123]
	v_cvt_f32_i32_e32 v117, v117
	v_cvt_f32_i32_e32 v116, v116
	v_add_f32_e32 v1, 1.0, v1
	v_rcp_f32_e32 v133, v1
	v_exp_f32_e64 v1, -v122
	v_pk_mul_f32 v[134:135], v[124:125], v[138:139] op_sel_hi:[1,0]
	v_pk_mul_f32 v[120:121], v[120:121], v[132:133]
	v_pk_mul_f32 v[116:117], v[134:135], v[116:117]
	v_add_f32_e32 v1, 1.0, v1
	v_pk_mul_f32 v[116:117], v[116:117], v[120:121]
	v_rcp_f32_e32 v120, v1
	v_exp_f32_e64 v1, -v123
	v_cvt_f32_i32_e32 v105, v105
	v_cvt_f32_i32_e32 v104, v104
	v_pk_mul_f32 v[134:135], v[112:113], v[138:139] op_sel_hi:[1,0]
	v_add_f32_e32 v1, 1.0, v1
	v_rcp_f32_e32 v121, v1
	v_pk_mul_f32 v[104:105], v[134:135], v[104:105]
	v_cvt_f32_i32_e32 v119, v119
	v_cvt_f32_i32_e32 v118, v118
	v_exp_f32_e64 v1, -v104
	v_pk_mul_f32 v[132:133], v[126:127], v[138:139] op_sel_hi:[1,0]
	v_pk_mul_f32 v[120:121], v[122:123], v[120:121]
	v_pk_mul_f32 v[118:119], v[132:133], v[118:119]
	v_add_f32_e32 v1, 1.0, v1
	v_pk_mul_f32 v[118:119], v[118:119], v[120:121]
	v_rcp_f32_e32 v120, v1
	v_exp_f32_e64 v1, -v105
	v_cvt_f32_i32_e32 v107, v107
	v_cvt_f32_i32_e32 v106, v106
	v_pk_mul_f32 v[122:123], v[114:115], v[138:139] op_sel_hi:[1,0]
	v_add_f32_e32 v1, 1.0, v1
	v_rcp_f32_e32 v121, v1
	v_pk_mul_f32 v[106:107], v[122:123], v[106:107]
	v_cvt_f32_i32_e32 v101, v101
	v_exp_f32_e64 v1, -v106
	v_pk_mul_f32 v[104:105], v[104:105], v[120:121]
	v_exp_f32_e64 v121, -v107
	v_cvt_f32_i32_e32 v100, v100
	v_add_f32_e32 v1, 1.0, v1
	v_rcp_f32_e32 v120, v1
	v_add_f32_e32 v1, 1.0, v121
	v_cvt_f32_i32_e32 v103, v103
	v_cvt_f32_i32_e32 v102, v102
	v_rcp_f32_e32 v121, v1
	v_pk_mul_f32 v[122:123], v[108:109], v[138:139] op_sel_hi:[1,0]
	v_pk_mul_f32 v[100:101], v[122:123], v[100:101]
	s_nop 0
	v_pk_mul_f32 v[104:105], v[100:101], v[104:105]
	v_pk_mul_f32 v[100:101], v[110:111], v[138:139] op_sel_hi:[1,0]
	s_nop 0
	v_pk_mul_f32 v[100:101], v[100:101], v[102:103]
	v_pk_mul_f32 v[102:103], v[106:107], v[120:121]
	s_nop 0
	v_pk_mul_f32 v[106:107], v[100:101], v[102:103]
	v_cvt_pk_bf16_f32 v102, v104, v105
	v_cvt_pk_bf16_f32 v100, v116, v117
	v_cvt_pk_bf16_f32 v101, v118, v119
	v_cvt_pk_bf16_f32 v103, v106, v107
	v_lshl_add_u64 v[4:5], v[4:5], 0, s[98:99]
	global_store_dwordx4 v[4:5], v[100:103], off
	s_cbranch_execz .LBB0_1498
	s_branch .LBB0_1499

.LBB0_1499:
	s_andn2_b64 vcc, exec, s[48:49]
	s_cbranch_vccnz .LBB0_1501
	v_cvt_f32_i32_e32 v97, v97
	v_cvt_f32_i32_e32 v96, v96
	s_waitcnt lgkmcnt(0)
	v_pk_mul_f32 v[100:101], v[182:183], v[128:129] op_sel_hi:[0,1]
	v_cvt_f32_i32_e32 v93, v93
	v_cvt_f32_i32_e32 v92, v92
	v_pk_mul_f32 v[96:97], v[100:101], v[96:97]
	v_cvt_f32_i32_e32 v99, v99
	v_exp_f32_e64 v1, -v96
	v_cvt_f32_i32_e32 v98, v98
	v_pk_mul_f32 v[102:103], v[182:183], v[124:125] op_sel_hi:[0,1]
	v_add_f32_e32 v1, 1.0, v1
	v_rcp_f32_e32 v100, v1
	v_exp_f32_e64 v1, -v97
	v_pk_mul_f32 v[92:93], v[102:103], v[92:93]
	v_pk_mul_f32 v[102:103], v[182:183], v[130:131] op_sel_hi:[0,1]
	v_pk_mul_f32 v[98:99], v[102:103], v[98:99]
	v_add_f32_e32 v1, 1.0, v1
	v_rcp_f32_e32 v101, v1
	v_exp_f32_e64 v1, -v98
	v_cvt_f32_i32_e32 v89, v89
	v_pk_mul_f32 v[96:97], v[96:97], v[100:101]
	v_cvt_f32_i32_e32 v88, v88
	v_add_f32_e32 v1, 1.0, v1
	v_rcp_f32_e32 v100, v1
	v_exp_f32_e64 v1, -v99
	v_pk_mul_f32 v[102:103], v[182:183], v[112:113] op_sel_hi:[0,1]
	v_pk_mul_f32 v[88:89], v[102:103], v[88:89]
	v_cvt_f32_i32_e32 v95, v95
	v_add_f32_e32 v1, 1.0, v1
	v_rcp_f32_e32 v101, v1
	v_cvt_f32_i32_e32 v94, v94
	v_exp_f32_e64 v1, -v88
	v_pk_mul_f32 v[92:93], v[92:93], v[96:97]
	v_pk_mul_f32 v[96:97], v[182:183], v[126:127] op_sel_hi:[0,1]
	v_pk_mul_f32 v[94:95], v[96:97], v[94:95]
	v_pk_mul_f32 v[96:97], v[98:99], v[100:101]
	v_add_f32_e32 v1, 1.0, v1
	v_pk_mul_f32 v[94:95], v[94:95], v[96:97]
	v_rcp_f32_e32 v96, v1
	v_exp_f32_e64 v1, -v89
	v_cvt_f32_i32_e32 v91, v91
	v_cvt_f32_i32_e32 v90, v90
	v_pk_mul_f32 v[98:99], v[182:183], v[114:115] op_sel_hi:[0,1]
	v_add_f32_e32 v1, 1.0, v1
	v_rcp_f32_e32 v97, v1
	v_pk_mul_f32 v[90:91], v[98:99], v[90:91]
	v_cvt_f32_i32_e32 v85, v85
	v_exp_f32_e64 v1, -v90
	v_exp_f32_e64 v3, -v91
	v_cvt_f32_i32_e32 v84, v84
	v_add_f32_e32 v1, 1.0, v1
	v_pk_mul_f32 v[88:89], v[88:89], v[96:97]
	v_rcp_f32_e32 v96, v1
	v_add_f32_e32 v1, 1.0, v3
	v_cvt_f32_i32_e32 v87, v87
	v_cvt_f32_i32_e32 v86, v86
	v_rcp_f32_e32 v97, v1
	v_pk_mul_f32 v[98:99], v[182:183], v[108:109] op_sel_hi:[0,1]
	v_pk_mul_f32 v[84:85], v[98:99], v[84:85]
	v_cvt_f32_i32_e32 v81, v81
	v_pk_mul_f32 v[84:85], v[84:85], v[88:89]
	v_pk_mul_f32 v[88:89], v[182:183], v[110:111] op_sel_hi:[0,1]
	v_cvt_f32_i32_e32 v80, v80
	v_pk_mul_f32 v[86:87], v[88:89], v[86:87]
	v_pk_mul_f32 v[88:89], v[90:91], v[96:97]
	v_add_u32_e32 v1, s41, v225
	v_pk_mul_f32 v[90:91], v[86:87], v[88:89]
	v_cvt_pk_bf16_f32 v86, v92, v93
	v_mov_b32_e32 v92, v183
	v_cvt_pk_bf16_f32 v87, v94, v95
	v_pk_mul_f32 v[94:95], v[92:93], v[128:129] op_sel_hi:[0,1]
	v_cvt_pk_bf16_f32 v88, v84, v85
	v_mov_b64_e32 v[84:85], s[30:31]
	v_pk_mul_f32 v[80:81], v[94:95], v[80:81]
	v_cvt_pk_bf16_f32 v89, v90, v91
	v_mad_i64_i32 v[90:91], s[8:9], v1, s66, v[84:85]
	v_exp_f32_e64 v1, -v80
	s_lshl_b64 s[6:7], s[6:7], 1
	v_lshl_add_u64 v[90:91], v[90:91], 0, s[6:7]
	s_lshl_b32 s12, s79, 1
	v_lshl_add_u64 v[90:91], v[90:91], 0, s[12:13]
	v_mov_b32_e32 v3, v0
	v_lshl_add_u64 v[90:91], v[90:91], 0, v[2:3]
	v_add_f32_e32 v1, 1.0, v1
	v_mov_b64_e32 v[4:5], v[90:91]
	global_store_dwordx4 v[90:91], v[86:89], off
	v_cvt_f32_i32_e32 v83, v83
	v_cvt_f32_i32_e32 v82, v82
	v_rcp_f32_e32 v86, v1
	v_exp_f32_e64 v1, -v81
	v_pk_mul_f32 v[90:91], v[92:93], v[130:131] op_sel_hi:[0,1]
	v_pk_mul_f32 v[82:83], v[90:91], v[82:83]
	v_cvt_f32_i32_e32 v77, v77
	v_add_f32_e32 v1, 1.0, v1
	v_rcp_f32_e32 v87, v1
	v_cvt_f32_i32_e32 v76, v76
	v_exp_f32_e64 v1, -v82
	v_pk_mul_f32 v[88:89], v[92:93], v[124:125] op_sel_hi:[0,1]
	v_pk_mul_f32 v[80:81], v[80:81], v[86:87]
	v_pk_mul_f32 v[76:77], v[88:89], v[76:77]
	v_add_f32_e32 v1, 1.0, v1
	v_pk_mul_f32 v[76:77], v[76:77], v[80:81]
	v_rcp_f32_e32 v80, v1
	v_exp_f32_e64 v1, -v83
	v_cvt_f32_i32_e32 v73, v73
	v_cvt_f32_i32_e32 v72, v72
	v_pk_mul_f32 v[88:89], v[92:93], v[112:113] op_sel_hi:[0,1]
	v_add_f32_e32 v1, 1.0, v1
	v_rcp_f32_e32 v81, v1
	v_pk_mul_f32 v[72:73], v[88:89], v[72:73]
	v_cvt_f32_i32_e32 v79, v79
	v_cvt_f32_i32_e32 v78, v78
	v_exp_f32_e64 v1, -v72
	v_pk_mul_f32 v[86:87], v[92:93], v[126:127] op_sel_hi:[0,1]
	v_pk_mul_f32 v[80:81], v[82:83], v[80:81]
	v_pk_mul_f32 v[78:79], v[86:87], v[78:79]
	v_add_f32_e32 v1, 1.0, v1
	v_pk_mul_f32 v[78:79], v[78:79], v[80:81]
	v_rcp_f32_e32 v80, v1
	v_exp_f32_e64 v1, -v73
	v_cvt_f32_i32_e32 v75, v75
	v_cvt_f32_i32_e32 v74, v74
	v_pk_mul_f32 v[82:83], v[92:93], v[114:115] op_sel_hi:[0,1]
	v_add_f32_e32 v1, 1.0, v1
	v_rcp_f32_e32 v81, v1
	v_pk_mul_f32 v[74:75], v[82:83], v[74:75]
	v_cvt_f32_i32_e32 v69, v69
	v_exp_f32_e64 v1, -v74
	v_pk_mul_f32 v[72:73], v[72:73], v[80:81]
	v_exp_f32_e64 v81, -v75
	v_cvt_f32_i32_e32 v68, v68
	v_add_f32_e32 v1, 1.0, v1
	v_rcp_f32_e32 v80, v1
	v_add_f32_e32 v1, 1.0, v81
	v_cvt_f32_i32_e32 v71, v71
	v_cvt_f32_i32_e32 v70, v70
	v_rcp_f32_e32 v81, v1
	v_pk_mul_f32 v[82:83], v[92:93], v[108:109] op_sel_hi:[0,1]
	v_pk_mul_f32 v[68:69], v[82:83], v[68:69]
	v_cvt_f32_i32_e32 v65, v65
	v_pk_mul_f32 v[72:73], v[68:69], v[72:73]
	v_pk_mul_f32 v[68:69], v[92:93], v[110:111] op_sel_hi:[0,1]
	v_cvt_f32_i32_e32 v64, v64
	v_pk_mul_f32 v[68:69], v[68:69], v[70:71]
	v_pk_mul_f32 v[70:71], v[74:75], v[80:81]
	v_pk_mul_f32 v[74:75], v[68:69], v[70:71]
	v_cvt_pk_bf16_f32 v70, v72, v73
	v_cvt_pk_bf16_f32 v71, v74, v75
	v_pk_mul_f32 v[74:75], v[180:181], v[128:129] op_sel_hi:[0,1]
	v_pk_mul_f32 v[64:65], v[74:75], v[64:65]
	v_exp_f32_e64 v1, -v64
	v_cvt_pk_bf16_f32 v68, v76, v77
	v_cvt_pk_bf16_f32 v69, v78, v79
	v_add_f32_e32 v1, 1.0, v1
	v_lshl_add_u64 v[4:5], v[4:5], 0, s[98:99]
	global_store_dwordx4 v[4:5], v[68:71], off
	v_cvt_f32_i32_e32 v67, v67
	v_cvt_f32_i32_e32 v66, v66
	v_rcp_f32_e32 v68, v1
	v_exp_f32_e64 v1, -v65
	v_pk_mul_f32 v[72:73], v[180:181], v[130:131] op_sel_hi:[0,1]
	v_pk_mul_f32 v[66:67], v[72:73], v[66:67]
	v_cvt_f32_i32_e32 v61, v61
	v_add_f32_e32 v1, 1.0, v1
	v_rcp_f32_e32 v69, v1
	v_cvt_f32_i32_e32 v60, v60
	v_exp_f32_e64 v1, -v66
	v_pk_mul_f32 v[70:71], v[180:181], v[124:125] op_sel_hi:[0,1]
	v_pk_mul_f32 v[64:65], v[64:65], v[68:69]
	v_pk_mul_f32 v[60:61], v[70:71], v[60:61]
	v_add_f32_e32 v1, 1.0, v1
	v_pk_mul_f32 v[60:61], v[60:61], v[64:65]
	v_rcp_f32_e32 v64, v1
	v_exp_f32_e64 v1, -v67
	v_cvt_f32_i32_e32 v57, v57
	v_cvt_f32_i32_e32 v56, v56
	v_pk_mul_f32 v[70:71], v[180:181], v[112:113] op_sel_hi:[0,1]
	v_add_f32_e32 v1, 1.0, v1
	v_rcp_f32_e32 v65, v1
	v_pk_mul_f32 v[56:57], v[70:71], v[56:57]
	v_cvt_f32_i32_e32 v63, v63
	v_cvt_f32_i32_e32 v62, v62
	v_exp_f32_e64 v1, -v56
	v_pk_mul_f32 v[68:69], v[180:181], v[126:127] op_sel_hi:[0,1]
	v_pk_mul_f32 v[64:65], v[66:67], v[64:65]
	v_pk_mul_f32 v[62:63], v[68:69], v[62:63]
	v_add_f32_e32 v1, 1.0, v1
	v_pk_mul_f32 v[62:63], v[62:63], v[64:65]
	v_rcp_f32_e32 v64, v1
	v_exp_f32_e64 v1, -v57
	v_cvt_f32_i32_e32 v59, v59
	v_cvt_f32_i32_e32 v58, v58
	v_pk_mul_f32 v[66:67], v[180:181], v[114:115] op_sel_hi:[0,1]
	v_add_f32_e32 v1, 1.0, v1
	v_rcp_f32_e32 v65, v1
	v_pk_mul_f32 v[58:59], v[66:67], v[58:59]
	v_cvt_f32_i32_e32 v53, v53
	v_exp_f32_e64 v1, -v58
	v_pk_mul_f32 v[56:57], v[56:57], v[64:65]
	v_exp_f32_e64 v65, -v59
	v_cvt_f32_i32_e32 v52, v52
	v_add_f32_e32 v1, 1.0, v1
	v_rcp_f32_e32 v64, v1
	v_add_f32_e32 v1, 1.0, v65
	v_cvt_f32_i32_e32 v55, v55
	v_cvt_f32_i32_e32 v54, v54
	v_rcp_f32_e32 v65, v1
	v_pk_mul_f32 v[66:67], v[180:181], v[108:109] op_sel_hi:[0,1]
	v_pk_mul_f32 v[52:53], v[66:67], v[52:53]
	v_cvt_f32_i32_e32 v49, v49
	v_pk_mul_f32 v[56:57], v[52:53], v[56:57]
	v_pk_mul_f32 v[52:53], v[180:181], v[110:111] op_sel_hi:[0,1]
	v_pk_mul_f32 v[52:53], v[52:53], v[54:55]
	v_pk_mul_f32 v[54:55], v[58:59], v[64:65]
	v_cvt_f32_i32_e32 v48, v48
	v_pk_mul_f32 v[58:59], v[52:53], v[54:55]
	v_cvt_pk_bf16_f32 v52, v60, v61
	v_cvt_pk_bf16_f32 v55, v58, v59
	v_mov_b32_e32 v58, v181
	v_pk_mul_f32 v[60:61], v[58:59], v[128:129] op_sel_hi:[0,1]
	v_pk_mul_f32 v[48:49], v[60:61], v[48:49]
	v_cvt_pk_bf16_f32 v54, v56, v57
	v_exp_f32_e64 v1, -v48
	v_cvt_pk_bf16_f32 v53, v62, v63
	v_add_f32_e32 v1, 1.0, v1
	v_lshl_add_u64 v[4:5], v[4:5], 0, s[98:99]
	global_store_dwordx4 v[4:5], v[52:55], off
	v_cvt_f32_i32_e32 v51, v51
	v_cvt_f32_i32_e32 v50, v50
	v_rcp_f32_e32 v52, v1
	v_exp_f32_e64 v1, -v49
	v_pk_mul_f32 v[56:57], v[58:59], v[130:131] op_sel_hi:[0,1]
	v_pk_mul_f32 v[50:51], v[56:57], v[50:51]
	v_cvt_f32_i32_e32 v45, v45
	v_add_f32_e32 v1, 1.0, v1
	v_rcp_f32_e32 v53, v1
	v_cvt_f32_i32_e32 v44, v44
	v_exp_f32_e64 v1, -v50
	v_pk_mul_f32 v[54:55], v[58:59], v[124:125] op_sel_hi:[0,1]
	v_pk_mul_f32 v[48:49], v[48:49], v[52:53]
	v_pk_mul_f32 v[44:45], v[54:55], v[44:45]
	v_add_f32_e32 v1, 1.0, v1
	v_pk_mul_f32 v[44:45], v[44:45], v[48:49]
	v_rcp_f32_e32 v48, v1
	v_exp_f32_e64 v1, -v51
	v_cvt_f32_i32_e32 v41, v41
	v_cvt_f32_i32_e32 v40, v40
	v_pk_mul_f32 v[54:55], v[58:59], v[112:113] op_sel_hi:[0,1]
	v_add_f32_e32 v1, 1.0, v1
	v_rcp_f32_e32 v49, v1
	v_pk_mul_f32 v[40:41], v[54:55], v[40:41]
	v_cvt_f32_i32_e32 v47, v47
	v_cvt_f32_i32_e32 v46, v46
	v_exp_f32_e64 v1, -v40
	v_pk_mul_f32 v[52:53], v[58:59], v[126:127] op_sel_hi:[0,1]
	v_pk_mul_f32 v[48:49], v[50:51], v[48:49]
	v_pk_mul_f32 v[46:47], v[52:53], v[46:47]
	v_add_f32_e32 v1, 1.0, v1
	v_pk_mul_f32 v[46:47], v[46:47], v[48:49]
	v_rcp_f32_e32 v48, v1
	v_exp_f32_e64 v1, -v41
	v_cvt_f32_i32_e32 v43, v43
	v_cvt_f32_i32_e32 v42, v42
	v_pk_mul_f32 v[50:51], v[58:59], v[114:115] op_sel_hi:[0,1]
	v_add_f32_e32 v1, 1.0, v1
	v_rcp_f32_e32 v49, v1
	v_pk_mul_f32 v[42:43], v[50:51], v[42:43]
	v_cvt_f32_i32_e32 v37, v37
	v_exp_f32_e64 v1, -v42
	v_pk_mul_f32 v[40:41], v[40:41], v[48:49]
	v_exp_f32_e64 v49, -v43
	v_cvt_f32_i32_e32 v36, v36
	v_add_f32_e32 v1, 1.0, v1
	v_rcp_f32_e32 v48, v1
	v_add_f32_e32 v1, 1.0, v49
	v_cvt_f32_i32_e32 v39, v39
	v_cvt_f32_i32_e32 v38, v38
	v_rcp_f32_e32 v49, v1
	v_pk_mul_f32 v[50:51], v[58:59], v[108:109] op_sel_hi:[0,1]
	v_pk_mul_f32 v[36:37], v[50:51], v[36:37]
	v_pk_mul_f32 v[40:41], v[36:37], v[40:41]
	v_pk_mul_f32 v[36:37], v[58:59], v[110:111] op_sel_hi:[0,1]
	v_pk_mul_f32 v[36:37], v[36:37], v[38:39]
	v_pk_mul_f32 v[38:39], v[42:43], v[48:49]
	s_nop 0
	v_pk_mul_f32 v[42:43], v[36:37], v[38:39]
	v_cvt_pk_bf16_f32 v38, v40, v41
	v_cvt_pk_bf16_f32 v36, v44, v45
	v_cvt_pk_bf16_f32 v37, v46, v47
	v_cvt_pk_bf16_f32 v39, v42, v43
	v_lshl_add_u64 v[4:5], v[4:5], 0, s[98:99]
	global_store_dwordx4 v[4:5], v[36:39], off

.LBB0_2213:
	s_and_b32 s71, s71, 1
	v_lshl_add_u32 v128, s71, 12, v227
	ds_read2st64_b32 v[178:179], v128 offset1:1
	ds_read2st64_b32 v[176:177], v128 offset0:2 offset1:3
	ds_read2st64_b32 v[174:175], v128 offset0:4 offset1:5
	ds_read2st64_b32 v[172:173], v128 offset0:6 offset1:7
	v_lshl_add_u32 v128, s71, 10, v226
	ds_read_b128 v[140:143], v128
	ds_read_b128 v[136:139], v128 offset:16
	ds_read_b128 v[132:135], v128 offset:512
	ds_read_b128 v[128:131], v128 offset:528
	v_cvt_f32_i32_e32 v83, v83
	v_cvt_f32_i32_e32 v82, v82
	v_cvt_f32_i32_e32 v73, v73
	v_cvt_f32_i32_e32 v72, v72
	v_cvt_f32_i32_e32 v65, v65
	v_cvt_f32_i32_e32 v64, v64
	v_cvt_f32_i32_e32 v127, v127
	v_cvt_f32_i32_e32 v126, v126
	v_cvt_f32_i32_e32 v125, v125
	v_cvt_f32_i32_e32 v124, v124
	v_cvt_f32_i32_e32 v181, v123
	v_cvt_f32_i32_e32 v180, v122
	s_waitcnt lgkmcnt(0)
	v_pk_mul_f32 v[186:187], v[130:131], v[82:83]
	v_pk_mul_f32 v[82:83], v[128:129], v[72:73]
	v_cvt_f32_i32_e32 v73, v67
	v_cvt_f32_i32_e32 v72, v66
	v_pk_mul_f32 v[66:67], v[128:129], v[64:65]
	v_cvt_f32_i32_e32 v63, v63
	v_cvt_f32_i32_e32 v62, v62
	v_cvt_f32_i32_e32 v61, v61
	v_cvt_f32_i32_e32 v60, v60
	v_cvt_f32_i32_e32 v65, v59
	v_cvt_f32_i32_e32 v64, v58
	v_pk_mul_f32 v[122:123], v[140:141], v[124:125]
	v_pk_mul_f32 v[124:125], v[142:143], v[126:127]
	v_pk_mul_f32 v[126:127], v[138:139], v[180:181]
	v_cvt_f32_i32_e32 v119, v119
	v_cvt_f32_i32_e32 v118, v118
	v_cvt_f32_i32_e32 v117, v117
	v_cvt_f32_i32_e32 v116, v116
	v_cvt_f32_i32_e32 v181, v115
	v_cvt_f32_i32_e32 v180, v114
	v_pk_mul_f32 v[58:59], v[140:141], v[60:61]
	v_pk_mul_f32 v[60:61], v[142:143], v[62:63]
	v_pk_mul_f32 v[62:63], v[138:139], v[64:65]
	v_cvt_f32_i32_e32 v55, v55
	v_cvt_f32_i32_e32 v54, v54
	v_cvt_f32_i32_e32 v53, v53
	v_cvt_f32_i32_e32 v52, v52
	v_cvt_f32_i32_e32 v65, v51
	v_cvt_f32_i32_e32 v64, v50
	v_pk_mul_f32 v[114:115], v[140:141], v[116:117]
	v_pk_mul_f32 v[116:117], v[142:143], v[118:119]
	v_pk_mul_f32 v[118:119], v[138:139], v[180:181]
	v_cvt_f32_i32_e32 v111, v111
	v_cvt_f32_i32_e32 v110, v110
	v_cvt_f32_i32_e32 v109, v109
	v_cvt_f32_i32_e32 v108, v108
	v_cvt_f32_i32_e32 v181, v107
	v_cvt_f32_i32_e32 v180, v106
	v_pk_mul_f32 v[50:51], v[140:141], v[52:53]
	v_pk_mul_f32 v[52:53], v[142:143], v[54:55]
	v_pk_mul_f32 v[54:55], v[138:139], v[64:65]
	v_cvt_f32_i32_e32 v47, v47
	v_cvt_f32_i32_e32 v46, v46
	v_cvt_f32_i32_e32 v45, v45
	v_cvt_f32_i32_e32 v44, v44
	v_cvt_f32_i32_e32 v65, v43
	v_cvt_f32_i32_e32 v64, v42
	v_cvt_f32_i32_e32 v95, v95
	v_cvt_f32_i32_e32 v94, v94
	v_cvt_f32_i32_e32 v91, v91
	v_cvt_f32_i32_e32 v90, v90
	v_cvt_f32_i32_e32 v87, v87
	v_cvt_f32_i32_e32 v86, v86
	v_cvt_f32_i32_e32 v85, v85
	v_cvt_f32_i32_e32 v84, v84
	v_cvt_f32_i32_e32 v79, v79
	v_cvt_f32_i32_e32 v78, v78
	v_cvt_f32_i32_e32 v77, v77
	v_cvt_f32_i32_e32 v76, v76
	v_cvt_f32_i32_e32 v71, v71
	v_cvt_f32_i32_e32 v70, v70
	v_cvt_f32_i32_e32 v31, v31
	v_cvt_f32_i32_e32 v30, v30
	v_cvt_f32_i32_e32 v25, v25
	v_cvt_f32_i32_e32 v24, v24
	v_cvt_f32_i32_e32 v23, v23
	v_cvt_f32_i32_e32 v22, v22
	v_cvt_f32_i32_e32 v21, v21
	v_cvt_f32_i32_e32 v20, v20
	v_cvt_f32_i32_e32 v15, v15
	v_cvt_f32_i32_e32 v14, v14
	v_cvt_f32_i32_e32 v7, v7
	v_cvt_f32_i32_e32 v6, v6
	v_cvt_f32_i32_e32 v121, v121
	v_cvt_f32_i32_e32 v120, v120
	v_cvt_f32_i32_e32 v113, v113
	v_cvt_f32_i32_e32 v112, v112
	v_cvt_f32_i32_e32 v105, v105
	v_cvt_f32_i32_e32 v104, v104
	v_pk_mul_f32 v[106:107], v[140:141], v[108:109]
	v_pk_mul_f32 v[108:109], v[142:143], v[110:111]
	v_pk_mul_f32 v[110:111], v[138:139], v[180:181]
	v_cvt_f32_i32_e32 v103, v103
	v_cvt_f32_i32_e32 v102, v102
	v_cvt_f32_i32_e32 v101, v101
	v_cvt_f32_i32_e32 v100, v100
	v_cvt_f32_i32_e32 v181, v99
	v_cvt_f32_i32_e32 v97, v97
	v_cvt_f32_i32_e32 v96, v96
	v_cvt_f32_i32_e32 v180, v98
	v_cvt_f32_i32_e32 v93, v93
	v_cvt_f32_i32_e32 v92, v92
	v_cvt_f32_i32_e32 v89, v89
	v_cvt_f32_i32_e32 v88, v88
	v_cvt_f32_i32_e32 v81, v81
	v_cvt_f32_i32_e32 v80, v80
	v_cvt_f32_i32_e32 v75, v75
	v_cvt_f32_i32_e32 v74, v74
	v_cvt_f32_i32_e32 v69, v69
	v_cvt_f32_i32_e32 v68, v68
	v_cvt_f32_i32_e32 v57, v57
	v_cvt_f32_i32_e32 v56, v56
	v_cvt_f32_i32_e32 v49, v49
	v_cvt_f32_i32_e32 v48, v48
	v_cvt_f32_i32_e32 v41, v41
	v_cvt_f32_i32_e32 v40, v40
	v_pk_mul_f32 v[42:43], v[140:141], v[44:45]
	v_pk_mul_f32 v[44:45], v[142:143], v[46:47]
	v_pk_mul_f32 v[46:47], v[138:139], v[64:65]
	v_cvt_f32_i32_e32 v39, v39
	v_cvt_f32_i32_e32 v38, v38
	v_cvt_f32_i32_e32 v37, v37
	v_cvt_f32_i32_e32 v36, v36
	v_cvt_f32_i32_e32 v65, v35
	v_cvt_f32_i32_e32 v33, v33
	v_cvt_f32_i32_e32 v32, v32
	v_cvt_f32_i32_e32 v64, v34
	v_cvt_f32_i32_e32 v29, v29
	v_cvt_f32_i32_e32 v28, v28
	v_cvt_f32_i32_e32 v27, v27
	v_cvt_f32_i32_e32 v26, v26
	v_cvt_f32_i32_e32 v19, v19
	v_cvt_f32_i32_e32 v17, v17
	v_cvt_f32_i32_e32 v16, v16
	v_cvt_f32_i32_e32 v18, v18
	v_cvt_f32_i32_e32 v13, v13
	v_cvt_f32_i32_e32 v12, v12
	v_cvt_f32_i32_e32 v11, v11
	v_cvt_f32_i32_e32 v9, v9
	v_cvt_f32_i32_e32 v8, v8
	v_cvt_f32_i32_e32 v10, v10
	v_cvt_f32_i32_e32 v5, v5
	v_cvt_f32_i32_e32 v4, v4
	v_cvt_f32_i32_e32 v3, v3
	v_cvt_f32_i32_e32 v1, v1
	v_cvt_f32_i32_e32 v0, v0
	v_cvt_f32_i32_e32 v2, v2
	v_pk_mul_f32 v[192:193], v[134:135], v[94:95]
	v_pk_mul_f32 v[194:195], v[130:131], v[90:91]
	v_pk_mul_f32 v[182:183], v[132:133], v[84:85]
	v_pk_mul_f32 v[184:185], v[134:135], v[86:87]
	v_pk_mul_f32 v[84:85], v[132:133], v[76:77]
	v_pk_mul_f32 v[86:87], v[134:135], v[78:79]
	v_pk_mul_f32 v[70:71], v[134:135], v[70:71]
	v_pk_mul_f32 v[94:95], v[134:135], v[30:31]
	v_pk_mul_f32 v[90:91], v[128:129], v[24:25]
	v_pk_mul_f32 v[76:77], v[132:133], v[20:21]
	v_pk_mul_f32 v[78:79], v[134:135], v[22:23]
	v_pk_mul_f32 v[30:31], v[134:135], v[14:15]
	v_pk_mul_f32 v[20:21], v[134:135], v[6:7]
	v_lshl_or_b32 v134, s61, 6, v158
	v_lshl_add_u32 v24, s70, 8, v224
	v_pk_mul_f32 v[120:121], v[136:137], v[120:121]
	v_pk_mul_f32 v[112:113], v[136:137], v[112:113]
	v_pk_mul_f32 v[104:105], v[136:137], v[104:105]
	v_pk_mul_f32 v[98:99], v[140:141], v[100:101]
	v_pk_mul_f32 v[100:101], v[142:143], v[102:103]
	v_pk_mul_f32 v[96:97], v[136:137], v[96:97]
	v_pk_mul_f32 v[102:103], v[138:139], v[180:181]
	v_pk_mul_f32 v[190:191], v[132:133], v[92:93]
	v_pk_mul_f32 v[188:189], v[128:129], v[88:89]
	v_pk_mul_f32 v[180:181], v[128:129], v[80:81]
	v_pk_mul_f32 v[88:89], v[130:131], v[74:75]
	v_pk_mul_f32 v[68:69], v[132:133], v[68:69]
	v_pk_mul_f32 v[72:73], v[130:131], v[72:73]
	v_pk_mul_f32 v[56:57], v[136:137], v[56:57]
	v_pk_mul_f32 v[48:49], v[136:137], v[48:49]
	v_pk_mul_f32 v[40:41], v[136:137], v[40:41]
	v_pk_mul_f32 v[34:35], v[140:141], v[36:37]
	v_pk_mul_f32 v[36:37], v[142:143], v[38:39]
	v_pk_mul_f32 v[32:33], v[136:137], v[32:33]
	v_pk_mul_f32 v[38:39], v[138:139], v[64:65]
	v_pk_mul_f32 v[92:93], v[132:133], v[28:29]
	v_pk_mul_f32 v[136:137], v[130:131], v[26:27]
	v_pk_mul_f32 v[74:75], v[128:129], v[16:17]
	v_pk_mul_f32 v[80:81], v[130:131], v[18:19]
	v_pk_mul_f32 v[28:29], v[132:133], v[12:13]
	v_pk_mul_f32 v[26:27], v[128:129], v[8:9]
	v_pk_mul_f32 v[64:65], v[130:131], v[10:11]
	v_pk_mul_f32 v[18:19], v[132:133], v[4:5]
	v_pk_mul_f32 v[16:17], v[128:129], v[0:1]
	v_pk_mul_f32 v[22:23], v[130:131], v[2:3]
	s_mov_b64 s[70:71], -1
	s_andn2_b64 vcc, exec, s[48:49]
	v_ashrrev_i32_e32 v135, 31, v134
	v_ashrrev_i32_e32 v25, 31, v24
	v_or_b32_e32 v132, 16, v24
	v_or_b32_e32 v130, 32, v24
	v_or_b32_e32 v128, 48, v24
	s_cbranch_vccz .LBB0_2215
	v_lshlrev_b32_e32 v0, 7, v24
	v_and_b32_e32 v144, 0x3e780, v0
	v_lshl_add_u64 v[0:1], s[38:39], 0, v[144:145]
	v_mov_b32_e32 v171, v145
	v_cmp_lt_i32_e32 vcc, v213, v212
	v_lshl_add_u64 v[12:13], v[0:1], 0, v[170:171]
	v_mul_f32_e32 v1, v191, v191
	v_cndmask_b32_e32 v0, v159, v213, vcc
	v_cmp_lt_i32_e32 vcc, v214, v212
	v_lshlrev_b32_e32 v131, 2, v0
	v_fmac_f32_e32 v1, v123, v123
	v_cndmask_b32_e32 v0, v159, v214, vcc
	v_lshlrev_b32_e32 v129, 2, v0
	v_mul_f32_e32 v0, v190, v190
	v_fmac_f32_e32 v0, v122, v122
	v_add_f32_e32 v4, v0, v1
	v_pk_mul_f32 v[0:1], v[192:193], v[192:193]
	v_lshl_add_u64 v[2:3], s[72:73], 2, v[160:161]
	v_pk_fma_f32 v[0:1], v[124:125], v[124:125], v[0:1]
	global_load_dwordx4 v[200:203], v[12:13], off
	global_load_dwordx4 v[234:237], v[12:13], off offset:16
	v_add_f32_e32 v0, v0, v4
	v_pk_mul_f32 v[4:5], v[188:189], v[188:189]
	v_add_f32_e32 v6, v1, v0
	v_pk_fma_f32 v[4:5], v[120:121], v[120:121], v[4:5]
	v_pk_mul_f32 v[0:1], v[194:195], v[194:195]
	v_add_f32_e32 v4, v4, v6
	v_pk_fma_f32 v[0:1], v[126:127], v[126:127], v[0:1]
	v_add_f32_e32 v4, v5, v4
	v_add_f32_e32 v0, v0, v4
	global_load_dwordx4 v[4:7], v[2:3], off
	global_load_dwordx4 v[206:209], v[2:3], off offset:16
	v_add_f32_e32 v0, v1, v0
	ds_bpermute_b32 v1, v131, v0
	v_mul_lo_u32 v133, s68, v25
	v_lshl_add_u64 v[138:139], v[134:135], 1, s[6:7]
	s_mov_b64 s[70:71], 0
	s_waitcnt lgkmcnt(0)
	v_add_f32_e32 v0, v0, v1
	ds_bpermute_b32 v1, v129, v0
	s_waitcnt lgkmcnt(0)
	v_add_f32_e32 v0, v0, v1
	v_mul_f32_e32 v0, v178, v0
	v_mul_f32_e32 v0, v178, v0
	v_fmamk_f32 v0, v0, 0x3c800000, v215
	v_cmp_gt_f32_e32 vcc, s82, v0
	v_mul_f32_e32 v1, 0x4b800000, v0
	s_waitcnt vmcnt(0)
	v_cvt_f32_f16_e32 v15, v201
	v_cndmask_b32_e32 v0, v0, v1, vcc
	v_rsq_f32_e32 v0, v0
	v_cvt_f32_f16_e32 v14, v200
	v_cvt_f32_f16_e32 v205, v235
	v_cvt_f32_f16_e32 v204, v234
	v_mul_f32_e32 v1, 0x45800000, v0
	v_cndmask_b32_e32 v0, v0, v1, vcc
	v_mul_f32_e32 v0, v178, v0
	v_mul_f32_e32 v8, s1, v0
	v_cvt_f32_f16_sdwa v197, v5 dst_sel:DWORD dst_unused:UNUSED_PAD src0_sel:WORD_1
	v_cvt_f32_f16_sdwa v196, v4 dst_sel:DWORD dst_unused:UNUSED_PAD src0_sel:WORD_1
	v_cvt_f32_f16_e32 v199, v5
	v_cvt_f32_f16_e32 v198, v4
	v_cvt_f32_f16_sdwa v5, v201 dst_sel:DWORD dst_unused:UNUSED_PAD src0_sel:WORD_1
	v_cvt_f32_f16_sdwa v4, v200 dst_sel:DWORD dst_unused:UNUSED_PAD src0_sel:WORD_1
	v_pk_mul_f32 v[10:11], v[8:9], v[196:197] op_sel_hi:[0,1]
	v_pk_mul_f32 v[0:1], v[8:9], v[198:199] op_sel_hi:[0,1]
	v_pk_mul_f32 v[10:11], v[190:191], v[10:11]
	v_pk_mul_f32 v[0:1], v[122:123], v[0:1]
	v_pk_mul_f32 v[140:141], v[10:11], v[14:15]
	v_cvt_f32_f16_e32 v143, v7
	v_pk_fma_f32 v[200:201], v[0:1], v[4:5], v[140:141]
	v_cvt_f32_f16_sdwa v141, v7 dst_sel:DWORD dst_unused:UNUSED_PAD src0_sel:WORD_1
	v_cvt_f32_f16_sdwa v140, v6 dst_sel:DWORD dst_unused:UNUSED_PAD src0_sel:WORD_1
	v_pk_mul_f32 v[4:5], v[10:11], v[4:5]
	v_cvt_f32_f16_e32 v142, v6
	v_pk_fma_f32 v[0:1], v[0:1], v[14:15], v[4:5] neg_lo:[0,0,1] neg_hi:[0,0,1]
	v_cvt_f32_f16_e32 v15, v203
	v_cvt_f32_f16_e32 v14, v202
	v_cvt_f32_f16_sdwa v7, v203 dst_sel:DWORD dst_unused:UNUSED_PAD src0_sel:WORD_1
	v_cvt_f32_f16_sdwa v6, v202 dst_sel:DWORD dst_unused:UNUSED_PAD src0_sel:WORD_1
	v_pk_mul_f32 v[10:11], v[8:9], v[140:141] op_sel_hi:[0,1]
	v_pk_mul_f32 v[4:5], v[8:9], v[142:143] op_sel_hi:[0,1]
	v_pk_mul_f32 v[10:11], v[192:193], v[10:11]
	v_pk_mul_f32 v[4:5], v[124:125], v[4:5]
	v_pk_mul_f32 v[202:203], v[10:11], v[14:15]
	v_cvt_pk_bf16_f32 v0, v0, v1
	v_pk_fma_f32 v[202:203], v[4:5], v[6:7], v[202:203]
	v_pk_mul_f32 v[6:7], v[10:11], v[6:7]
	v_cvt_f32_f16_sdwa v11, v235 dst_sel:DWORD dst_unused:UNUSED_PAD src0_sel:WORD_1
	v_pk_fma_f32 v[4:5], v[4:5], v[14:15], v[6:7] neg_lo:[0,0,1] neg_hi:[0,0,1]
	v_cvt_f32_f16_sdwa v10, v234 dst_sel:DWORD dst_unused:UNUSED_PAD src0_sel:WORD_1
	v_cvt_pk_bf16_f32 v1, v4, v5
	v_cvt_pk_bf16_f32 v4, v200, v201
	v_cvt_f32_f16_sdwa v201, v207 dst_sel:DWORD dst_unused:UNUSED_PAD src0_sel:WORD_1
	v_cvt_f32_f16_sdwa v200, v206 dst_sel:DWORD dst_unused:UNUSED_PAD src0_sel:WORD_1
	v_cvt_pk_bf16_f32 v5, v202, v203
	v_cvt_f32_f16_e32 v203, v207
	v_cvt_f32_f16_e32 v202, v206
	v_pk_mul_f32 v[6:7], v[8:9], v[200:201] op_sel_hi:[0,1]
	v_pk_mul_f32 v[14:15], v[188:189], v[6:7]
	v_cvt_f32_f16_e32 v207, v209
	v_pk_mul_f32 v[2:3], v[8:9], v[202:203] op_sel_hi:[0,1]
	v_pk_mul_f32 v[2:3], v[120:121], v[2:3]
	v_pk_mul_f32 v[6:7], v[14:15], v[204:205]
	v_cvt_f32_f16_e32 v206, v208
	v_pk_fma_f32 v[6:7], v[2:3], v[10:11], v[6:7]
	v_pk_mul_f32 v[10:11], v[14:15], v[10:11]
	v_cvt_f32_f16_sdwa v15, v237 dst_sel:DWORD dst_unused:UNUSED_PAD src0_sel:WORD_1
	v_pk_fma_f32 v[2:3], v[2:3], v[204:205], v[10:11] neg_lo:[0,0,1] neg_hi:[0,0,1]
	v_cvt_f32_f16_sdwa v205, v209 dst_sel:DWORD dst_unused:UNUSED_PAD src0_sel:WORD_1
	v_cvt_f32_f16_sdwa v204, v208 dst_sel:DWORD dst_unused:UNUSED_PAD src0_sel:WORD_1
	v_cvt_f32_f16_sdwa v14, v236 dst_sel:DWORD dst_unused:UNUSED_PAD src0_sel:WORD_1
	v_cvt_f32_f16_e32 v209, v237
	v_cvt_f32_f16_e32 v208, v236
	v_pk_mul_f32 v[10:11], v[8:9], v[206:207] op_sel_hi:[0,1]
	v_pk_mul_f32 v[8:9], v[8:9], v[204:205] op_sel_hi:[0,1]
	v_pk_mul_f32 v[8:9], v[194:195], v[8:9]
	v_pk_mul_f32 v[10:11], v[126:127], v[10:11]
	v_pk_mul_f32 v[210:211], v[8:9], v[208:209]
	v_pk_mul_f32 v[8:9], v[8:9], v[14:15]
	v_cvt_pk_bf16_f32 v2, v2, v3
	v_pk_fma_f32 v[8:9], v[10:11], v[208:209], v[8:9] neg_lo:[0,0,1] neg_hi:[0,0,1]
	v_pk_fma_f32 v[210:211], v[10:11], v[14:15], v[210:211]
	v_cvt_pk_bf16_f32 v3, v8, v9
	v_mul_lo_u32 v10, s69, v24
	v_mad_u64_u32 v[8:9], s[48:49], s68, v24, 0
	v_add3_u32 v9, v9, v133, v10
	v_lshl_add_u64 v[14:15], v[8:9], 1, v[138:139]
	v_mov_b64_e32 v[250:251], v[14:15]
	s_mul_i32 s98, s68, 32
	s_mov_b32 s99, 0
	s_mul_i32 s100, s68, 0xa0
	s_mov_b32 s101, 0
	global_load_dwordx4 v[8:11], v[12:13], off offset:2048
	global_load_dwordx4 v[234:237], v[12:13], off offset:2064
	v_cvt_pk_bf16_f32 v6, v6, v7
	v_cvt_pk_bf16_f32 v7, v210, v211
	global_store_dwordx4 v[14:15], v[0:3], off
	global_store_dwordx4 v[14:15], v[4:7], off offset:64
	v_lshl_add_u64 v[208:209], v[12:13], 0, s[12:13]
	v_mul_f32_e32 v0, v182, v182
	v_mul_f32_e32 v1, v183, v183
	v_fmac_f32_e32 v0, v114, v114
	v_fmac_f32_e32 v1, v115, v115
	v_add_f32_e32 v2, v0, v1
	v_pk_mul_f32 v[0:1], v[184:185], v[184:185]
	s_waitcnt vmcnt(3)
	v_cvt_f32_f16_e32 v7, v9
	v_pk_fma_f32 v[0:1], v[116:117], v[116:117], v[0:1]
	v_cvt_f32_f16_e32 v6, v8
	v_add_f32_e32 v0, v0, v2
	v_pk_mul_f32 v[2:3], v[180:181], v[180:181]
	v_add_f32_e32 v4, v1, v0
	v_pk_fma_f32 v[2:3], v[112:113], v[112:113], v[2:3]
	v_pk_mul_f32 v[0:1], v[186:187], v[186:187]
	v_add_f32_e32 v2, v2, v4
	v_pk_fma_f32 v[0:1], v[118:119], v[118:119], v[0:1]
	v_add_f32_e32 v2, v3, v2
	v_add_f32_e32 v0, v0, v2
	v_add_f32_e32 v0, v1, v0
	ds_bpermute_b32 v1, v131, v0
	v_cvt_f32_f16_sdwa v3, v9 dst_sel:DWORD dst_unused:UNUSED_PAD src0_sel:WORD_1
	v_cvt_f32_f16_sdwa v2, v8 dst_sel:DWORD dst_unused:UNUSED_PAD src0_sel:WORD_1
	s_waitcnt lgkmcnt(0)
	v_add_f32_e32 v0, v0, v1
	ds_bpermute_b32 v1, v129, v0
	s_waitcnt lgkmcnt(0)
	v_add_f32_e32 v0, v0, v1
	v_mul_f32_e32 v0, v179, v0
	v_mul_f32_e32 v0, v179, v0
	v_fmamk_f32 v0, v0, 0x3c800000, v215
	v_cmp_gt_f32_e32 vcc, s82, v0
	v_mul_f32_e32 v1, 0x4b800000, v0
	s_nop 0
	v_cndmask_b32_e32 v0, v0, v1, vcc
	v_rsq_f32_e32 v0, v0
	s_nop 0
	v_mul_f32_e32 v1, 0x45800000, v0
	v_cndmask_b32_e32 v0, v0, v1, vcc
	v_mul_f32_e32 v0, v179, v0
	v_mul_f32_e32 v14, s1, v0
	v_pk_mul_f32 v[4:5], v[14:15], v[196:197] op_sel_hi:[0,1]
	v_pk_mul_f32 v[0:1], v[14:15], v[198:199] op_sel_hi:[0,1]
	v_pk_mul_f32 v[4:5], v[182:183], v[4:5]
	v_pk_mul_f32 v[0:1], v[114:115], v[0:1]
	v_pk_mul_f32 v[8:9], v[4:5], v[6:7]
	s_nop 0
	v_pk_fma_f32 v[8:9], v[0:1], v[2:3], v[8:9]
	v_pk_mul_f32 v[2:3], v[4:5], v[2:3]
	v_cvt_f32_f16_sdwa v5, v11 dst_sel:DWORD dst_unused:UNUSED_PAD src0_sel:WORD_1
	v_cvt_f32_f16_sdwa v4, v10 dst_sel:DWORD dst_unused:UNUSED_PAD src0_sel:WORD_1
	v_cvt_f32_f16_e32 v11, v11
	v_cvt_f32_f16_e32 v10, v10
	v_pk_fma_f32 v[0:1], v[0:1], v[6:7], v[2:3] neg_lo:[0,0,1] neg_hi:[0,0,1]
	v_pk_mul_f32 v[6:7], v[14:15], v[140:141] op_sel_hi:[0,1]
	v_pk_mul_f32 v[2:3], v[14:15], v[142:143] op_sel_hi:[0,1]
	v_pk_mul_f32 v[6:7], v[184:185], v[6:7]
	v_pk_mul_f32 v[2:3], v[116:117], v[2:3]
	v_pk_mul_f32 v[210:211], v[6:7], v[10:11]
	v_cvt_pk_bf16_f32 v0, v0, v1
	v_pk_fma_f32 v[210:211], v[2:3], v[4:5], v[210:211]
	v_pk_mul_f32 v[4:5], v[6:7], v[4:5]
	v_pk_mul_f32 v[6:7], v[14:15], v[200:201] op_sel_hi:[0,1]
	v_pk_fma_f32 v[2:3], v[2:3], v[10:11], v[4:5] neg_lo:[0,0,1] neg_hi:[0,0,1]
	v_cvt_pk_bf16_f32 v5, v210, v211
	s_waitcnt vmcnt(2)
	v_cvt_f32_f16_e32 v211, v235
	v_cvt_f32_f16_e32 v210, v234
	v_cvt_pk_bf16_f32 v4, v8, v9
	v_cvt_f32_f16_sdwa v9, v235 dst_sel:DWORD dst_unused:UNUSED_PAD src0_sel:WORD_1
	v_cvt_f32_f16_sdwa v8, v234 dst_sel:DWORD dst_unused:UNUSED_PAD src0_sel:WORD_1
	v_cvt_pk_bf16_f32 v1, v2, v3
	v_pk_mul_f32 v[2:3], v[14:15], v[202:203] op_sel_hi:[0,1]
	v_pk_mul_f32 v[10:11], v[180:181], v[6:7]
	v_pk_mul_f32 v[2:3], v[112:113], v[2:3]
	v_pk_mul_f32 v[6:7], v[10:11], v[210:211]
	s_nop 0
	v_pk_fma_f32 v[6:7], v[2:3], v[8:9], v[6:7]
	v_pk_mul_f32 v[8:9], v[10:11], v[8:9]
	v_cvt_f32_f16_sdwa v11, v237 dst_sel:DWORD dst_unused:UNUSED_PAD src0_sel:WORD_1
	v_pk_fma_f32 v[2:3], v[2:3], v[210:211], v[8:9] neg_lo:[0,0,1] neg_hi:[0,0,1]
	v_cvt_f32_f16_e32 v211, v237
	v_cvt_f32_f16_e32 v210, v236
	v_cvt_f32_f16_sdwa v10, v236 dst_sel:DWORD dst_unused:UNUSED_PAD src0_sel:WORD_1
	v_pk_mul_f32 v[8:9], v[14:15], v[206:207] op_sel_hi:[0,1]
	v_pk_mul_f32 v[14:15], v[14:15], v[204:205] op_sel_hi:[0,1]
	v_pk_mul_f32 v[14:15], v[186:187], v[14:15]
	v_pk_mul_f32 v[8:9], v[118:119], v[8:9]
	v_pk_mul_f32 v[230:231], v[14:15], v[210:211]
	v_cvt_pk_bf16_f32 v2, v2, v3
	v_pk_fma_f32 v[230:231], v[8:9], v[10:11], v[230:231]
	v_pk_mul_f32 v[10:11], v[14:15], v[10:11]
	v_add_co_u32_e32 v14, vcc, s83, v12
	v_pk_fma_f32 v[8:9], v[8:9], v[210:211], v[10:11] neg_lo:[0,0,1] neg_hi:[0,0,1]
	v_cvt_pk_bf16_f32 v3, v8, v9
	v_addc_co_u32_e32 v15, vcc, 0, v13, vcc
	v_lshl_add_u64 v[250:251], v[250:251], 0, s[98:99]
	global_load_dwordx4 v[8:11], v[14:15], off
	global_load_dwordx4 v[234:237], v[208:209], off offset:16
	v_cvt_pk_bf16_f32 v6, v6, v7
	v_cvt_pk_bf16_f32 v7, v230, v231
	global_store_dwordx4 v[250:251], v[0:3], off
	global_store_dwordx4 v[250:251], v[4:7], off offset:64
	v_lshl_add_u64 v[12:13], v[12:13], 0, s[26:27]
	v_mul_f32_e32 v0, v84, v84
	v_mul_f32_e32 v1, v85, v85
	v_fmac_f32_e32 v0, v106, v106
	v_fmac_f32_e32 v1, v107, v107
	v_add_f32_e32 v2, v0, v1
	v_pk_mul_f32 v[0:1], v[86:87], v[86:87]
	s_waitcnt vmcnt(3)
	v_cvt_f32_f16_sdwa v5, v9 dst_sel:DWORD dst_unused:UNUSED_PAD src0_sel:WORD_1
	v_pk_fma_f32 v[0:1], v[108:109], v[108:109], v[0:1]
	v_cvt_f32_f16_e32 v9, v9
	v_add_f32_e32 v0, v0, v2
	v_pk_mul_f32 v[2:3], v[82:83], v[82:83]
	v_add_f32_e32 v4, v1, v0
	v_pk_fma_f32 v[2:3], v[104:105], v[104:105], v[2:3]
	v_pk_mul_f32 v[0:1], v[88:89], v[88:89]
	v_add_f32_e32 v2, v2, v4
	v_pk_fma_f32 v[0:1], v[110:111], v[110:111], v[0:1]
	v_add_f32_e32 v2, v3, v2
	v_add_f32_e32 v0, v0, v2
	v_add_f32_e32 v0, v1, v0
	ds_bpermute_b32 v1, v131, v0
	v_cvt_f32_f16_sdwa v4, v8 dst_sel:DWORD dst_unused:UNUSED_PAD src0_sel:WORD_1
	v_cvt_f32_f16_e32 v8, v8
	s_waitcnt lgkmcnt(0)
	v_add_f32_e32 v0, v0, v1
	ds_bpermute_b32 v1, v129, v0
	s_waitcnt lgkmcnt(0)
	v_add_f32_e32 v0, v0, v1
	v_mul_f32_e32 v0, v176, v0
	v_mul_f32_e32 v0, v176, v0
	v_fmamk_f32 v0, v0, 0x3c800000, v215
	v_cmp_gt_f32_e32 vcc, s82, v0
	v_mul_f32_e32 v1, 0x4b800000, v0
	s_nop 0
	v_cndmask_b32_e32 v0, v0, v1, vcc
	v_rsq_f32_e32 v0, v0
	s_nop 0
	v_mul_f32_e32 v1, 0x45800000, v0
	v_cndmask_b32_e32 v0, v0, v1, vcc
	v_mul_f32_e32 v0, v176, v0
	v_mul_f32_e32 v0, s1, v0
	v_pk_mul_f32 v[6:7], v[0:1], v[196:197] op_sel_hi:[0,1]
	v_pk_mul_f32 v[2:3], v[0:1], v[198:199] op_sel_hi:[0,1]
	v_pk_mul_f32 v[6:7], v[84:85], v[6:7]
	v_pk_mul_f32 v[2:3], v[106:107], v[2:3]
	v_pk_mul_f32 v[208:209], v[6:7], v[8:9]
	s_nop 0
	v_pk_fma_f32 v[208:209], v[2:3], v[4:5], v[208:209]
	v_pk_mul_f32 v[4:5], v[6:7], v[4:5]
	v_cvt_f32_f16_sdwa v7, v11 dst_sel:DWORD dst_unused:UNUSED_PAD src0_sel:WORD_1
	v_cvt_f32_f16_sdwa v6, v10 dst_sel:DWORD dst_unused:UNUSED_PAD src0_sel:WORD_1
	v_cvt_f32_f16_e32 v11, v11
	v_cvt_f32_f16_e32 v10, v10
	v_pk_fma_f32 v[2:3], v[2:3], v[8:9], v[4:5] neg_lo:[0,0,1] neg_hi:[0,0,1]
	v_pk_mul_f32 v[8:9], v[0:1], v[140:141] op_sel_hi:[0,1]
	v_pk_mul_f32 v[4:5], v[0:1], v[142:143] op_sel_hi:[0,1]
	v_pk_mul_f32 v[8:9], v[86:87], v[8:9]
	v_pk_mul_f32 v[4:5], v[108:109], v[4:5]
	v_pk_mul_f32 v[210:211], v[8:9], v[10:11]
	s_nop 0
	v_pk_fma_f32 v[210:211], v[4:5], v[6:7], v[210:211]
	v_pk_mul_f32 v[6:7], v[8:9], v[6:7]
	v_cvt_pk_bf16_f32 v9, v210, v211
	v_pk_fma_f32 v[6:7], v[4:5], v[10:11], v[6:7] neg_lo:[0,0,1] neg_hi:[0,0,1]
	s_waitcnt vmcnt(2)
	v_cvt_f32_f16_e32 v211, v235
	v_cvt_f32_f16_e32 v210, v234
	v_cvt_pk_bf16_f32 v5, v6, v7
	v_cvt_f32_f16_sdwa v7, v235 dst_sel:DWORD dst_unused:UNUSED_PAD src0_sel:WORD_1
	v_cvt_f32_f16_sdwa v6, v234 dst_sel:DWORD dst_unused:UNUSED_PAD src0_sel:WORD_1
	v_pk_mul_f32 v[10:11], v[0:1], v[200:201] op_sel_hi:[0,1]
	v_cvt_pk_bf16_f32 v4, v2, v3
	v_cvt_pk_bf16_f32 v8, v208, v209
	v_pk_mul_f32 v[2:3], v[0:1], v[202:203] op_sel_hi:[0,1]
	v_pk_mul_f32 v[208:209], v[82:83], v[10:11]
	v_pk_mul_f32 v[2:3], v[104:105], v[2:3]
	v_pk_mul_f32 v[10:11], v[208:209], v[210:211]
	s_nop 0
	v_pk_fma_f32 v[10:11], v[2:3], v[6:7], v[10:11]
	v_pk_mul_f32 v[6:7], v[208:209], v[6:7]
	v_cvt_f32_f16_sdwa v209, v237 dst_sel:DWORD dst_unused:UNUSED_PAD src0_sel:WORD_1
	v_pk_fma_f32 v[2:3], v[2:3], v[210:211], v[6:7] neg_lo:[0,0,1] neg_hi:[0,0,1]
	v_cvt_f32_f16_sdwa v208, v236 dst_sel:DWORD dst_unused:UNUSED_PAD src0_sel:WORD_1
	v_cvt_f32_f16_e32 v211, v237
	v_cvt_f32_f16_e32 v210, v236
	v_cvt_pk_bf16_f32 v6, v2, v3
	v_pk_mul_f32 v[2:3], v[0:1], v[206:207] op_sel_hi:[0,1]
	v_pk_mul_f32 v[0:1], v[0:1], v[204:205] op_sel_hi:[0,1]
	v_pk_mul_f32 v[0:1], v[88:89], v[0:1]
	v_pk_mul_f32 v[2:3], v[110:111], v[2:3]
	v_pk_mul_f32 v[230:231], v[0:1], v[210:211]
	v_pk_mul_f32 v[0:1], v[0:1], v[208:209]
	v_pk_fma_f32 v[230:231], v[2:3], v[208:209], v[230:231]
	v_pk_fma_f32 v[0:1], v[2:3], v[210:211], v[0:1] neg_lo:[0,0,1] neg_hi:[0,0,1]
	v_cvt_pk_bf16_f32 v7, v0, v1
	v_lshl_add_u64 v[250:251], v[250:251], 0, s[98:99]
	global_load_dwordx4 v[0:3], v[14:15], off offset:2048
	global_load_dwordx4 v[234:237], v[12:13], off offset:16
	v_cvt_pk_bf16_f32 v10, v10, v11
	v_cvt_pk_bf16_f32 v11, v230, v231
	global_store_dwordx4 v[250:251], v[4:7], off
	global_store_dwordx4 v[250:251], v[8:11], off offset:64
	s_nop 0
	v_lshl_add_u32 v4, v24, 5, v217
	v_and_b32_e32 v4, 0xf9e0, v4
	v_lshlrev_b32_e32 v144, 2, v4
	v_mul_f32_e32 v4, v68, v68
	v_mul_f32_e32 v5, v69, v69
	v_fmac_f32_e32 v4, v98, v98
	v_fmac_f32_e32 v5, v99, v99
	v_add_f32_e32 v6, v4, v5
	v_pk_mul_f32 v[4:5], v[70:71], v[70:71]
	v_lshl_add_u64 v[12:13], v[162:163], 0, v[144:145]
	v_pk_fma_f32 v[4:5], v[100:101], v[100:101], v[4:5]
	s_nop 0
	v_add_f32_e32 v4, v4, v6
	v_pk_mul_f32 v[6:7], v[66:67], v[66:67]
	v_add_f32_e32 v8, v5, v4
	v_pk_fma_f32 v[6:7], v[96:97], v[96:97], v[6:7]
	v_pk_mul_f32 v[4:5], v[72:73], v[72:73]
	v_add_f32_e32 v6, v6, v8
	v_pk_fma_f32 v[4:5], v[102:103], v[102:103], v[4:5]
	v_add_f32_e32 v6, v7, v6
	v_add_f32_e32 v4, v4, v6
	v_add_f32_e32 v4, v5, v4
	ds_bpermute_b32 v5, v131, v4
	s_waitcnt lgkmcnt(0)
	v_add_f32_e32 v4, v4, v5
	ds_bpermute_b32 v5, v129, v4
	s_waitcnt lgkmcnt(0)
	v_add_f32_e32 v4, v4, v5
	v_mul_f32_e32 v4, v177, v4
	v_mul_f32_e32 v4, v177, v4
	v_fmamk_f32 v4, v4, 0x3c800000, v215
	v_cmp_gt_f32_e32 vcc, s82, v4
	v_mul_f32_e32 v5, 0x4b800000, v4
	s_waitcnt vmcnt(3)
	v_cvt_f32_f16_sdwa v7, v1 dst_sel:DWORD dst_unused:UNUSED_PAD src0_sel:WORD_1
	v_cndmask_b32_e32 v4, v4, v5, vcc
	v_rsq_f32_e32 v4, v4
	v_cvt_f32_f16_sdwa v6, v0 dst_sel:DWORD dst_unused:UNUSED_PAD src0_sel:WORD_1
	v_cvt_f32_f16_e32 v1, v1
	v_cvt_f32_f16_e32 v0, v0
	v_mul_f32_e32 v5, 0x45800000, v4
	v_cndmask_b32_e32 v4, v4, v5, vcc
	v_mul_f32_e32 v4, v177, v4
	v_mul_f32_e32 v14, s1, v4
	v_pk_mul_f32 v[8:9], v[14:15], v[196:197] op_sel_hi:[0,1]
	v_pk_mul_f32 v[4:5], v[14:15], v[198:199] op_sel_hi:[0,1]
	v_pk_mul_f32 v[8:9], v[68:69], v[8:9]
	v_pk_mul_f32 v[4:5], v[98:99], v[4:5]
	v_pk_mul_f32 v[10:11], v[8:9], v[0:1]
	s_nop 0
	v_pk_fma_f32 v[10:11], v[4:5], v[6:7], v[10:11]
	v_pk_mul_f32 v[6:7], v[8:9], v[6:7]
	v_pk_mul_f32 v[8:9], v[14:15], v[140:141] op_sel_hi:[0,1]
	v_pk_fma_f32 v[0:1], v[4:5], v[0:1], v[6:7] neg_lo:[0,0,1] neg_hi:[0,0,1]
	v_cvt_f32_f16_sdwa v7, v3 dst_sel:DWORD dst_unused:UNUSED_PAD src0_sel:WORD_1
	v_cvt_f32_f16_sdwa v6, v2 dst_sel:DWORD dst_unused:UNUSED_PAD src0_sel:WORD_1
	v_cvt_f32_f16_e32 v3, v3
	v_cvt_f32_f16_e32 v2, v2
	v_pk_mul_f32 v[4:5], v[14:15], v[142:143] op_sel_hi:[0,1]
	v_pk_mul_f32 v[8:9], v[70:71], v[8:9]
	v_pk_mul_f32 v[4:5], v[100:101], v[4:5]
	v_pk_mul_f32 v[208:209], v[8:9], v[2:3]
	s_nop 0
	v_pk_fma_f32 v[208:209], v[4:5], v[6:7], v[208:209]
	v_pk_mul_f32 v[6:7], v[8:9], v[6:7]
	v_cvt_pk_bf16_f32 v9, v208, v209
	v_pk_fma_f32 v[2:3], v[4:5], v[2:3], v[6:7] neg_lo:[0,0,1] neg_hi:[0,0,1]
	s_waitcnt vmcnt(2)
	v_cvt_f32_f16_e32 v209, v235
	v_cvt_f32_f16_e32 v208, v234
	v_cvt_pk_bf16_f32 v5, v2, v3
	v_cvt_f32_f16_sdwa v3, v235 dst_sel:DWORD dst_unused:UNUSED_PAD src0_sel:WORD_1
	v_cvt_f32_f16_sdwa v2, v234 dst_sel:DWORD dst_unused:UNUSED_PAD src0_sel:WORD_1
	v_pk_mul_f32 v[6:7], v[14:15], v[200:201] op_sel_hi:[0,1]
	v_cvt_pk_bf16_f32 v4, v0, v1
	v_pk_mul_f32 v[0:1], v[14:15], v[202:203] op_sel_hi:[0,1]
	v_pk_mul_f32 v[6:7], v[66:67], v[6:7]
	v_cvt_pk_bf16_f32 v8, v10, v11
	v_pk_mul_f32 v[0:1], v[96:97], v[0:1]
	v_pk_mul_f32 v[10:11], v[6:7], v[208:209]
	s_nop 0
	v_pk_fma_f32 v[10:11], v[0:1], v[2:3], v[10:11]
	v_pk_mul_f32 v[2:3], v[6:7], v[2:3]
	v_cvt_pk_bf16_f32 v10, v10, v11
	v_pk_fma_f32 v[0:1], v[0:1], v[208:209], v[2:3] neg_lo:[0,0,1] neg_hi:[0,0,1]
	v_cvt_f32_f16_e32 v209, v237
	v_cvt_f32_f16_e32 v208, v236
	v_cvt_f32_f16_sdwa v3, v237 dst_sel:DWORD dst_unused:UNUSED_PAD src0_sel:WORD_1
	v_cvt_f32_f16_sdwa v2, v236 dst_sel:DWORD dst_unused:UNUSED_PAD src0_sel:WORD_1
	v_cvt_pk_bf16_f32 v6, v0, v1
	v_pk_mul_f32 v[0:1], v[14:15], v[206:207] op_sel_hi:[0,1]
	v_pk_mul_f32 v[14:15], v[14:15], v[204:205] op_sel_hi:[0,1]
	v_pk_mul_f32 v[14:15], v[72:73], v[14:15]
	v_pk_mul_f32 v[0:1], v[102:103], v[0:1]
	v_pk_mul_f32 v[210:211], v[14:15], v[208:209]
	s_nop 0
	v_pk_fma_f32 v[210:211], v[0:1], v[2:3], v[210:211]
	v_pk_mul_f32 v[2:3], v[14:15], v[2:3]
	v_cvt_pk_bf16_f32 v11, v210, v211
	v_pk_fma_f32 v[0:1], v[0:1], v[208:209], v[2:3] neg_lo:[0,0,1] neg_hi:[0,0,1]
	v_cvt_pk_bf16_f32 v7, v0, v1
	v_lshl_add_u64 v[250:251], v[250:251], 0, s[98:99]
	global_load_dwordx4 v[0:3], v[12:13], off
	s_nop 0
	global_load_dwordx4 v[12:15], v[12:13], off offset:16
	v_add_u32_e32 v133, 0x80, v24
	global_store_dwordx4 v[250:251], v[4:7], off
	global_store_dwordx4 v[250:251], v[8:11], off offset:64
	s_nop 0
	v_lshlrev_b32_e32 v4, 7, v133
	v_and_b32_e32 v144, 0x3e780, v4
	v_lshl_add_u64 v[4:5], s[38:39], 0, v[144:145]
	v_lshl_add_u64 v[208:209], v[4:5], 0, v[170:171]
	v_mul_f32_e32 v4, v92, v92
	v_mul_f32_e32 v5, v93, v93
	v_fmac_f32_e32 v4, v58, v58
	v_fmac_f32_e32 v5, v59, v59
	v_add_f32_e32 v6, v4, v5
	v_pk_mul_f32 v[4:5], v[94:95], v[94:95]
	s_nop 0
	v_pk_fma_f32 v[4:5], v[60:61], v[60:61], v[4:5]
	s_nop 0
	v_add_f32_e32 v4, v4, v6
	v_pk_mul_f32 v[6:7], v[90:91], v[90:91]
	v_add_f32_e32 v8, v5, v4
	v_pk_fma_f32 v[6:7], v[56:57], v[56:57], v[6:7]
	v_pk_mul_f32 v[4:5], v[136:137], v[136:137]
	v_add_f32_e32 v6, v6, v8
	v_pk_fma_f32 v[4:5], v[62:63], v[62:63], v[4:5]
	v_add_f32_e32 v6, v7, v6
	v_add_f32_e32 v4, v4, v6
	v_add_f32_e32 v4, v5, v4
	ds_bpermute_b32 v5, v131, v4
	s_waitcnt lgkmcnt(0)
	v_add_f32_e32 v4, v4, v5
	ds_bpermute_b32 v5, v129, v4
	s_waitcnt lgkmcnt(0)
	v_add_f32_e32 v4, v4, v5
	v_mul_f32_e32 v4, v174, v4
	v_mul_f32_e32 v4, v174, v4
	v_fmamk_f32 v4, v4, 0x3c800000, v215
	v_cmp_gt_f32_e32 vcc, s82, v4
	v_mul_f32_e32 v5, 0x4b800000, v4
	s_waitcnt vmcnt(3)
	v_cvt_f32_f16_sdwa v7, v1 dst_sel:DWORD dst_unused:UNUSED_PAD src0_sel:WORD_1
	v_cndmask_b32_e32 v4, v4, v5, vcc
	v_rsq_f32_e32 v4, v4
	v_cvt_f32_f16_sdwa v6, v0 dst_sel:DWORD dst_unused:UNUSED_PAD src0_sel:WORD_1
	v_cvt_f32_f16_e32 v1, v1
	v_cvt_f32_f16_e32 v0, v0
	v_mul_f32_e32 v5, 0x45800000, v4
	v_cndmask_b32_e32 v4, v4, v5, vcc
	v_mul_f32_e32 v4, v174, v4
	v_mul_f32_e32 v8, s1, v4
	v_pk_mul_f32 v[10:11], v[8:9], v[196:197] op_sel_hi:[0,1]
	v_pk_mul_f32 v[4:5], v[8:9], v[198:199] op_sel_hi:[0,1]
	v_pk_mul_f32 v[10:11], v[92:93], v[10:11]
	v_pk_mul_f32 v[4:5], v[58:59], v[4:5]
	v_pk_mul_f32 v[210:211], v[10:11], v[0:1]
	s_nop 0
	v_pk_fma_f32 v[210:211], v[4:5], v[6:7], v[210:211]
	v_pk_mul_f32 v[6:7], v[10:11], v[6:7]
	v_pk_mul_f32 v[10:11], v[8:9], v[140:141] op_sel_hi:[0,1]
	v_pk_fma_f32 v[0:1], v[4:5], v[0:1], v[6:7] neg_lo:[0,0,1] neg_hi:[0,0,1]
	v_cvt_f32_f16_sdwa v7, v3 dst_sel:DWORD dst_unused:UNUSED_PAD src0_sel:WORD_1
	v_cvt_f32_f16_sdwa v6, v2 dst_sel:DWORD dst_unused:UNUSED_PAD src0_sel:WORD_1
	v_cvt_f32_f16_e32 v3, v3
	v_cvt_f32_f16_e32 v2, v2
	v_pk_mul_f32 v[4:5], v[8:9], v[142:143] op_sel_hi:[0,1]
	v_pk_mul_f32 v[10:11], v[94:95], v[10:11]
	v_pk_mul_f32 v[4:5], v[60:61], v[4:5]
	v_pk_mul_f32 v[230:231], v[10:11], v[2:3]
	v_cvt_pk_bf16_f32 v0, v0, v1
	v_pk_fma_f32 v[230:231], v[4:5], v[6:7], v[230:231]
	v_pk_mul_f32 v[6:7], v[10:11], v[6:7]
	s_waitcnt vmcnt(2)
	v_cvt_f32_f16_sdwa v11, v13 dst_sel:DWORD dst_unused:UNUSED_PAD src0_sel:WORD_1
	v_cvt_f32_f16_sdwa v10, v12 dst_sel:DWORD dst_unused:UNUSED_PAD src0_sel:WORD_1
	v_cvt_f32_f16_e32 v13, v13
	v_cvt_f32_f16_e32 v12, v12
	v_pk_fma_f32 v[2:3], v[4:5], v[2:3], v[6:7] neg_lo:[0,0,1] neg_hi:[0,0,1]
	v_pk_mul_f32 v[6:7], v[8:9], v[200:201] op_sel_hi:[0,1]
	v_cvt_pk_bf16_f32 v1, v2, v3
	v_cvt_pk_bf16_f32 v4, v210, v211
	v_pk_mul_f32 v[2:3], v[8:9], v[202:203] op_sel_hi:[0,1]
	v_pk_mul_f32 v[210:211], v[90:91], v[6:7]
	v_pk_mul_f32 v[2:3], v[56:57], v[2:3]
	v_pk_mul_f32 v[6:7], v[210:211], v[12:13]
	v_cvt_pk_bf16_f32 v5, v230, v231
	v_pk_fma_f32 v[6:7], v[2:3], v[10:11], v[6:7]
	v_pk_mul_f32 v[10:11], v[210:211], v[10:11]
	v_cvt_pk_bf16_f32 v6, v6, v7
	v_pk_fma_f32 v[2:3], v[2:3], v[12:13], v[10:11] neg_lo:[0,0,1] neg_hi:[0,0,1]
	v_cvt_f32_f16_sdwa v13, v15 dst_sel:DWORD dst_unused:UNUSED_PAD src0_sel:WORD_1
	v_cvt_f32_f16_sdwa v12, v14 dst_sel:DWORD dst_unused:UNUSED_PAD src0_sel:WORD_1
	v_cvt_f32_f16_e32 v15, v15
	v_cvt_f32_f16_e32 v14, v14
	v_pk_mul_f32 v[10:11], v[8:9], v[206:207] op_sel_hi:[0,1]
	v_pk_mul_f32 v[8:9], v[8:9], v[204:205] op_sel_hi:[0,1]
	v_pk_mul_f32 v[8:9], v[136:137], v[8:9]
	v_pk_mul_f32 v[10:11], v[62:63], v[10:11]
	v_pk_mul_f32 v[210:211], v[8:9], v[14:15]
	v_pk_mul_f32 v[8:9], v[8:9], v[12:13]
	v_cvt_pk_bf16_f32 v2, v2, v3
	v_pk_fma_f32 v[8:9], v[10:11], v[14:15], v[8:9] neg_lo:[0,0,1] neg_hi:[0,0,1]
	v_pk_fma_f32 v[210:211], v[10:11], v[12:13], v[210:211]
	v_cvt_pk_bf16_f32 v3, v8, v9
	v_lshl_add_u64 v[250:251], v[250:251], 0, s[100:101]
	global_load_dwordx4 v[8:11], v[208:209], off offset:2048
	global_load_dwordx4 v[234:237], v[208:209], off offset:2064
	v_cvt_pk_bf16_f32 v7, v210, v211
	global_store_dwordx4 v[250:251], v[0:3], off
	global_store_dwordx4 v[250:251], v[4:7], off offset:64
	v_add_u32_e32 v133, 0x90, v24
	v_mul_f32_e32 v0, v76, v76
	v_mul_f32_e32 v1, v77, v77
	v_fmac_f32_e32 v0, v50, v50
	v_fmac_f32_e32 v1, v51, v51
	v_add_f32_e32 v2, v0, v1
	v_pk_mul_f32 v[0:1], v[78:79], v[78:79]
	v_lshl_add_u64 v[14:15], v[208:209], 0, s[12:13]
	v_pk_fma_f32 v[0:1], v[52:53], v[52:53], v[0:1]
	s_waitcnt vmcnt(3)
	v_cvt_f32_f16_e32 v7, v9
	v_add_f32_e32 v0, v0, v2
	v_pk_mul_f32 v[2:3], v[74:75], v[74:75]
	v_add_f32_e32 v4, v1, v0
	v_pk_fma_f32 v[2:3], v[48:49], v[48:49], v[2:3]
	v_pk_mul_f32 v[0:1], v[80:81], v[80:81]
	v_add_f32_e32 v2, v2, v4
	v_pk_fma_f32 v[0:1], v[54:55], v[54:55], v[0:1]
	v_add_f32_e32 v2, v3, v2
	v_add_f32_e32 v0, v0, v2
	v_add_f32_e32 v0, v1, v0
	ds_bpermute_b32 v1, v131, v0
	v_cvt_f32_f16_e32 v6, v8
	v_cvt_f32_f16_sdwa v3, v9 dst_sel:DWORD dst_unused:UNUSED_PAD src0_sel:WORD_1
	v_cvt_f32_f16_sdwa v2, v8 dst_sel:DWORD dst_unused:UNUSED_PAD src0_sel:WORD_1
	s_waitcnt lgkmcnt(0)
	v_add_f32_e32 v0, v0, v1
	ds_bpermute_b32 v1, v129, v0
	s_waitcnt lgkmcnt(0)
	v_add_f32_e32 v0, v0, v1
	v_mul_f32_e32 v0, v175, v0
	v_mul_f32_e32 v0, v175, v0
	v_fmamk_f32 v0, v0, 0x3c800000, v215
	v_cmp_gt_f32_e32 vcc, s82, v0
	v_mul_f32_e32 v1, 0x4b800000, v0
	s_nop 0
	v_cndmask_b32_e32 v0, v0, v1, vcc
	v_rsq_f32_e32 v0, v0
	s_nop 0
	v_mul_f32_e32 v1, 0x45800000, v0
	v_cndmask_b32_e32 v0, v0, v1, vcc
	v_mul_f32_e32 v0, v175, v0
	v_mul_f32_e32 v12, s1, v0
	v_pk_mul_f32 v[4:5], v[12:13], v[196:197] op_sel_hi:[0,1]
	v_pk_mul_f32 v[0:1], v[12:13], v[198:199] op_sel_hi:[0,1]
	v_pk_mul_f32 v[4:5], v[76:77], v[4:5]
	v_pk_mul_f32 v[0:1], v[50:51], v[0:1]
	v_pk_mul_f32 v[8:9], v[4:5], v[6:7]
	s_nop 0
	v_pk_fma_f32 v[8:9], v[0:1], v[2:3], v[8:9]
	v_pk_mul_f32 v[2:3], v[4:5], v[2:3]
	v_cvt_f32_f16_sdwa v5, v11 dst_sel:DWORD dst_unused:UNUSED_PAD src0_sel:WORD_1
	v_cvt_f32_f16_sdwa v4, v10 dst_sel:DWORD dst_unused:UNUSED_PAD src0_sel:WORD_1
	v_cvt_f32_f16_e32 v11, v11
	v_cvt_f32_f16_e32 v10, v10
	v_pk_fma_f32 v[0:1], v[0:1], v[6:7], v[2:3] neg_lo:[0,0,1] neg_hi:[0,0,1]
	v_pk_mul_f32 v[6:7], v[12:13], v[140:141] op_sel_hi:[0,1]
	v_pk_mul_f32 v[2:3], v[12:13], v[142:143] op_sel_hi:[0,1]
	v_pk_mul_f32 v[6:7], v[78:79], v[6:7]
	v_pk_mul_f32 v[2:3], v[52:53], v[2:3]
	v_pk_mul_f32 v[210:211], v[6:7], v[10:11]
	v_cvt_pk_bf16_f32 v0, v0, v1
	v_pk_fma_f32 v[210:211], v[2:3], v[4:5], v[210:211]
	v_pk_mul_f32 v[4:5], v[6:7], v[4:5]
	v_pk_mul_f32 v[6:7], v[12:13], v[200:201] op_sel_hi:[0,1]
	v_pk_fma_f32 v[2:3], v[2:3], v[10:11], v[4:5] neg_lo:[0,0,1] neg_hi:[0,0,1]
	v_cvt_pk_bf16_f32 v5, v210, v211
	s_waitcnt vmcnt(2)
	v_cvt_f32_f16_e32 v211, v235
	v_cvt_f32_f16_e32 v210, v234
	v_cvt_pk_bf16_f32 v4, v8, v9
	v_cvt_f32_f16_sdwa v9, v235 dst_sel:DWORD dst_unused:UNUSED_PAD src0_sel:WORD_1
	v_cvt_f32_f16_sdwa v8, v234 dst_sel:DWORD dst_unused:UNUSED_PAD src0_sel:WORD_1
	v_cvt_pk_bf16_f32 v1, v2, v3
	v_pk_mul_f32 v[2:3], v[12:13], v[202:203] op_sel_hi:[0,1]
	v_pk_mul_f32 v[10:11], v[74:75], v[6:7]
	v_pk_mul_f32 v[2:3], v[48:49], v[2:3]
	v_pk_mul_f32 v[6:7], v[10:11], v[210:211]
	s_nop 0
	v_pk_fma_f32 v[6:7], v[2:3], v[8:9], v[6:7]
	v_pk_mul_f32 v[8:9], v[10:11], v[8:9]
	v_cvt_f32_f16_sdwa v11, v237 dst_sel:DWORD dst_unused:UNUSED_PAD src0_sel:WORD_1
	v_pk_fma_f32 v[2:3], v[2:3], v[210:211], v[8:9] neg_lo:[0,0,1] neg_hi:[0,0,1]
	v_cvt_f32_f16_e32 v211, v237
	v_cvt_f32_f16_e32 v210, v236
	v_cvt_f32_f16_sdwa v10, v236 dst_sel:DWORD dst_unused:UNUSED_PAD src0_sel:WORD_1
	v_pk_mul_f32 v[8:9], v[12:13], v[206:207] op_sel_hi:[0,1]
	v_pk_mul_f32 v[12:13], v[12:13], v[204:205] op_sel_hi:[0,1]
	v_pk_mul_f32 v[12:13], v[80:81], v[12:13]
	v_pk_mul_f32 v[8:9], v[54:55], v[8:9]
	v_pk_mul_f32 v[230:231], v[12:13], v[210:211]
	v_cvt_pk_bf16_f32 v2, v2, v3
	v_pk_fma_f32 v[230:231], v[8:9], v[10:11], v[230:231]
	v_pk_mul_f32 v[10:11], v[12:13], v[10:11]
	v_add_co_u32_e32 v12, vcc, s83, v208
	v_pk_fma_f32 v[8:9], v[8:9], v[210:211], v[10:11] neg_lo:[0,0,1] neg_hi:[0,0,1]
	v_cvt_pk_bf16_f32 v3, v8, v9
	v_addc_co_u32_e32 v13, vcc, 0, v209, vcc
	v_lshl_add_u64 v[250:251], v[250:251], 0, s[98:99]
	global_load_dwordx4 v[8:11], v[12:13], off
	global_load_dwordx4 v[234:237], v[14:15], off offset:16
	v_cvt_pk_bf16_f32 v6, v6, v7
	v_cvt_pk_bf16_f32 v7, v230, v231
	global_store_dwordx4 v[250:251], v[0:3], off
	global_store_dwordx4 v[250:251], v[4:7], off offset:64
	v_lshl_add_u64 v[14:15], v[208:209], 0, s[26:27]
	v_mul_f32_e32 v0, v28, v28
	v_mul_f32_e32 v1, v29, v29
	v_fmac_f32_e32 v0, v42, v42
	v_fmac_f32_e32 v1, v43, v43
	v_add_f32_e32 v2, v0, v1
	v_pk_mul_f32 v[0:1], v[30:31], v[30:31]
	v_add_u32_e32 v133, 0xa0, v24
	v_pk_fma_f32 v[0:1], v[44:45], v[44:45], v[0:1]
	s_waitcnt vmcnt(3)
	v_cvt_f32_f16_e32 v7, v9
	v_add_f32_e32 v0, v0, v2
	v_pk_mul_f32 v[2:3], v[26:27], v[26:27]
	v_add_f32_e32 v4, v1, v0
	v_pk_fma_f32 v[2:3], v[40:41], v[40:41], v[2:3]
	v_pk_mul_f32 v[0:1], v[64:65], v[64:65]
	v_add_f32_e32 v2, v2, v4
	v_pk_fma_f32 v[0:1], v[46:47], v[46:47], v[0:1]
	v_add_f32_e32 v2, v3, v2
	v_add_f32_e32 v0, v0, v2
	v_add_f32_e32 v0, v1, v0
	ds_bpermute_b32 v1, v131, v0
	v_cvt_f32_f16_e32 v6, v8
	v_cvt_f32_f16_sdwa v3, v9 dst_sel:DWORD dst_unused:UNUSED_PAD src0_sel:WORD_1
	v_cvt_f32_f16_sdwa v2, v8 dst_sel:DWORD dst_unused:UNUSED_PAD src0_sel:WORD_1
	s_waitcnt vmcnt(2)
	v_cvt_f32_f16_e32 v211, v237
	s_waitcnt lgkmcnt(0)
	v_add_f32_e32 v0, v0, v1
	ds_bpermute_b32 v1, v129, v0
	v_cvt_f32_f16_e32 v210, v236
	s_waitcnt lgkmcnt(0)
	v_add_f32_e32 v0, v0, v1
	v_mul_f32_e32 v0, v172, v0
	v_mul_f32_e32 v0, v172, v0
	v_fmamk_f32 v0, v0, 0x3c800000, v215
	v_cmp_gt_f32_e32 vcc, s82, v0
	v_mul_f32_e32 v1, 0x4b800000, v0
	s_nop 0
	v_cndmask_b32_e32 v0, v0, v1, vcc
	v_rsq_f32_e32 v0, v0
	s_nop 0
	v_mul_f32_e32 v1, 0x45800000, v0
	v_cndmask_b32_e32 v0, v0, v1, vcc
	v_mul_f32_e32 v0, v172, v0
	v_mul_f32_e32 v144, s1, v0
	v_pk_mul_f32 v[4:5], v[144:145], v[196:197] op_sel_hi:[0,1]
	v_pk_mul_f32 v[0:1], v[144:145], v[198:199] op_sel_hi:[0,1]
	v_pk_mul_f32 v[4:5], v[28:29], v[4:5]
	v_pk_mul_f32 v[0:1], v[42:43], v[0:1]
	v_pk_mul_f32 v[8:9], v[4:5], v[6:7]
	s_nop 0
	v_pk_fma_f32 v[8:9], v[0:1], v[2:3], v[8:9]
	v_pk_mul_f32 v[2:3], v[4:5], v[2:3]
	v_cvt_f32_f16_sdwa v5, v11 dst_sel:DWORD dst_unused:UNUSED_PAD src0_sel:WORD_1
	v_cvt_f32_f16_sdwa v4, v10 dst_sel:DWORD dst_unused:UNUSED_PAD src0_sel:WORD_1
	v_cvt_f32_f16_e32 v11, v11
	v_cvt_f32_f16_e32 v10, v10
	v_pk_fma_f32 v[0:1], v[0:1], v[6:7], v[2:3] neg_lo:[0,0,1] neg_hi:[0,0,1]
	v_pk_mul_f32 v[6:7], v[144:145], v[140:141] op_sel_hi:[0,1]
	v_pk_mul_f32 v[2:3], v[144:145], v[142:143] op_sel_hi:[0,1]
	v_pk_mul_f32 v[6:7], v[30:31], v[6:7]
	v_pk_mul_f32 v[2:3], v[44:45], v[2:3]
	v_pk_mul_f32 v[208:209], v[6:7], v[10:11]
	v_cvt_pk_bf16_f32 v0, v0, v1
	v_pk_fma_f32 v[208:209], v[2:3], v[4:5], v[208:209]
	v_pk_mul_f32 v[4:5], v[6:7], v[4:5]
	v_pk_mul_f32 v[6:7], v[144:145], v[200:201] op_sel_hi:[0,1]
	v_pk_fma_f32 v[2:3], v[2:3], v[10:11], v[4:5] neg_lo:[0,0,1] neg_hi:[0,0,1]
	v_cvt_pk_bf16_f32 v5, v208, v209
	v_cvt_f32_f16_e32 v209, v235
	v_cvt_f32_f16_e32 v208, v234
	v_cvt_pk_bf16_f32 v4, v8, v9
	v_cvt_f32_f16_sdwa v9, v235 dst_sel:DWORD dst_unused:UNUSED_PAD src0_sel:WORD_1
	v_cvt_f32_f16_sdwa v8, v234 dst_sel:DWORD dst_unused:UNUSED_PAD src0_sel:WORD_1
	v_cvt_pk_bf16_f32 v1, v2, v3
	v_pk_mul_f32 v[2:3], v[144:145], v[202:203] op_sel_hi:[0,1]
	v_pk_mul_f32 v[10:11], v[26:27], v[6:7]
	v_pk_mul_f32 v[2:3], v[40:41], v[2:3]
	v_pk_mul_f32 v[6:7], v[10:11], v[208:209]
	s_nop 0
	v_pk_fma_f32 v[6:7], v[2:3], v[8:9], v[6:7]
	v_pk_mul_f32 v[8:9], v[10:11], v[8:9]
	v_cvt_f32_f16_sdwa v11, v237 dst_sel:DWORD dst_unused:UNUSED_PAD src0_sel:WORD_1
	v_cvt_f32_f16_sdwa v10, v236 dst_sel:DWORD dst_unused:UNUSED_PAD src0_sel:WORD_1
	v_pk_fma_f32 v[2:3], v[2:3], v[208:209], v[8:9] neg_lo:[0,0,1] neg_hi:[0,0,1]
	v_pk_mul_f32 v[208:209], v[144:145], v[204:205] op_sel_hi:[0,1]
	v_pk_mul_f32 v[8:9], v[144:145], v[206:207] op_sel_hi:[0,1]
	v_pk_mul_f32 v[208:209], v[64:65], v[208:209]
	v_pk_mul_f32 v[8:9], v[46:47], v[8:9]
	v_pk_mul_f32 v[230:231], v[208:209], v[210:211]
	v_cvt_pk_bf16_f32 v2, v2, v3
	v_pk_fma_f32 v[230:231], v[8:9], v[10:11], v[230:231]
	v_pk_mul_f32 v[10:11], v[208:209], v[10:11]
	v_cvt_pk_bf16_f32 v6, v6, v7
	v_pk_fma_f32 v[8:9], v[8:9], v[210:211], v[10:11] neg_lo:[0,0,1] neg_hi:[0,0,1]
	v_cvt_pk_bf16_f32 v3, v8, v9
	v_lshl_add_u64 v[250:251], v[250:251], 0, s[98:99]
	global_load_dwordx4 v[8:11], v[12:13], off offset:2048
	s_nop 0
	global_load_dwordx4 v[12:15], v[14:15], off offset:16
	v_cvt_pk_bf16_f32 v7, v230, v231
	global_store_dwordx4 v[250:251], v[0:3], off
	global_store_dwordx4 v[250:251], v[4:7], off offset:64
	v_add_u32_e32 v133, 0xb0, v24
	v_mul_f32_e32 v0, v18, v18
	v_mul_f32_e32 v1, v19, v19
	v_fmac_f32_e32 v0, v34, v34
	v_fmac_f32_e32 v1, v35, v35
	v_add_f32_e32 v2, v0, v1
	v_pk_mul_f32 v[0:1], v[20:21], v[20:21]
	s_waitcnt vmcnt(3)
	v_cvt_f32_f16_e32 v7, v9
	v_pk_fma_f32 v[0:1], v[36:37], v[36:37], v[0:1]
	v_cvt_f32_f16_e32 v6, v8
	v_add_f32_e32 v0, v0, v2
	v_pk_mul_f32 v[2:3], v[16:17], v[16:17]
	v_add_f32_e32 v4, v1, v0
	v_pk_fma_f32 v[2:3], v[32:33], v[32:33], v[2:3]
	v_pk_mul_f32 v[0:1], v[22:23], v[22:23]
	v_add_f32_e32 v2, v2, v4
	v_pk_fma_f32 v[0:1], v[38:39], v[38:39], v[0:1]
	v_add_f32_e32 v2, v3, v2
	v_add_f32_e32 v0, v0, v2
	v_add_f32_e32 v0, v1, v0
	ds_bpermute_b32 v1, v131, v0
	v_cvt_f32_f16_sdwa v3, v9 dst_sel:DWORD dst_unused:UNUSED_PAD src0_sel:WORD_1
	v_cvt_f32_f16_sdwa v2, v8 dst_sel:DWORD dst_unused:UNUSED_PAD src0_sel:WORD_1
	s_waitcnt lgkmcnt(0)
	v_add_f32_e32 v0, v0, v1
	ds_bpermute_b32 v1, v129, v0
	s_waitcnt lgkmcnt(0)
	v_add_f32_e32 v0, v0, v1
	v_mul_f32_e32 v0, v173, v0
	v_mul_f32_e32 v0, v173, v0
	v_fmamk_f32 v0, v0, 0x3c800000, v215
	v_cmp_gt_f32_e32 vcc, s82, v0
	v_mul_f32_e32 v1, 0x4b800000, v0
	s_nop 0
	v_cndmask_b32_e32 v0, v0, v1, vcc
	v_rsq_f32_e32 v0, v0
	s_nop 0
	v_mul_f32_e32 v1, 0x45800000, v0
	v_cndmask_b32_e32 v0, v0, v1, vcc
	v_mul_f32_e32 v0, v173, v0
	v_mul_f32_e32 v144, s1, v0
	v_pk_mul_f32 v[4:5], v[144:145], v[196:197] op_sel_hi:[0,1]
	v_pk_mul_f32 v[0:1], v[144:145], v[198:199] op_sel_hi:[0,1]
	v_pk_mul_f32 v[4:5], v[18:19], v[4:5]
	v_pk_mul_f32 v[0:1], v[34:35], v[0:1]
	v_pk_mul_f32 v[8:9], v[4:5], v[6:7]
	s_nop 0
	v_pk_fma_f32 v[8:9], v[0:1], v[2:3], v[8:9]
	v_pk_mul_f32 v[2:3], v[4:5], v[2:3]
	v_cvt_f32_f16_sdwa v5, v11 dst_sel:DWORD dst_unused:UNUSED_PAD src0_sel:WORD_1
	v_cvt_f32_f16_sdwa v4, v10 dst_sel:DWORD dst_unused:UNUSED_PAD src0_sel:WORD_1
	v_cvt_f32_f16_e32 v11, v11
	v_cvt_f32_f16_e32 v10, v10
	v_pk_fma_f32 v[0:1], v[0:1], v[6:7], v[2:3] neg_lo:[0,0,1] neg_hi:[0,0,1]
	v_pk_mul_f32 v[6:7], v[144:145], v[140:141] op_sel_hi:[0,1]
	v_pk_mul_f32 v[2:3], v[144:145], v[142:143] op_sel_hi:[0,1]
	v_pk_mul_f32 v[6:7], v[20:21], v[6:7]
	v_pk_mul_f32 v[2:3], v[36:37], v[2:3]
	v_pk_mul_f32 v[140:141], v[6:7], v[10:11]
	v_cvt_pk_bf16_f32 v0, v0, v1
	v_pk_fma_f32 v[140:141], v[2:3], v[4:5], v[140:141]
	v_pk_mul_f32 v[4:5], v[6:7], v[4:5]
	v_pk_mul_f32 v[6:7], v[144:145], v[200:201] op_sel_hi:[0,1]
	v_pk_fma_f32 v[2:3], v[2:3], v[10:11], v[4:5] neg_lo:[0,0,1] neg_hi:[0,0,1]
	v_cvt_pk_bf16_f32 v4, v8, v9
	s_waitcnt vmcnt(2)
	v_cvt_f32_f16_sdwa v9, v13 dst_sel:DWORD dst_unused:UNUSED_PAD src0_sel:WORD_1
	v_cvt_f32_f16_sdwa v8, v12 dst_sel:DWORD dst_unused:UNUSED_PAD src0_sel:WORD_1
	v_cvt_f32_f16_e32 v13, v13
	v_cvt_f32_f16_e32 v12, v12
	v_cvt_pk_bf16_f32 v1, v2, v3
	v_pk_mul_f32 v[2:3], v[144:145], v[202:203] op_sel_hi:[0,1]
	v_pk_mul_f32 v[10:11], v[16:17], v[6:7]
	v_pk_mul_f32 v[2:3], v[32:33], v[2:3]
	v_pk_mul_f32 v[6:7], v[10:11], v[12:13]
	v_cvt_pk_bf16_f32 v5, v140, v141
	v_pk_fma_f32 v[6:7], v[2:3], v[8:9], v[6:7]
	v_pk_mul_f32 v[8:9], v[10:11], v[8:9]
	v_cvt_f32_f16_sdwa v11, v15 dst_sel:DWORD dst_unused:UNUSED_PAD src0_sel:WORD_1
	v_cvt_f32_f16_sdwa v10, v14 dst_sel:DWORD dst_unused:UNUSED_PAD src0_sel:WORD_1
	v_cvt_f32_f16_e32 v15, v15
	v_cvt_f32_f16_e32 v14, v14
	v_pk_fma_f32 v[2:3], v[2:3], v[12:13], v[8:9] neg_lo:[0,0,1] neg_hi:[0,0,1]
	v_pk_mul_f32 v[12:13], v[144:145], v[204:205] op_sel_hi:[0,1]
	v_pk_mul_f32 v[8:9], v[144:145], v[206:207] op_sel_hi:[0,1]
	v_pk_mul_f32 v[12:13], v[22:23], v[12:13]
	v_pk_mul_f32 v[8:9], v[38:39], v[8:9]
	v_pk_mul_f32 v[140:141], v[12:13], v[14:15]
	v_cvt_pk_bf16_f32 v2, v2, v3
	v_pk_fma_f32 v[140:141], v[8:9], v[10:11], v[140:141]
	v_pk_mul_f32 v[10:11], v[12:13], v[10:11]
	v_cvt_pk_bf16_f32 v6, v6, v7
	v_pk_fma_f32 v[8:9], v[8:9], v[14:15], v[10:11] neg_lo:[0,0,1] neg_hi:[0,0,1]
	v_cvt_pk_bf16_f32 v3, v8, v9
	v_lshl_add_u64 v[250:251], v[250:251], 0, s[98:99]
	v_cvt_pk_bf16_f32 v7, v140, v141
	global_store_dwordx4 v[250:251], v[0:3], off
	global_store_dwordx4 v[250:251], v[4:7], off offset:64

.LBB0_3554:
	s_andn2_b64 vcc, exec, s[30:31]
	s_cbranch_vccnz .LBB0_3561
	s_and_b32 s4, s10, 1
	s_lshl_b32 s5, s4, 12
	v_add_u32_e32 v1, s5, v230
	v_lshl_add_u32 v2, s4, 10, v229
	s_waitcnt lgkmcnt(0)
	ds_read2st64_b32 v[182:183], v1 offset0:4 offset1:5
	ds_read2st64_b32 v[180:181], v1 offset0:6 offset1:7
	ds_read_b128 v[128:131], v2
	ds_read_b128 v[112:115], v2 offset:16
	ds_read_b128 v[124:127], v2 offset:512
	ds_read_b128 v[108:111], v2 offset:528
	s_and_b64 vcc, exec, s[52:53]
	v_lshlrev_b32_e32 v2, 1, v206
	s_mov_b32 s98, 0x3fb8aa3b
	s_mov_b32 s99, 0x3fb8aa3b
	s_mov_b32 s100, 0x3f317218
	s_mov_b32 s101, 0x3f317218
	s_waitcnt lgkmcnt(0)
	v_pk_mul_f32 v[128:129], v[128:129], s[98:99]
	v_pk_mul_f32 v[130:131], v[130:131], s[98:99]
	v_pk_mul_f32 v[112:113], v[112:113], s[98:99]
	v_pk_mul_f32 v[114:115], v[114:115], s[98:99]
	v_pk_mul_f32 v[124:125], v[124:125], s[100:101]
	v_pk_mul_f32 v[126:127], v[126:127], s[100:101]
	v_pk_mul_f32 v[108:109], v[108:109], s[100:101]
	v_pk_mul_f32 v[110:111], v[110:111], s[100:101]
	s_mov_b32 s98, 0x16000
	s_mov_b32 s99, 0
	s_cbranch_vccz .LBB0_3557
	ds_read2st64_b32 v[184:185], v1 offset1:1
	v_cvt_f32_i32_e32 v187, v177
	v_cvt_f32_i32_e32 v186, v176
	ds_read2st64_b32 v[176:177], v1 offset0:2 offset1:3
	v_cvt_f32_i32_e32 v179, v179
	s_waitcnt lgkmcnt(0)
	v_pk_mul_f32 v[188:189], v[128:129], v[184:185] op_sel_hi:[1,0]
	v_cvt_f32_i32_e32 v178, v178
	v_pk_mul_f32 v[186:187], v[188:189], v[186:187]
	v_pk_mul_f32 v[192:193], v[130:131], v[184:185] op_sel_hi:[1,0]
	v_exp_f32_e64 v1, -v186
	v_exp_f32_e64 v3, -v187
	v_pk_mul_f32 v[178:179], v[192:193], v[178:179]
	v_add_f32_e32 v1, 1.0, v1
	v_rcp_f32_e32 v188, v1
	v_add_f32_e32 v1, 1.0, v3
	v_rcp_f32_e32 v189, v1
	v_cvt_f32_i32_e32 v173, v173
	v_cvt_f32_i32_e32 v172, v172
	v_exp_f32_e64 v1, -v178
	v_pk_mul_f32 v[190:191], v[124:125], v[184:185] op_sel_hi:[1,0]
	v_pk_mul_f32 v[186:187], v[186:187], v[188:189]
	v_pk_mul_f32 v[172:173], v[190:191], v[172:173]
	v_add_f32_e32 v1, 1.0, v1
	v_pk_mul_f32 v[172:173], v[172:173], v[186:187]
	v_rcp_f32_e32 v186, v1
	v_exp_f32_e64 v1, -v179
	v_cvt_f32_i32_e32 v169, v169
	v_cvt_f32_i32_e32 v168, v168
	v_pk_mul_f32 v[190:191], v[112:113], v[184:185] op_sel_hi:[1,0]
	v_add_f32_e32 v1, 1.0, v1
	v_rcp_f32_e32 v187, v1
	v_pk_mul_f32 v[168:169], v[190:191], v[168:169]
	v_cvt_f32_i32_e32 v175, v175
	v_cvt_f32_i32_e32 v174, v174
	v_exp_f32_e64 v1, -v168
	v_pk_mul_f32 v[188:189], v[126:127], v[184:185] op_sel_hi:[1,0]
	v_pk_mul_f32 v[178:179], v[178:179], v[186:187]
	v_pk_mul_f32 v[174:175], v[188:189], v[174:175]
	v_add_f32_e32 v1, 1.0, v1
	v_pk_mul_f32 v[174:175], v[174:175], v[178:179]
	v_rcp_f32_e32 v178, v1
	v_exp_f32_e64 v1, -v169
	v_cvt_f32_i32_e32 v171, v171
	v_cvt_f32_i32_e32 v170, v170
	v_pk_mul_f32 v[186:187], v[114:115], v[184:185] op_sel_hi:[1,0]
	v_add_f32_e32 v1, 1.0, v1
	v_rcp_f32_e32 v179, v1
	v_pk_mul_f32 v[170:171], v[186:187], v[170:171]
	v_cvt_f32_i32_e32 v165, v165
	v_exp_f32_e64 v1, -v170
	v_exp_f32_e64 v3, -v171
	v_cvt_f32_i32_e32 v164, v164
	v_add_f32_e32 v1, 1.0, v1
	v_pk_mul_f32 v[168:169], v[168:169], v[178:179]
	v_rcp_f32_e32 v178, v1
	v_add_f32_e32 v1, 1.0, v3
	v_cvt_f32_i32_e32 v167, v167
	v_cvt_f32_i32_e32 v166, v166
	v_rcp_f32_e32 v179, v1
	v_pk_mul_f32 v[186:187], v[108:109], v[184:185] op_sel_hi:[1,0]
	v_cvt_f32_i32_e32 v161, v161
	v_pk_mul_f32 v[164:165], v[186:187], v[164:165]
	v_cvt_f32_i32_e32 v160, v160
	v_pk_mul_f32 v[164:165], v[164:165], v[168:169]
	v_pk_mul_f32 v[168:169], v[110:111], v[184:185] op_sel_hi:[1,0]
	s_lshl_b32 s37, s50, 8
	v_pk_mul_f32 v[166:167], v[168:169], v[166:167]
	v_pk_mul_f32 v[168:169], v[170:171], v[178:179]
	v_add_u32_e32 v1, s37, v221
	v_pk_mul_f32 v[170:171], v[166:167], v[168:169]
	v_cvt_pk_bf16_f32 v166, v172, v173
	v_mov_b32_e32 v172, v185
	v_cvt_pk_bf16_f32 v167, v174, v175
	v_cvt_pk_bf16_f32 v168, v164, v165
	v_mov_b64_e32 v[164:165], s[28:29]
	v_pk_mul_f32 v[174:175], v[128:129], v[172:173] op_sel_hi:[1,0]
	v_cvt_pk_bf16_f32 v169, v170, v171
	v_mad_i64_i32 v[170:171], s[4:5], v1, s66, v[164:165]
	v_pk_mul_f32 v[160:161], v[174:175], v[160:161]
	s_lshl_b32 s4, s48, 7
	s_ashr_i32 s5, s4, 31
	v_exp_f32_e64 v1, -v160
	s_lshl_b64 s[6:7], s[4:5], 1
	v_lshl_add_u64 v[170:171], v[170:171], 0, s[6:7]
	s_lshl_b32 s10, s79, 1
	v_lshl_add_u64 v[170:171], v[170:171], 0, s[10:11]
	v_mov_b32_e32 v3, v0
	v_lshl_add_u64 v[170:171], v[170:171], 0, v[2:3]
	v_add_f32_e32 v1, 1.0, v1
	v_mov_b64_e32 v[4:5], v[170:171]
	global_store_dwordx4 v[170:171], v[166:169], off
	v_cvt_f32_i32_e32 v163, v163
	v_cvt_f32_i32_e32 v162, v162
	v_rcp_f32_e32 v166, v1
	v_exp_f32_e64 v1, -v161
	v_pk_mul_f32 v[170:171], v[130:131], v[172:173] op_sel_hi:[1,0]
	v_cvt_f32_i32_e32 v157, v157
	v_pk_mul_f32 v[162:163], v[170:171], v[162:163]
	v_add_f32_e32 v1, 1.0, v1
	v_rcp_f32_e32 v167, v1
	v_cvt_f32_i32_e32 v156, v156
	v_exp_f32_e64 v1, -v162
	v_pk_mul_f32 v[168:169], v[124:125], v[172:173] op_sel_hi:[1,0]
	v_pk_mul_f32 v[160:161], v[160:161], v[166:167]
	v_pk_mul_f32 v[156:157], v[168:169], v[156:157]
	v_add_f32_e32 v1, 1.0, v1
	v_pk_mul_f32 v[156:157], v[156:157], v[160:161]
	v_rcp_f32_e32 v160, v1
	v_exp_f32_e64 v1, -v163
	v_cvt_f32_i32_e32 v153, v153
	v_cvt_f32_i32_e32 v152, v152
	v_pk_mul_f32 v[168:169], v[112:113], v[172:173] op_sel_hi:[1,0]
	v_add_f32_e32 v1, 1.0, v1
	v_rcp_f32_e32 v161, v1
	v_pk_mul_f32 v[152:153], v[168:169], v[152:153]
	v_cvt_f32_i32_e32 v159, v159
	v_cvt_f32_i32_e32 v158, v158
	v_exp_f32_e64 v1, -v152
	v_pk_mul_f32 v[166:167], v[126:127], v[172:173] op_sel_hi:[1,0]
	v_pk_mul_f32 v[160:161], v[162:163], v[160:161]
	v_pk_mul_f32 v[158:159], v[166:167], v[158:159]
	v_add_f32_e32 v1, 1.0, v1
	v_pk_mul_f32 v[158:159], v[158:159], v[160:161]
	v_rcp_f32_e32 v160, v1
	v_exp_f32_e64 v1, -v153
	v_cvt_f32_i32_e32 v155, v155
	v_cvt_f32_i32_e32 v154, v154
	v_pk_mul_f32 v[162:163], v[114:115], v[172:173] op_sel_hi:[1,0]
	v_add_f32_e32 v1, 1.0, v1
	v_rcp_f32_e32 v161, v1
	v_pk_mul_f32 v[154:155], v[162:163], v[154:155]
	v_cvt_f32_i32_e32 v149, v149
	v_exp_f32_e64 v1, -v154
	v_pk_mul_f32 v[152:153], v[152:153], v[160:161]
	v_exp_f32_e64 v161, -v155
	v_cvt_f32_i32_e32 v148, v148
	v_add_f32_e32 v1, 1.0, v1
	v_rcp_f32_e32 v160, v1
	v_add_f32_e32 v1, 1.0, v161
	v_cvt_f32_i32_e32 v151, v151
	v_cvt_f32_i32_e32 v150, v150
	v_rcp_f32_e32 v161, v1
	v_pk_mul_f32 v[162:163], v[108:109], v[172:173] op_sel_hi:[1,0]
	v_cvt_f32_i32_e32 v145, v145
	v_pk_mul_f32 v[148:149], v[162:163], v[148:149]
	v_cvt_f32_i32_e32 v144, v144
	v_pk_mul_f32 v[152:153], v[148:149], v[152:153]
	v_pk_mul_f32 v[148:149], v[110:111], v[172:173] op_sel_hi:[1,0]
	v_pk_mul_f32 v[148:149], v[148:149], v[150:151]
	v_pk_mul_f32 v[150:151], v[154:155], v[160:161]
	v_cvt_f32_i32_e32 v147, v147
	v_pk_mul_f32 v[154:155], v[148:149], v[150:151]
	v_cvt_pk_bf16_f32 v150, v152, v153
	v_cvt_pk_bf16_f32 v151, v154, v155
	v_pk_mul_f32 v[154:155], v[128:129], v[176:177] op_sel_hi:[1,0]
	v_pk_mul_f32 v[144:145], v[154:155], v[144:145]
	v_exp_f32_e64 v1, -v144
	v_cvt_pk_bf16_f32 v148, v156, v157
	v_cvt_pk_bf16_f32 v149, v158, v159
	v_add_f32_e32 v1, 1.0, v1
	v_lshl_add_u64 v[4:5], v[4:5], 0, s[98:99]
	global_store_dwordx4 v[4:5], v[148:151], off
	v_cvt_f32_i32_e32 v146, v146
	v_pk_mul_f32 v[152:153], v[130:131], v[176:177] op_sel_hi:[1,0]
	v_rcp_f32_e32 v148, v1
	v_exp_f32_e64 v1, -v145
	v_pk_mul_f32 v[146:147], v[152:153], v[146:147]
	v_cvt_f32_i32_e32 v141, v141
	v_cvt_f32_i32_e32 v140, v140
	v_add_f32_e32 v1, 1.0, v1
	v_rcp_f32_e32 v149, v1
	v_exp_f32_e64 v1, -v146
	v_pk_mul_f32 v[150:151], v[124:125], v[176:177] op_sel_hi:[1,0]
	v_pk_mul_f32 v[144:145], v[144:145], v[148:149]
	v_pk_mul_f32 v[140:141], v[150:151], v[140:141]
	v_add_f32_e32 v1, 1.0, v1
	v_pk_mul_f32 v[140:141], v[140:141], v[144:145]
	v_rcp_f32_e32 v144, v1
	v_exp_f32_e64 v1, -v147
	v_cvt_f32_i32_e32 v137, v137
	v_cvt_f32_i32_e32 v136, v136
	v_pk_mul_f32 v[150:151], v[112:113], v[176:177] op_sel_hi:[1,0]
	v_add_f32_e32 v1, 1.0, v1
	v_rcp_f32_e32 v145, v1
	v_pk_mul_f32 v[136:137], v[150:151], v[136:137]
	v_cvt_f32_i32_e32 v143, v143
	v_cvt_f32_i32_e32 v142, v142
	v_exp_f32_e64 v1, -v136
	v_pk_mul_f32 v[148:149], v[126:127], v[176:177] op_sel_hi:[1,0]
	v_pk_mul_f32 v[144:145], v[146:147], v[144:145]
	v_pk_mul_f32 v[142:143], v[148:149], v[142:143]
	v_add_f32_e32 v1, 1.0, v1
	v_pk_mul_f32 v[142:143], v[142:143], v[144:145]
	v_rcp_f32_e32 v144, v1
	v_exp_f32_e64 v1, -v137
	v_cvt_f32_i32_e32 v139, v139
	v_cvt_f32_i32_e32 v138, v138
	v_pk_mul_f32 v[146:147], v[114:115], v[176:177] op_sel_hi:[1,0]
	v_add_f32_e32 v1, 1.0, v1
	v_rcp_f32_e32 v145, v1
	v_pk_mul_f32 v[138:139], v[146:147], v[138:139]
	v_cvt_f32_i32_e32 v133, v133
	v_exp_f32_e64 v1, -v138
	v_pk_mul_f32 v[136:137], v[136:137], v[144:145]
	v_exp_f32_e64 v145, -v139
	v_cvt_f32_i32_e32 v132, v132
	v_add_f32_e32 v1, 1.0, v1
	v_rcp_f32_e32 v144, v1
	v_add_f32_e32 v1, 1.0, v145
	v_cvt_f32_i32_e32 v135, v135
	v_cvt_f32_i32_e32 v134, v134
	v_rcp_f32_e32 v145, v1
	v_pk_mul_f32 v[146:147], v[108:109], v[176:177] op_sel_hi:[1,0]
	v_cvt_f32_i32_e32 v121, v121
	v_pk_mul_f32 v[132:133], v[146:147], v[132:133]
	v_cvt_f32_i32_e32 v120, v120
	v_pk_mul_f32 v[136:137], v[132:133], v[136:137]
	v_pk_mul_f32 v[132:133], v[110:111], v[176:177] op_sel_hi:[1,0]
	v_pk_mul_f32 v[132:133], v[132:133], v[134:135]
	v_pk_mul_f32 v[134:135], v[138:139], v[144:145]
	v_cvt_f32_i32_e32 v123, v123
	v_pk_mul_f32 v[138:139], v[132:133], v[134:135]
	v_cvt_pk_bf16_f32 v132, v140, v141
	v_cvt_pk_bf16_f32 v135, v138, v139
	v_mov_b32_e32 v138, v177
	v_pk_mul_f32 v[140:141], v[128:129], v[138:139] op_sel_hi:[1,0]
	v_cvt_pk_bf16_f32 v134, v136, v137
	v_pk_mul_f32 v[120:121], v[140:141], v[120:121]
	v_exp_f32_e64 v1, -v120
	v_cvt_pk_bf16_f32 v133, v142, v143
	v_add_f32_e32 v1, 1.0, v1
	v_lshl_add_u64 v[4:5], v[4:5], 0, s[98:99]
	global_store_dwordx4 v[4:5], v[132:135], off
	v_cvt_f32_i32_e32 v122, v122
	v_pk_mul_f32 v[136:137], v[130:131], v[138:139] op_sel_hi:[1,0]
	v_rcp_f32_e32 v132, v1
	v_exp_f32_e64 v1, -v121
	v_pk_mul_f32 v[122:123], v[136:137], v[122:123]
	v_cvt_f32_i32_e32 v117, v117
	v_cvt_f32_i32_e32 v116, v116
	v_add_f32_e32 v1, 1.0, v1
	v_rcp_f32_e32 v133, v1
	v_exp_f32_e64 v1, -v122
	v_pk_mul_f32 v[134:135], v[124:125], v[138:139] op_sel_hi:[1,0]
	v_pk_mul_f32 v[120:121], v[120:121], v[132:133]
	v_pk_mul_f32 v[116:117], v[134:135], v[116:117]
	v_add_f32_e32 v1, 1.0, v1
	v_pk_mul_f32 v[116:117], v[116:117], v[120:121]
	v_rcp_f32_e32 v120, v1
	v_exp_f32_e64 v1, -v123
	v_cvt_f32_i32_e32 v105, v105
	v_cvt_f32_i32_e32 v104, v104
	v_pk_mul_f32 v[134:135], v[112:113], v[138:139] op_sel_hi:[1,0]
	v_add_f32_e32 v1, 1.0, v1
	v_rcp_f32_e32 v121, v1
	v_pk_mul_f32 v[104:105], v[134:135], v[104:105]
	v_cvt_f32_i32_e32 v119, v119
	v_cvt_f32_i32_e32 v118, v118
	v_exp_f32_e64 v1, -v104
	v_pk_mul_f32 v[132:133], v[126:127], v[138:139] op_sel_hi:[1,0]
	v_pk_mul_f32 v[120:121], v[122:123], v[120:121]
	v_pk_mul_f32 v[118:119], v[132:133], v[118:119]
	v_add_f32_e32 v1, 1.0, v1
	v_pk_mul_f32 v[118:119], v[118:119], v[120:121]
	v_rcp_f32_e32 v120, v1
	v_exp_f32_e64 v1, -v105
	v_cvt_f32_i32_e32 v107, v107
	v_cvt_f32_i32_e32 v106, v106
	v_pk_mul_f32 v[122:123], v[114:115], v[138:139] op_sel_hi:[1,0]
	v_add_f32_e32 v1, 1.0, v1
	v_rcp_f32_e32 v121, v1
	v_pk_mul_f32 v[106:107], v[122:123], v[106:107]
	v_cvt_f32_i32_e32 v101, v101
	v_exp_f32_e64 v1, -v106
	v_pk_mul_f32 v[104:105], v[104:105], v[120:121]
	v_exp_f32_e64 v121, -v107
	v_cvt_f32_i32_e32 v100, v100
	v_add_f32_e32 v1, 1.0, v1
	v_rcp_f32_e32 v120, v1
	v_add_f32_e32 v1, 1.0, v121
	v_cvt_f32_i32_e32 v103, v103
	v_cvt_f32_i32_e32 v102, v102
	v_rcp_f32_e32 v121, v1
	v_pk_mul_f32 v[122:123], v[108:109], v[138:139] op_sel_hi:[1,0]
	v_pk_mul_f32 v[100:101], v[122:123], v[100:101]
	s_nop 0
	v_pk_mul_f32 v[104:105], v[100:101], v[104:105]
	v_pk_mul_f32 v[100:101], v[110:111], v[138:139] op_sel_hi:[1,0]
	s_nop 0
	v_pk_mul_f32 v[100:101], v[100:101], v[102:103]
	v_pk_mul_f32 v[102:103], v[106:107], v[120:121]
	s_nop 0
	v_pk_mul_f32 v[106:107], v[100:101], v[102:103]
	v_cvt_pk_bf16_f32 v102, v104, v105
	v_cvt_pk_bf16_f32 v100, v116, v117
	v_cvt_pk_bf16_f32 v101, v118, v119
	v_cvt_pk_bf16_f32 v103, v106, v107
	v_lshl_add_u64 v[4:5], v[4:5], 0, s[98:99]
	global_store_dwordx4 v[4:5], v[100:103], off
	s_cbranch_execz .LBB0_3558
	s_branch .LBB0_3559

.LBB0_3559:
	s_andn2_b64 vcc, exec, s[0:1]
	s_cbranch_vccnz .LBB0_3561
	v_cvt_f32_i32_e32 v97, v97
	v_cvt_f32_i32_e32 v96, v96
	s_waitcnt lgkmcnt(0)
	v_pk_mul_f32 v[100:101], v[182:183], v[128:129] op_sel_hi:[0,1]
	v_cvt_f32_i32_e32 v93, v93
	v_cvt_f32_i32_e32 v92, v92
	v_pk_mul_f32 v[96:97], v[100:101], v[96:97]
	v_cvt_f32_i32_e32 v99, v99
	v_exp_f32_e64 v1, -v96
	v_cvt_f32_i32_e32 v98, v98
	v_pk_mul_f32 v[102:103], v[182:183], v[124:125] op_sel_hi:[0,1]
	v_add_f32_e32 v1, 1.0, v1
	v_rcp_f32_e32 v100, v1
	v_exp_f32_e64 v1, -v97
	v_pk_mul_f32 v[92:93], v[102:103], v[92:93]
	v_pk_mul_f32 v[102:103], v[182:183], v[130:131] op_sel_hi:[0,1]
	v_pk_mul_f32 v[98:99], v[102:103], v[98:99]
	v_add_f32_e32 v1, 1.0, v1
	v_rcp_f32_e32 v101, v1
	v_exp_f32_e64 v1, -v98
	v_cvt_f32_i32_e32 v89, v89
	v_pk_mul_f32 v[96:97], v[96:97], v[100:101]
	v_cvt_f32_i32_e32 v88, v88
	v_add_f32_e32 v1, 1.0, v1
	v_rcp_f32_e32 v100, v1
	v_exp_f32_e64 v1, -v99
	v_pk_mul_f32 v[102:103], v[182:183], v[112:113] op_sel_hi:[0,1]
	v_pk_mul_f32 v[88:89], v[102:103], v[88:89]
	v_cvt_f32_i32_e32 v95, v95
	v_add_f32_e32 v1, 1.0, v1
	v_rcp_f32_e32 v101, v1
	v_cvt_f32_i32_e32 v94, v94
	v_exp_f32_e64 v1, -v88
	v_pk_mul_f32 v[92:93], v[92:93], v[96:97]
	v_pk_mul_f32 v[96:97], v[182:183], v[126:127] op_sel_hi:[0,1]
	v_pk_mul_f32 v[94:95], v[96:97], v[94:95]
	v_pk_mul_f32 v[96:97], v[98:99], v[100:101]
	v_add_f32_e32 v1, 1.0, v1
	v_pk_mul_f32 v[94:95], v[94:95], v[96:97]
	v_rcp_f32_e32 v96, v1
	v_exp_f32_e64 v1, -v89
	v_cvt_f32_i32_e32 v91, v91
	v_cvt_f32_i32_e32 v90, v90
	v_pk_mul_f32 v[98:99], v[182:183], v[114:115] op_sel_hi:[0,1]
	v_add_f32_e32 v1, 1.0, v1
	v_rcp_f32_e32 v97, v1
	v_pk_mul_f32 v[90:91], v[98:99], v[90:91]
	v_cvt_f32_i32_e32 v85, v85
	v_exp_f32_e64 v1, -v90
	v_exp_f32_e64 v3, -v91
	v_cvt_f32_i32_e32 v84, v84
	v_add_f32_e32 v1, 1.0, v1
	v_pk_mul_f32 v[88:89], v[88:89], v[96:97]
	v_rcp_f32_e32 v96, v1
	v_add_f32_e32 v1, 1.0, v3
	v_cvt_f32_i32_e32 v87, v87
	v_cvt_f32_i32_e32 v86, v86
	v_rcp_f32_e32 v97, v1
	v_pk_mul_f32 v[98:99], v[182:183], v[108:109] op_sel_hi:[0,1]
	v_pk_mul_f32 v[84:85], v[98:99], v[84:85]
	v_cvt_f32_i32_e32 v81, v81
	v_pk_mul_f32 v[84:85], v[84:85], v[88:89]
	v_pk_mul_f32 v[88:89], v[182:183], v[110:111] op_sel_hi:[0,1]
	v_cvt_f32_i32_e32 v80, v80
	v_pk_mul_f32 v[86:87], v[88:89], v[86:87]
	v_pk_mul_f32 v[88:89], v[90:91], v[96:97]
	v_add_u32_e32 v1, s37, v225
	v_pk_mul_f32 v[90:91], v[86:87], v[88:89]
	v_cvt_pk_bf16_f32 v86, v92, v93
	v_mov_b32_e32 v92, v183
	v_cvt_pk_bf16_f32 v87, v94, v95
	v_pk_mul_f32 v[94:95], v[92:93], v[128:129] op_sel_hi:[0,1]
	v_cvt_pk_bf16_f32 v88, v84, v85
	v_mov_b64_e32 v[84:85], s[28:29]
	v_pk_mul_f32 v[80:81], v[94:95], v[80:81]
	v_cvt_pk_bf16_f32 v89, v90, v91
	v_mad_i64_i32 v[90:91], s[0:1], v1, s66, v[84:85]
	v_exp_f32_e64 v1, -v80
	s_lshl_b64 s[0:1], s[4:5], 1
	v_lshl_add_u64 v[90:91], v[90:91], 0, s[0:1]
	s_lshl_b32 s10, s79, 1
	v_lshl_add_u64 v[90:91], v[90:91], 0, s[10:11]
	v_mov_b32_e32 v3, v0
	v_lshl_add_u64 v[90:91], v[90:91], 0, v[2:3]
	v_add_f32_e32 v1, 1.0, v1
	v_mov_b64_e32 v[4:5], v[90:91]
	global_store_dwordx4 v[90:91], v[86:89], off
	v_cvt_f32_i32_e32 v83, v83
	v_cvt_f32_i32_e32 v82, v82
	v_rcp_f32_e32 v86, v1
	v_exp_f32_e64 v1, -v81
	v_pk_mul_f32 v[90:91], v[92:93], v[130:131] op_sel_hi:[0,1]
	v_pk_mul_f32 v[82:83], v[90:91], v[82:83]
	v_cvt_f32_i32_e32 v77, v77
	v_add_f32_e32 v1, 1.0, v1
	v_rcp_f32_e32 v87, v1
	v_cvt_f32_i32_e32 v76, v76
	v_exp_f32_e64 v1, -v82
	v_pk_mul_f32 v[88:89], v[92:93], v[124:125] op_sel_hi:[0,1]
	v_pk_mul_f32 v[80:81], v[80:81], v[86:87]
	v_pk_mul_f32 v[76:77], v[88:89], v[76:77]
	v_add_f32_e32 v1, 1.0, v1
	v_pk_mul_f32 v[76:77], v[76:77], v[80:81]
	v_rcp_f32_e32 v80, v1
	v_exp_f32_e64 v1, -v83
	v_cvt_f32_i32_e32 v73, v73
	v_cvt_f32_i32_e32 v72, v72
	v_pk_mul_f32 v[88:89], v[92:93], v[112:113] op_sel_hi:[0,1]
	v_add_f32_e32 v1, 1.0, v1
	v_rcp_f32_e32 v81, v1
	v_pk_mul_f32 v[72:73], v[88:89], v[72:73]
	v_cvt_f32_i32_e32 v79, v79
	v_cvt_f32_i32_e32 v78, v78
	v_exp_f32_e64 v1, -v72
	v_pk_mul_f32 v[86:87], v[92:93], v[126:127] op_sel_hi:[0,1]
	v_pk_mul_f32 v[80:81], v[82:83], v[80:81]
	v_pk_mul_f32 v[78:79], v[86:87], v[78:79]
	v_add_f32_e32 v1, 1.0, v1
	v_pk_mul_f32 v[78:79], v[78:79], v[80:81]
	v_rcp_f32_e32 v80, v1
	v_exp_f32_e64 v1, -v73
	v_cvt_f32_i32_e32 v75, v75
	v_cvt_f32_i32_e32 v74, v74
	v_pk_mul_f32 v[82:83], v[92:93], v[114:115] op_sel_hi:[0,1]
	v_add_f32_e32 v1, 1.0, v1
	v_rcp_f32_e32 v81, v1
	v_pk_mul_f32 v[74:75], v[82:83], v[74:75]
	v_cvt_f32_i32_e32 v69, v69
	v_exp_f32_e64 v1, -v74
	v_pk_mul_f32 v[72:73], v[72:73], v[80:81]
	v_exp_f32_e64 v81, -v75
	v_cvt_f32_i32_e32 v68, v68
	v_add_f32_e32 v1, 1.0, v1
	v_rcp_f32_e32 v80, v1
	v_add_f32_e32 v1, 1.0, v81
	v_cvt_f32_i32_e32 v71, v71
	v_cvt_f32_i32_e32 v70, v70
	v_rcp_f32_e32 v81, v1
	v_pk_mul_f32 v[82:83], v[92:93], v[108:109] op_sel_hi:[0,1]
	v_pk_mul_f32 v[68:69], v[82:83], v[68:69]
	v_cvt_f32_i32_e32 v65, v65
	v_pk_mul_f32 v[72:73], v[68:69], v[72:73]
	v_pk_mul_f32 v[68:69], v[92:93], v[110:111] op_sel_hi:[0,1]
	v_cvt_f32_i32_e32 v64, v64
	v_pk_mul_f32 v[68:69], v[68:69], v[70:71]
	v_pk_mul_f32 v[70:71], v[74:75], v[80:81]
	v_pk_mul_f32 v[74:75], v[68:69], v[70:71]
	v_cvt_pk_bf16_f32 v70, v72, v73
	v_cvt_pk_bf16_f32 v71, v74, v75
	v_pk_mul_f32 v[74:75], v[180:181], v[128:129] op_sel_hi:[0,1]
	v_pk_mul_f32 v[64:65], v[74:75], v[64:65]
	v_exp_f32_e64 v1, -v64
	v_cvt_pk_bf16_f32 v68, v76, v77
	v_cvt_pk_bf16_f32 v69, v78, v79
	v_add_f32_e32 v1, 1.0, v1
	v_lshl_add_u64 v[4:5], v[4:5], 0, s[98:99]
	global_store_dwordx4 v[4:5], v[68:71], off
	v_cvt_f32_i32_e32 v67, v67
	v_cvt_f32_i32_e32 v66, v66
	v_rcp_f32_e32 v68, v1
	v_exp_f32_e64 v1, -v65
	v_pk_mul_f32 v[72:73], v[180:181], v[130:131] op_sel_hi:[0,1]
	v_pk_mul_f32 v[66:67], v[72:73], v[66:67]
	v_cvt_f32_i32_e32 v61, v61
	v_add_f32_e32 v1, 1.0, v1
	v_rcp_f32_e32 v69, v1
	v_cvt_f32_i32_e32 v60, v60
	v_exp_f32_e64 v1, -v66
	v_pk_mul_f32 v[70:71], v[180:181], v[124:125] op_sel_hi:[0,1]
	v_pk_mul_f32 v[64:65], v[64:65], v[68:69]
	v_pk_mul_f32 v[60:61], v[70:71], v[60:61]
	v_add_f32_e32 v1, 1.0, v1
	v_pk_mul_f32 v[60:61], v[60:61], v[64:65]
	v_rcp_f32_e32 v64, v1
	v_exp_f32_e64 v1, -v67
	v_cvt_f32_i32_e32 v57, v57
	v_cvt_f32_i32_e32 v56, v56
	v_pk_mul_f32 v[70:71], v[180:181], v[112:113] op_sel_hi:[0,1]
	v_add_f32_e32 v1, 1.0, v1
	v_rcp_f32_e32 v65, v1
	v_pk_mul_f32 v[56:57], v[70:71], v[56:57]
	v_cvt_f32_i32_e32 v63, v63
	v_cvt_f32_i32_e32 v62, v62
	v_exp_f32_e64 v1, -v56
	v_pk_mul_f32 v[68:69], v[180:181], v[126:127] op_sel_hi:[0,1]
	v_pk_mul_f32 v[64:65], v[66:67], v[64:65]
	v_pk_mul_f32 v[62:63], v[68:69], v[62:63]
	v_add_f32_e32 v1, 1.0, v1
	v_pk_mul_f32 v[62:63], v[62:63], v[64:65]
	v_rcp_f32_e32 v64, v1
	v_exp_f32_e64 v1, -v57
	v_cvt_f32_i32_e32 v59, v59
	v_cvt_f32_i32_e32 v58, v58
	v_pk_mul_f32 v[66:67], v[180:181], v[114:115] op_sel_hi:[0,1]
	v_add_f32_e32 v1, 1.0, v1
	v_rcp_f32_e32 v65, v1
	v_pk_mul_f32 v[58:59], v[66:67], v[58:59]
	v_cvt_f32_i32_e32 v53, v53
	v_exp_f32_e64 v1, -v58
	v_pk_mul_f32 v[56:57], v[56:57], v[64:65]
	v_exp_f32_e64 v65, -v59
	v_cvt_f32_i32_e32 v52, v52
	v_add_f32_e32 v1, 1.0, v1
	v_rcp_f32_e32 v64, v1
	v_add_f32_e32 v1, 1.0, v65
	v_cvt_f32_i32_e32 v55, v55
	v_cvt_f32_i32_e32 v54, v54
	v_rcp_f32_e32 v65, v1
	v_pk_mul_f32 v[66:67], v[180:181], v[108:109] op_sel_hi:[0,1]
	v_pk_mul_f32 v[52:53], v[66:67], v[52:53]
	v_cvt_f32_i32_e32 v49, v49
	v_pk_mul_f32 v[56:57], v[52:53], v[56:57]
	v_pk_mul_f32 v[52:53], v[180:181], v[110:111] op_sel_hi:[0,1]
	v_pk_mul_f32 v[52:53], v[52:53], v[54:55]
	v_pk_mul_f32 v[54:55], v[58:59], v[64:65]
	v_cvt_f32_i32_e32 v48, v48
	v_pk_mul_f32 v[58:59], v[52:53], v[54:55]
	v_cvt_pk_bf16_f32 v52, v60, v61
	v_cvt_pk_bf16_f32 v55, v58, v59
	v_mov_b32_e32 v58, v181
	v_pk_mul_f32 v[60:61], v[58:59], v[128:129] op_sel_hi:[0,1]
	v_pk_mul_f32 v[48:49], v[60:61], v[48:49]
	v_cvt_pk_bf16_f32 v54, v56, v57
	v_exp_f32_e64 v1, -v48
	v_cvt_pk_bf16_f32 v53, v62, v63
	v_add_f32_e32 v1, 1.0, v1
	v_lshl_add_u64 v[4:5], v[4:5], 0, s[98:99]
	global_store_dwordx4 v[4:5], v[52:55], off
	v_cvt_f32_i32_e32 v51, v51
	v_cvt_f32_i32_e32 v50, v50
	v_rcp_f32_e32 v52, v1
	v_exp_f32_e64 v1, -v49
	v_pk_mul_f32 v[56:57], v[58:59], v[130:131] op_sel_hi:[0,1]
	v_pk_mul_f32 v[50:51], v[56:57], v[50:51]
	v_cvt_f32_i32_e32 v45, v45
	v_add_f32_e32 v1, 1.0, v1
	v_rcp_f32_e32 v53, v1
	v_cvt_f32_i32_e32 v44, v44
	v_exp_f32_e64 v1, -v50
	v_pk_mul_f32 v[54:55], v[58:59], v[124:125] op_sel_hi:[0,1]
	v_pk_mul_f32 v[48:49], v[48:49], v[52:53]
	v_pk_mul_f32 v[44:45], v[54:55], v[44:45]
	v_add_f32_e32 v1, 1.0, v1
	v_pk_mul_f32 v[44:45], v[44:45], v[48:49]
	v_rcp_f32_e32 v48, v1
	v_exp_f32_e64 v1, -v51
	v_cvt_f32_i32_e32 v41, v41
	v_cvt_f32_i32_e32 v40, v40
	v_pk_mul_f32 v[54:55], v[58:59], v[112:113] op_sel_hi:[0,1]
	v_add_f32_e32 v1, 1.0, v1
	v_rcp_f32_e32 v49, v1
	v_pk_mul_f32 v[40:41], v[54:55], v[40:41]
	v_cvt_f32_i32_e32 v47, v47
	v_cvt_f32_i32_e32 v46, v46
	v_exp_f32_e64 v1, -v40
	v_pk_mul_f32 v[52:53], v[58:59], v[126:127] op_sel_hi:[0,1]
	v_pk_mul_f32 v[48:49], v[50:51], v[48:49]
	v_pk_mul_f32 v[46:47], v[52:53], v[46:47]
	v_add_f32_e32 v1, 1.0, v1
	v_pk_mul_f32 v[46:47], v[46:47], v[48:49]
	v_rcp_f32_e32 v48, v1
	v_exp_f32_e64 v1, -v41
	v_cvt_f32_i32_e32 v43, v43
	v_cvt_f32_i32_e32 v42, v42
	v_pk_mul_f32 v[50:51], v[58:59], v[114:115] op_sel_hi:[0,1]
	v_add_f32_e32 v1, 1.0, v1
	v_rcp_f32_e32 v49, v1
	v_pk_mul_f32 v[42:43], v[50:51], v[42:43]
	v_cvt_f32_i32_e32 v37, v37
	v_exp_f32_e64 v1, -v42
	v_pk_mul_f32 v[40:41], v[40:41], v[48:49]
	v_exp_f32_e64 v49, -v43
	v_cvt_f32_i32_e32 v36, v36
	v_add_f32_e32 v1, 1.0, v1
	v_rcp_f32_e32 v48, v1
	v_add_f32_e32 v1, 1.0, v49
	v_cvt_f32_i32_e32 v39, v39
	v_cvt_f32_i32_e32 v38, v38
	v_rcp_f32_e32 v49, v1
	v_pk_mul_f32 v[50:51], v[58:59], v[108:109] op_sel_hi:[0,1]
	v_pk_mul_f32 v[36:37], v[50:51], v[36:37]
	v_pk_mul_f32 v[40:41], v[36:37], v[40:41]
	v_pk_mul_f32 v[36:37], v[58:59], v[110:111] op_sel_hi:[0,1]
	v_pk_mul_f32 v[36:37], v[36:37], v[38:39]
	v_pk_mul_f32 v[38:39], v[42:43], v[48:49]
	s_nop 0
	v_pk_mul_f32 v[42:43], v[36:37], v[38:39]
	v_cvt_pk_bf16_f32 v38, v40, v41
	v_cvt_pk_bf16_f32 v36, v44, v45
	v_cvt_pk_bf16_f32 v37, v46, v47
	v_cvt_pk_bf16_f32 v39, v42, v43
	v_lshl_add_u64 v[4:5], v[4:5], 0, s[98:99]
	global_store_dwordx4 v[4:5], v[36:39], off
